# GEMM K-loops: first iteration peeled with literal-0 accumulator input on first-touch MFMAs; per-unit accumulator zeroing removed
# speedup vs baseline: 1.0143x; 1.0066x over previous
; #define PG8_STAGE(bufoff, gbase, voff) do { _Pragma("unroll") for (int _i = 0; _i < 2; ++_i) \
;     __builtin_amdgcn_global_load_lds((const unsigned*)((const char*)(gbase) + (voff)[_i]), (PG8_LAS unsigned*)(lds + (bufoff) + ldsw + _i * 8192), 16, 0, 0); } while (0)
; #define PG8_LDA(dst, b, h) do { _Pragma("unroll") for (int m = 0; m < 4; ++m) _Pragma("unroll") for (int k = 0; k < 2; ++k) dst[m][k] = *(const PG8_LAS bf16x8*)(lds + PG8_SA(b, h) + aoff + m * 2048 + k * 1024); } while (0)
; #define PG8_LDB(dst, b, h) do { _Pragma("unroll") for (int n = 0; n < 2; ++n) _Pragma("unroll") for (int k = 0; k < 2; ++k) dst[n][k] = *(const PG8_LAS bf16x8*)(lds + PG8_SB(b, h) + boff + n * 2048 + k * 1024); } while (0)
; #define PG8_MMA(ai, bj, At, Bt) do { __builtin_amdgcn_s_setprio(1); _Pragma("unroll") for (int m = 0; m < 4; ++m) _Pragma("unroll") for (int n = 0; n < 2; ++n) _Pragma("unroll") for (int k = 0; k < 2; ++k) \
;     acc[ai][bj][m][n] = __builtin_amdgcn_mfma_f32_16x16x32_bf16(Bt[n][k], At[m][k], acc[ai][bj][m][n], 0, 0, 0); __builtin_amdgcn_s_setprio(0); } while (0)
; #define PG8_WAIT_L(n) asm volatile("s_waitcnt lgkmcnt(" #n ")" ::: "memory")
; #define PG8_BAR __builtin_amdgcn_s_barrier()
; #define PG8_SCHED __builtin_amdgcn_sched_barrier(0)
; template <class Epi>
; DI void gemm_phase(PG8_LAS unsigned char* lds, const Gemm g, const StaticOrder& S, const Epi& E) {
;     ...
;     const bool has_next = S.next(ui + 1, nxt);
;     const char* nA = has_next ? (const char*)g.A + (size_t)nxt.pm * tstepA : cA; const char* nB = has_next ? (const char*)g.Bt + (size_t)nxt.pn * tstepB : cB;
;     for (int t = 0; t < nt; t += 2) {
;       const bool last = (t == nt - 2);
;       const char* a1 = cA + (size_t)(t + 1) * kstep;
;       const char* a2 = last ? nA : cA + (size_t)(t + 2) * kstep; const char* b2 = last ? nB : cB + (size_t)(t + 2) * kstep;
;       const char* a3 = a2 + kstep; const char* b3 = b2 + kstep;
;       PG8_LDB(B0, 0, 0); PG8_SCHED; PG8_LDA(At, 0, 0); PG8_STAGE(PG8_SA(1, 1), a1 + hstepA, voffA);
;       PG8_WAIT_L(8); PG8_BAR; PG8_WAIT_L(0); PG8_MMA(0, 0, At, B0); PG8_BAR; PG8_SCHED;
;       PG8_LDB(B1, 0, 1); PG8_STAGE(PG8_SB(0, 0), b2, voffB);
;       PG8_BAR; PG8_WAIT_L(0); PG8_MMA(0, 1, At, B1); PG8_BAR;
;       PG8_LDA(At, 0, 1); PG8_STAGE(PG8_SA(0, 0), a2, voffA);
;       PG8_BAR; PG8_WAIT_L(0); PG8_MMA(1, 0, At, B0); PG8_BAR; PG8_SCHED;
.LBB0_51:
	v_mov_b64_e32 v[2:3], 0x580
	s_ashr_i32 s51, s50, 31
	v_cmp_lt_i64_e32 vcc, s[52:53], v[2:3]
	s_lshl_b64 s[52:53], s[50:51], 19
	s_add_u32 s52, s22, s52
	s_addc_u32 s53, s23, s53
	s_and_b64 s[54:55], vcc, exec
	s_cselect_b32 s51, s53, s57
	s_cselect_b32 s72, s52, s56
	s_ashr_i32 s31, s30, 31
	s_lshl_b64 s[54:55], s[30:31], 19
	v_readlane_b32 s60, v252, 11
	v_readlane_b32 s61, v252, 12
	s_add_u32 s54, s60, s54
	s_addc_u32 s55, s61, s55
	s_and_b64 s[60:61], vcc, exec
	s_cselect_b32 s31, s55, s59
	s_cselect_b32 s73, s54, s58
	s_add_u32 s56, s56, 0x40080
	s_addc_u32 s57, s57, 0
	s_add_u32 s74, s58, 0x100
	v_mov_b32_e32 v2, 0
	s_addc_u32 s75, s59, 0
	s_mov_b32 s76, -2
	s_add_u32 s58, s56, 0xfffc0080
	s_addc_u32 s59, s57, -1
	s_add_i32 s77, 0, 0x10000
	v_add_u32_e32 v153, s77, v149
	ds_read_b128 v[144:147], v153
	ds_read_b128 v[154:157], v153 offset:1024
	ds_read_b128 v[158:161], v153 offset:2048
	ds_read_b128 v[162:165], v153 offset:3072
	s_cmp_eq_u32 s76, 12
	s_cselect_b32 s61, s51, s59
	s_cselect_b32 s60, s72, s58
	s_cselect_b32 s59, s31, s75
	s_cselect_b32 s58, s73, s74
	v_lshl_add_u64 v[198:199], s[56:57], 0, v[132:133]
	s_add_i32 m0, s37, 0xc000
	ds_read_b128 v[166:169], v152
	ds_read_b128 v[170:173], v152 offset:1024
	ds_read_b128 v[174:177], v152 offset:2048
	ds_read_b128 v[178:181], v152 offset:3072
	ds_read_b128 v[182:185], v152 offset:4096
	ds_read_b128 v[186:189], v152 offset:5120
	ds_read_b128 v[190:193], v152 offset:6144
	ds_read_b128 v[194:197], v152 offset:7168
	global_load_lds_dwordx4 v[198:199], off
	v_lshl_add_u64 v[198:199], s[56:57], 0, v[142:143]
	s_add_i32 m0, s37, 0xe000
	s_nop 0
	global_load_lds_dwordx4 v[198:199], off
	s_waitcnt lgkmcnt(8)
	s_barrier
	s_waitcnt lgkmcnt(0)
	s_waitcnt lgkmcnt(0)
	v_mfma_f32_16x16x32_bf16 v[126:129], v[144:147], v[166:169], 0
	v_mfma_f32_16x16x32_bf16 v[122:125], v[158:161], v[166:169], 0
	v_mfma_f32_16x16x32_bf16 v[110:113], v[144:147], v[174:177], 0
	v_mfma_f32_16x16x32_bf16 v[106:109], v[158:161], v[174:177], 0
	v_mfma_f32_16x16x32_bf16 v[94:97], v[144:147], v[182:185], 0
	v_mfma_f32_16x16x32_bf16 v[90:93], v[158:161], v[182:185], 0
	v_mfma_f32_16x16x32_bf16 v[78:81], v[144:147], v[190:193], 0
	v_mfma_f32_16x16x32_bf16 v[74:77], v[158:161], v[190:193], 0
	v_mfma_f32_16x16x32_bf16 v[126:129], v[154:157], v[170:173], v[126:129]
	v_mfma_f32_16x16x32_bf16 v[122:125], v[162:165], v[170:173], v[122:125]
	v_mfma_f32_16x16x32_bf16 v[110:113], v[154:157], v[178:181], v[110:113]
	v_mfma_f32_16x16x32_bf16 v[106:109], v[162:165], v[178:181], v[106:109]
	v_mfma_f32_16x16x32_bf16 v[94:97], v[154:157], v[186:189], v[94:97]
	v_mfma_f32_16x16x32_bf16 v[90:93], v[162:165], v[186:189], v[90:93]
	v_mfma_f32_16x16x32_bf16 v[78:81], v[154:157], v[194:197], v[78:81]
	v_mfma_f32_16x16x32_bf16 v[74:77], v[162:165], v[194:197], v[74:77]
	s_barrier
	s_add_i32 s80, 0, 0x14000
	s_add_i32 s77, s77, s34
	v_add_u32_e32 v153, s80, v149
	v_lshl_add_u64 v[198:199], s[58:59], 0, v[0:1]
	s_mov_b32 m0, s77
	ds_read_b128 v[222:225], v153
	ds_read_b128 v[226:229], v153 offset:1024
	ds_read_b128 v[230:233], v153 offset:2048
	ds_read_b128 v[234:237], v153 offset:3072
	global_load_lds_dwordx4 v[198:199], off
	v_lshl_add_u64 v[238:239], s[58:59], 0, v[130:131]
	s_add_i32 m0, s77, 0x2000
	s_nop 0
	global_load_lds_dwordx4 v[238:239], off
	s_barrier
	s_waitcnt lgkmcnt(0)
	s_waitcnt lgkmcnt(0)
	v_mfma_f32_16x16x32_bf16 v[118:121], v[222:225], v[166:169], 0
	v_mfma_f32_16x16x32_bf16 v[114:117], v[230:233], v[166:169], 0
	v_mfma_f32_16x16x32_bf16 v[102:105], v[222:225], v[174:177], 0
	v_mfma_f32_16x16x32_bf16 v[98:101], v[230:233], v[174:177], 0
	v_mfma_f32_16x16x32_bf16 v[86:89], v[222:225], v[182:185], 0
	v_mfma_f32_16x16x32_bf16 v[82:85], v[230:233], v[182:185], 0
	v_mfma_f32_16x16x32_bf16 v[70:73], v[222:225], v[190:193], 0
	v_mfma_f32_16x16x32_bf16 v[66:69], v[230:233], v[190:193], 0
	v_mfma_f32_16x16x32_bf16 v[118:121], v[226:229], v[170:173], v[118:121]
	v_mfma_f32_16x16x32_bf16 v[114:117], v[234:237], v[170:173], v[114:117]
	v_mfma_f32_16x16x32_bf16 v[102:105], v[226:229], v[178:181], v[102:105]
	v_mfma_f32_16x16x32_bf16 v[98:101], v[234:237], v[178:181], v[98:101]
	v_mfma_f32_16x16x32_bf16 v[86:89], v[226:229], v[186:189], v[86:89]
	v_mfma_f32_16x16x32_bf16 v[82:85], v[234:237], v[186:189], v[82:85]
	v_mfma_f32_16x16x32_bf16 v[70:73], v[226:229], v[194:197], v[70:73]
	v_mfma_f32_16x16x32_bf16 v[66:69], v[234:237], v[194:197], v[66:69]
	s_mov_b32 m0, s37
	v_lshl_add_u64 v[240:241], s[60:61], 0, v[0:1]
	s_barrier
	ds_read_b128 v[166:169], v152 offset:16384
	ds_read_b128 v[170:173], v152 offset:17408
	ds_read_b128 v[174:177], v152 offset:18432
	ds_read_b128 v[178:181], v152 offset:19456
	ds_read_b128 v[182:185], v152 offset:20480
	ds_read_b128 v[186:189], v152 offset:21504
	ds_read_b128 v[190:193], v152 offset:22528
	ds_read_b128 v[194:197], v152 offset:23552
	global_load_lds_dwordx4 v[240:241], off
	v_lshl_add_u64 v[242:243], s[60:61], 0, v[130:131]
	s_mov_b32 m0, s62
	s_nop 0
	global_load_lds_dwordx4 v[242:243], off
	s_barrier
	s_waitcnt lgkmcnt(0)
	s_waitcnt lgkmcnt(0)
	v_mfma_f32_16x16x32_bf16 v[62:65], v[144:147], v[166:169], 0
	v_mfma_f32_16x16x32_bf16 v[58:61], v[158:161], v[166:169], 0
	v_mfma_f32_16x16x32_bf16 v[46:49], v[144:147], v[174:177], 0
	v_mfma_f32_16x16x32_bf16 v[42:45], v[158:161], v[174:177], 0
	v_mfma_f32_16x16x32_bf16 v[30:33], v[144:147], v[182:185], 0
	v_mfma_f32_16x16x32_bf16 v[26:29], v[158:161], v[182:185], 0
	v_mfma_f32_16x16x32_bf16 v[14:17], v[144:147], v[190:193], 0
	v_mfma_f32_16x16x32_bf16 v[10:13], v[158:161], v[190:193], 0
	v_mfma_f32_16x16x32_bf16 v[62:65], v[154:157], v[170:173], v[62:65]
	v_mfma_f32_16x16x32_bf16 v[58:61], v[162:165], v[170:173], v[58:61]
	v_mfma_f32_16x16x32_bf16 v[46:49], v[154:157], v[178:181], v[46:49]
	v_mfma_f32_16x16x32_bf16 v[42:45], v[162:165], v[178:181], v[42:45]
	v_mfma_f32_16x16x32_bf16 v[30:33], v[154:157], v[186:189], v[30:33]
	v_mfma_f32_16x16x32_bf16 v[26:29], v[162:165], v[186:189], v[26:29]
	v_mfma_f32_16x16x32_bf16 v[14:17], v[154:157], v[194:197], v[14:17]
	v_mfma_f32_16x16x32_bf16 v[10:13], v[162:165], v[194:197], v[10:13]
	s_barrier
; #define PG8_STAGE(bufoff, gbase, voff) do { _Pragma("unroll") for (int _i = 0; _i < 2; ++_i) \
;     __builtin_amdgcn_global_load_lds((const unsigned*)((const char*)(gbase) + (voff)[_i]), (PG8_LAS unsigned*)(lds + (bufoff) + ldsw + _i * 8192), 16, 0, 0); } while (0)
; #define PG8_LDA(dst, b, h) do { _Pragma("unroll") for (int m = 0; m < 4; ++m) _Pragma("unroll") for (int k = 0; k < 2; ++k) dst[m][k] = *(const PG8_LAS bf16x8*)(lds + PG8_SA(b, h) + aoff + m * 2048 + k * 1024); } while (0)
; #define PG8_LDB(dst, b, h) do { _Pragma("unroll") for (int n = 0; n < 2; ++n) _Pragma("unroll") for (int k = 0; k < 2; ++k) dst[n][k] = *(const PG8_LAS bf16x8*)(lds + PG8_SB(b, h) + boff + n * 2048 + k * 1024); } while (0)
; #define PG8_MMA(ai, bj, At, Bt) do { __builtin_amdgcn_s_setprio(1); _Pragma("unroll") for (int m = 0; m < 4; ++m) _Pragma("unroll") for (int n = 0; n < 2; ++n) _Pragma("unroll") for (int k = 0; k < 2; ++k) \
;     acc[ai][bj][m][n] = __builtin_amdgcn_mfma_f32_16x16x32_bf16(Bt[n][k], At[m][k], acc[ai][bj][m][n], 0, 0, 0); __builtin_amdgcn_s_setprio(0); } while (0)
; #define PG8_WAIT_V(n) asm volatile("s_waitcnt vmcnt(" #n ")" ::: "memory")
; #define PG8_WAIT_L(n) asm volatile("s_waitcnt lgkmcnt(" #n ")" ::: "memory")
; #define PG8_BAR __builtin_amdgcn_s_barrier()
; #define PG8_SCHED __builtin_amdgcn_sched_barrier(0)
; template <class Epi>
; DI void gemm_phase(PG8_LAS unsigned char* lds, const Gemm g, const StaticOrder& S, const Epi& E) {
;     ...
;       PG8_BAR; PG8_WAIT_L(0); PG8_MMA(1, 0, At, B0); PG8_BAR; PG8_SCHED;
;       PG8_STAGE(PG8_SB(0, 1), b2 + hstepB, voffB);
;       PG8_WAIT_V(6); PG8_BAR; PG8_MMA(1, 1, At, B1); PG8_BAR;
;       PG8_LDB(B0, 1, 0); PG8_SCHED; PG8_LDA(At, 1, 0); PG8_STAGE(PG8_SA(0, 1), a2 + hstepA, voffA);
;       PG8_WAIT_L(8); PG8_BAR; PG8_WAIT_L(0); PG8_MMA(0, 0, At, B0); PG8_BAR; PG8_SCHED;
;       PG8_LDB(B1, 1, 1); PG8_STAGE(PG8_SB(1, 0), b3, voffB);
;       PG8_BAR; PG8_WAIT_L(0); PG8_MMA(0, 1, At, B1); PG8_BAR;
;       PG8_LDA(At, 1, 1); PG8_STAGE(PG8_SA(1, 0), a3, voffA);
	s_add_u32 s78, s58, 0x40000
	s_addc_u32 s79, s59, 0
	s_add_i32 s77, s80, s34
	v_lshl_add_u64 v[144:145], s[78:79], 0, v[0:1]
	s_mov_b32 m0, s77
	s_nop 0
	global_load_lds_dwordx4 v[144:145], off
	v_lshl_add_u64 v[144:145], s[78:79], 0, v[130:131]
	s_add_i32 m0, s77, 0x2000
	s_nop 0
	global_load_lds_dwordx4 v[144:145], off
	s_waitcnt vmcnt(6)
	s_barrier
	v_mfma_f32_16x16x32_bf16 v[54:57], v[222:225], v[166:169], 0
	v_mfma_f32_16x16x32_bf16 v[50:53], v[230:233], v[166:169], 0
	v_mfma_f32_16x16x32_bf16 v[38:41], v[222:225], v[174:177], 0
	v_mfma_f32_16x16x32_bf16 v[34:37], v[230:233], v[174:177], 0
	v_mfma_f32_16x16x32_bf16 v[22:25], v[222:225], v[182:185], 0
	v_mfma_f32_16x16x32_bf16 v[18:21], v[230:233], v[182:185], 0
	v_mfma_f32_16x16x32_bf16 v[6:9], v[222:225], v[190:193], 0
	v_mfma_f32_16x16x32_bf16 v[2:5], v[230:233], v[190:193], 0
	v_mfma_f32_16x16x32_bf16 v[54:57], v[226:229], v[170:173], v[54:57]
	v_mfma_f32_16x16x32_bf16 v[50:53], v[234:237], v[170:173], v[50:53]
	v_mfma_f32_16x16x32_bf16 v[38:41], v[226:229], v[178:181], v[38:41]
	v_mfma_f32_16x16x32_bf16 v[34:37], v[234:237], v[178:181], v[34:37]
	v_mfma_f32_16x16x32_bf16 v[22:25], v[226:229], v[186:189], v[22:25]
	v_mfma_f32_16x16x32_bf16 v[18:21], v[234:237], v[186:189], v[18:21]
	v_mfma_f32_16x16x32_bf16 v[6:9], v[226:229], v[194:197], v[6:9]
	v_mfma_f32_16x16x32_bf16 v[2:5], v[234:237], v[194:197], v[2:5]
	s_add_i32 s77, 0, 0x18000
	v_add_u32_e32 v153, s77, v149
	s_barrier
	ds_read_b128 v[144:147], v153
	ds_read_b128 v[154:157], v153 offset:1024
	ds_read_b128 v[158:161], v153 offset:2048
	ds_read_b128 v[162:165], v153 offset:3072
	s_add_u32 s60, s60, 0x40000
	s_addc_u32 s61, s61, 0
	s_mov_b32 m0, s63
	v_lshl_add_u64 v[222:223], s[60:61], 0, v[0:1]
	ds_read_b128 v[166:169], v152 offset:32768
	ds_read_b128 v[170:173], v152 offset:33792
	ds_read_b128 v[174:177], v152 offset:34816
	ds_read_b128 v[178:181], v152 offset:35840
	ds_read_b128 v[182:185], v152 offset:36864
	ds_read_b128 v[186:189], v152 offset:37888
	ds_read_b128 v[190:193], v152 offset:38912
	ds_read_b128 v[194:197], v152 offset:39936
	global_load_lds_dwordx4 v[222:223], off
	v_lshl_add_u64 v[222:223], s[60:61], 0, v[130:131]
	s_mov_b32 m0, s64
	s_nop 0
	global_load_lds_dwordx4 v[222:223], off
	s_waitcnt lgkmcnt(8)
	s_barrier
	s_waitcnt lgkmcnt(0)
	s_waitcnt lgkmcnt(0)
	v_mfma_f32_16x16x32_bf16 v[126:129], v[144:147], v[166:169], v[126:129]
	v_mfma_f32_16x16x32_bf16 v[122:125], v[158:161], v[166:169], v[122:125]
	v_mfma_f32_16x16x32_bf16 v[110:113], v[144:147], v[174:177], v[110:113]
	v_mfma_f32_16x16x32_bf16 v[106:109], v[158:161], v[174:177], v[106:109]
	v_mfma_f32_16x16x32_bf16 v[94:97], v[144:147], v[182:185], v[94:97]
	v_mfma_f32_16x16x32_bf16 v[90:93], v[158:161], v[182:185], v[90:93]
	v_mfma_f32_16x16x32_bf16 v[78:81], v[144:147], v[190:193], v[78:81]
	v_mfma_f32_16x16x32_bf16 v[74:77], v[158:161], v[190:193], v[74:77]
	v_mfma_f32_16x16x32_bf16 v[126:129], v[154:157], v[170:173], v[126:129]
	v_mfma_f32_16x16x32_bf16 v[122:125], v[162:165], v[170:173], v[122:125]
	v_mfma_f32_16x16x32_bf16 v[110:113], v[154:157], v[178:181], v[110:113]
	v_mfma_f32_16x16x32_bf16 v[106:109], v[162:165], v[178:181], v[106:109]
	v_mfma_f32_16x16x32_bf16 v[94:97], v[154:157], v[186:189], v[94:97]
	v_mfma_f32_16x16x32_bf16 v[90:93], v[162:165], v[186:189], v[90:93]
	v_mfma_f32_16x16x32_bf16 v[78:81], v[154:157], v[194:197], v[78:81]
	v_mfma_f32_16x16x32_bf16 v[74:77], v[162:165], v[194:197], v[74:77]
	s_barrier
	s_add_i32 s60, 0, 0x1c000
	s_add_i32 s61, s77, s34
	v_add_u32_e32 v153, s60, v149
	v_lshl_add_u64 v[198:199], v[198:199], 0, s[86:87]
	s_mov_b32 m0, s61
	ds_read_b128 v[222:225], v153
	ds_read_b128 v[226:229], v153 offset:1024
	ds_read_b128 v[230:233], v153 offset:2048
	ds_read_b128 v[234:237], v153 offset:3072
	global_load_lds_dwordx4 v[198:199], off
	v_lshl_add_u64 v[198:199], v[238:239], 0, s[86:87]
	s_add_i32 m0, s61, 0x2000
	s_nop 0
	global_load_lds_dwordx4 v[198:199], off
	s_barrier
; #define PG8_STAGE(bufoff, gbase, voff) do { _Pragma("unroll") for (int _i = 0; _i < 2; ++_i) \
;     __builtin_amdgcn_global_load_lds((const unsigned*)((const char*)(gbase) + (voff)[_i]), (PG8_LAS unsigned*)(lds + (bufoff) + ldsw + _i * 8192), 16, 0, 0); } while (0)
; #define PG8_LDA(dst, b, h) do { _Pragma("unroll") for (int m = 0; m < 4; ++m) _Pragma("unroll") for (int k = 0; k < 2; ++k) dst[m][k] = *(const PG8_LAS bf16x8*)(lds + PG8_SA(b, h) + aoff + m * 2048 + k * 1024); } while (0)
; #define PG8_MMA(ai, bj, At, Bt) do { __builtin_amdgcn_s_setprio(1); _Pragma("unroll") for (int m = 0; m < 4; ++m) _Pragma("unroll") for (int n = 0; n < 2; ++n) _Pragma("unroll") for (int k = 0; k < 2; ++k) \
;     acc[ai][bj][m][n] = __builtin_amdgcn_mfma_f32_16x16x32_bf16(Bt[n][k], At[m][k], acc[ai][bj][m][n], 0, 0, 0); __builtin_amdgcn_s_setprio(0); } while (0)
; #define PG8_WAIT_V(n) asm volatile("s_waitcnt vmcnt(" #n ")" ::: "memory")
; #define PG8_WAIT_L(n) asm volatile("s_waitcnt lgkmcnt(" #n ")" ::: "memory")
; #define PG8_BAR __builtin_amdgcn_s_barrier()
; #define PG8_SCHED __builtin_amdgcn_sched_barrier(0)
; template <class Epi>
; DI void gemm_phase(PG8_LAS unsigned char* lds, const Gemm g, const StaticOrder& S, const Epi& E) {
;     ...
;       PG8_BAR; PG8_WAIT_L(0); PG8_MMA(0, 1, At, B1); PG8_BAR;
;       PG8_LDA(At, 1, 1); PG8_STAGE(PG8_SA(1, 0), a3, voffA);
;       PG8_BAR; PG8_WAIT_L(0); PG8_MMA(1, 0, At, B0); PG8_BAR; PG8_SCHED;
;       PG8_STAGE(PG8_SB(1, 1), b3 + hstepB, voffB);
;       PG8_WAIT_V(6); PG8_BAR; PG8_MMA(1, 1, At, B1); PG8_BAR;
;     }
	s_waitcnt lgkmcnt(0)
	s_waitcnt lgkmcnt(0)
	v_mfma_f32_16x16x32_bf16 v[118:121], v[222:225], v[166:169], v[118:121]
	v_mfma_f32_16x16x32_bf16 v[114:117], v[230:233], v[166:169], v[114:117]
	v_mfma_f32_16x16x32_bf16 v[102:105], v[222:225], v[174:177], v[102:105]
	v_mfma_f32_16x16x32_bf16 v[98:101], v[230:233], v[174:177], v[98:101]
	v_mfma_f32_16x16x32_bf16 v[86:89], v[222:225], v[182:185], v[86:89]
	v_mfma_f32_16x16x32_bf16 v[82:85], v[230:233], v[182:185], v[82:85]
	v_mfma_f32_16x16x32_bf16 v[70:73], v[222:225], v[190:193], v[70:73]
	v_mfma_f32_16x16x32_bf16 v[66:69], v[230:233], v[190:193], v[66:69]
	v_mfma_f32_16x16x32_bf16 v[118:121], v[226:229], v[170:173], v[118:121]
	v_mfma_f32_16x16x32_bf16 v[114:117], v[234:237], v[170:173], v[114:117]
	v_mfma_f32_16x16x32_bf16 v[102:105], v[226:229], v[178:181], v[102:105]
	v_mfma_f32_16x16x32_bf16 v[98:101], v[234:237], v[178:181], v[98:101]
	v_mfma_f32_16x16x32_bf16 v[86:89], v[226:229], v[186:189], v[86:89]
	v_mfma_f32_16x16x32_bf16 v[82:85], v[234:237], v[186:189], v[82:85]
	v_mfma_f32_16x16x32_bf16 v[70:73], v[226:229], v[194:197], v[70:73]
	v_mfma_f32_16x16x32_bf16 v[66:69], v[234:237], v[194:197], v[66:69]
	s_mov_b32 m0, s65
	v_lshl_add_u64 v[198:199], v[240:241], 0, s[86:87]
	s_barrier
	ds_read_b128 v[166:169], v152 offset:49152
	ds_read_b128 v[170:173], v152 offset:50176
	ds_read_b128 v[174:177], v152 offset:51200
	ds_read_b128 v[178:181], v152 offset:52224
	ds_read_b128 v[182:185], v152 offset:53248
	ds_read_b128 v[186:189], v152 offset:54272
	ds_read_b128 v[190:193], v152 offset:55296
	ds_read_b128 v[194:197], v152 offset:56320
	global_load_lds_dwordx4 v[198:199], off
	v_lshl_add_u64 v[198:199], v[242:243], 0, s[86:87]
	s_mov_b32 m0, s66
	s_nop 0
	global_load_lds_dwordx4 v[198:199], off
	s_barrier
	s_waitcnt lgkmcnt(0)
	s_waitcnt lgkmcnt(0)
	v_mfma_f32_16x16x32_bf16 v[62:65], v[144:147], v[166:169], v[62:65]
	v_mfma_f32_16x16x32_bf16 v[58:61], v[158:161], v[166:169], v[58:61]
	v_mfma_f32_16x16x32_bf16 v[46:49], v[144:147], v[174:177], v[46:49]
	v_mfma_f32_16x16x32_bf16 v[42:45], v[158:161], v[174:177], v[42:45]
	v_mfma_f32_16x16x32_bf16 v[30:33], v[144:147], v[182:185], v[30:33]
	v_mfma_f32_16x16x32_bf16 v[26:29], v[158:161], v[182:185], v[26:29]
	v_mfma_f32_16x16x32_bf16 v[14:17], v[144:147], v[190:193], v[14:17]
	v_mfma_f32_16x16x32_bf16 v[10:13], v[158:161], v[190:193], v[10:13]
	v_mfma_f32_16x16x32_bf16 v[62:65], v[154:157], v[170:173], v[62:65]
	v_mfma_f32_16x16x32_bf16 v[58:61], v[162:165], v[170:173], v[58:61]
	v_mfma_f32_16x16x32_bf16 v[46:49], v[154:157], v[178:181], v[46:49]
	v_mfma_f32_16x16x32_bf16 v[42:45], v[162:165], v[178:181], v[42:45]
	v_mfma_f32_16x16x32_bf16 v[30:33], v[154:157], v[186:189], v[30:33]
	v_mfma_f32_16x16x32_bf16 v[26:29], v[162:165], v[186:189], v[26:29]
	v_mfma_f32_16x16x32_bf16 v[14:17], v[154:157], v[194:197], v[14:17]
	v_mfma_f32_16x16x32_bf16 v[10:13], v[162:165], v[194:197], v[10:13]
	s_barrier
	s_add_u32 s58, s58, 0x40080
	s_addc_u32 s59, s59, 0
	s_add_i32 s60, s60, s34
	v_lshl_add_u64 v[144:145], s[58:59], 0, v[0:1]
	s_mov_b32 m0, s60
	s_nop 0
	global_load_lds_dwordx4 v[144:145], off
	v_lshl_add_u64 v[144:145], s[58:59], 0, v[130:131]
	s_add_i32 m0, s60, 0x2000
	s_nop 0
	global_load_lds_dwordx4 v[144:145], off
	s_waitcnt vmcnt(6)
	s_barrier
	v_mfma_f32_16x16x32_bf16 v[54:57], v[222:225], v[166:169], v[54:57]
	v_mfma_f32_16x16x32_bf16 v[50:53], v[230:233], v[166:169], v[50:53]
	v_mfma_f32_16x16x32_bf16 v[38:41], v[222:225], v[174:177], v[38:41]
	v_mfma_f32_16x16x32_bf16 v[34:37], v[230:233], v[174:177], v[34:37]
	v_mfma_f32_16x16x32_bf16 v[22:25], v[222:225], v[182:185], v[22:25]
	v_mfma_f32_16x16x32_bf16 v[18:21], v[230:233], v[182:185], v[18:21]
	v_mfma_f32_16x16x32_bf16 v[6:9], v[222:225], v[190:193], v[6:9]
	v_mfma_f32_16x16x32_bf16 v[2:5], v[230:233], v[190:193], v[2:5]
	v_mfma_f32_16x16x32_bf16 v[54:57], v[226:229], v[170:173], v[54:57]
	v_mfma_f32_16x16x32_bf16 v[50:53], v[234:237], v[170:173], v[50:53]
	v_mfma_f32_16x16x32_bf16 v[38:41], v[226:229], v[178:181], v[38:41]
	v_mfma_f32_16x16x32_bf16 v[34:37], v[234:237], v[178:181], v[34:37]
	v_mfma_f32_16x16x32_bf16 v[22:25], v[226:229], v[186:189], v[22:25]
	v_mfma_f32_16x16x32_bf16 v[18:21], v[234:237], v[186:189], v[18:21]
	v_mfma_f32_16x16x32_bf16 v[6:9], v[226:229], v[194:197], v[6:9]
	v_mfma_f32_16x16x32_bf16 v[2:5], v[234:237], v[194:197], v[2:5]
	s_add_i32 s76, s76, 2
	s_add_u32 s56, s56, 0x100
	s_addc_u32 s57, s57, 0
	s_add_u32 s74, s74, 0x100
	s_addc_u32 s75, s75, 0
	s_cmp_gt_u32 s76, 13
	s_barrier
	s_cbranch_scc1 .Lpeel_exit_0

; DI unsigned pk2(float lo, float hi) { f32x2 v = {lo, hi}; bf2_t r = __builtin_convertvector(v, bf2_t); return __builtin_bit_cast(unsigned, r); }
; DI float silu(float x) { return x * __builtin_amdgcn_rcpf(1.f + __expf(-x)); }
; #define PG8_LAS __attribute__((address_space(3)))
;   DI void operator()(const f32x4 (&acc)[2][2][4][2], const Unit& u, int wr, int wc, int fr, int fq, const PG8_LAS float* sR) const {
;     const int row0 = u.pm * BM + wr * 64 + fr, j0 = (u.pn * BM + wc * 32) / 2 + 4 * fq;
; #pragma unroll
;     for (int ai = 0; ai < 2; ++ai)
; #pragma unroll
;       for (int m = 0; m < 4; ++m) {
;         bf16_t* rowp = Hd + (size_t)(row0 + ai * HALF + m * 16) * 2816 + j0;
;         const float rs = sR[ai * 128 + m * 16 + fr];
; #pragma unroll
;         for (int bj = 0; bj < 2; ++bj) {
;           const f32x4 g = acc[ai][bj][m][0] * rs, up = acc[ai][bj][m][1] * rs;
;           u32x2 o; o[0] = pk2(silu(g[0]) * up[0], silu(g[1]) * up[1]); o[1] = pk2(silu(g[2]) * up[2], silu(g[3]) * up[3]);
;           *(u32x2*)(rowp + bj * (HALF / 2)) = o;
;         }
;       }
.Lpeel_exit_0:
	v_lshl_add_u32 v154, s69, 10, v150
	ds_read2_b32 v[158:159], v154 offset1:16
	ds_read2_b32 v[160:161], v154 offset0:32 offset1:48
	s_lshl_b32 s31, s70, 8
	s_or_b32 s31, s31, s67
	s_ashr_i32 s31, s31, 1
	v_readlane_b32 s18, v253, 30
	v_readlane_b32 s19, v253, 31
	v_or_b32_e32 v146, s31, v151
	v_lshl_add_u32 v153, s71, 8, v148
	v_ashrrev_i32_e32 v147, 31, v146
	s_movk_i32 s4, 0x1600
	v_mov_b64_e32 v[144:145], s[18:19]
	v_lshlrev_b64 v[146:147], 1, v[146:147]
	v_mad_i64_i32 v[156:157], s[56:57], v153, s4, v[144:145]
	v_and_b32_e32 v144, 4, v151
	v_mul_u32_u24_e32 v144, 30, v144
	v_mov_b32_e32 v145, 0
	v_lshl_add_u64 v[156:157], v[156:157], 0, v[146:147]
	s_mov_b32 s70, s30
	s_mov_b32 s71, s50
	s_mov_b64 s[58:59], s[54:55]
	v_lshl_add_u64 v[156:157], v[156:157], 0, v[144:145]
	v_readlane_b32 s5, v253, 17
	v_readlane_b32 s6, v253, 18
	v_readlane_b32 s7, v253, 19
	v_readlane_b32 s8, v253, 20
	v_readlane_b32 s9, v253, 21
	v_readlane_b32 s10, v253, 22
	v_readlane_b32 s11, v253, 23
	v_readlane_b32 s12, v253, 24
	v_readlane_b32 s13, v253, 25
	v_readlane_b32 s14, v253, 26
	v_readlane_b32 s15, v253, 27
	v_readlane_b32 s16, v253, 28
	v_readlane_b32 s17, v253, 29
	s_mov_b32 s56, 0x16000
	s_mov_b32 s57, 0
	s_waitcnt lgkmcnt(0)
	v_pk_mul_f32 v[126:127], v[126:127], v[158:159] op_sel_hi:[1,0]
	v_pk_mul_f32 v[128:129], v[128:129], v[158:159] op_sel_hi:[1,0]
	v_pk_mul_f32 v[122:123], v[122:123], v[158:159] op_sel_hi:[1,0]
	v_pk_mul_f32 v[124:125], v[124:125], v[158:159] op_sel_hi:[1,0]
	v_mul_f32_e32 v144, 0xbfb8aa3b, v126
	v_mul_f32_e32 v145, 0xbfb8aa3b, v127
	v_mul_f32_e32 v146, 0xbfb8aa3b, v128
	v_mul_f32_e32 v147, 0xbfb8aa3b, v129
	v_exp_f32_e32 v144, v144
	v_exp_f32_e32 v145, v145
	v_exp_f32_e32 v146, v146
	v_exp_f32_e32 v147, v147
	v_add_f32_e32 v144, 1.0, v144
	v_add_f32_e32 v145, 1.0, v145
	v_add_f32_e32 v146, 1.0, v146
	v_add_f32_e32 v147, 1.0, v147
	v_rcp_f32_e32 v144, v144
	v_rcp_f32_e32 v145, v145
	v_rcp_f32_e32 v146, v146
	v_rcp_f32_e32 v147, v147
	v_pk_mul_f32 v[126:127], v[126:127], v[144:145]
	v_pk_mul_f32 v[128:129], v[128:129], v[146:147]
	v_pk_mul_f32 v[126:127], v[126:127], v[122:123]
	v_pk_mul_f32 v[128:129], v[128:129], v[124:125]
	v_cvt_pk_bf16_f32 v122, v126, v127
	v_cvt_pk_bf16_f32 v123, v128, v129
	v_pk_mul_f32 v[118:119], v[118:119], v[158:159] op_sel_hi:[1,0]
	v_pk_mul_f32 v[120:121], v[120:121], v[158:159] op_sel_hi:[1,0]
	v_pk_mul_f32 v[114:115], v[114:115], v[158:159] op_sel_hi:[1,0]
	v_pk_mul_f32 v[116:117], v[116:117], v[158:159] op_sel_hi:[1,0]
	v_pk_mul_f32 v[110:111], v[110:111], v[158:159] op_sel:[0,1]
	v_pk_mul_f32 v[112:113], v[112:113], v[158:159] op_sel:[0,1]
	v_pk_mul_f32 v[106:107], v[106:107], v[158:159] op_sel:[0,1]
	v_pk_mul_f32 v[108:109], v[108:109], v[158:159] op_sel:[0,1]
	v_mul_f32_e32 v144, 0xbfb8aa3b, v118
	v_mul_f32_e32 v145, 0xbfb8aa3b, v119
	v_mul_f32_e32 v146, 0xbfb8aa3b, v120
	v_mul_f32_e32 v147, 0xbfb8aa3b, v121
	v_mul_f32_e32 v126, 0xbfb8aa3b, v110
	v_mul_f32_e32 v127, 0xbfb8aa3b, v111
	v_mul_f32_e32 v128, 0xbfb8aa3b, v112
	v_mul_f32_e32 v129, 0xbfb8aa3b, v113
	v_exp_f32_e32 v144, v144
	v_exp_f32_e32 v145, v145
	v_exp_f32_e32 v146, v146
	v_exp_f32_e32 v147, v147
	v_exp_f32_e32 v126, v126
	v_exp_f32_e32 v127, v127
	v_exp_f32_e32 v128, v128
	v_exp_f32_e32 v129, v129
	v_add_f32_e32 v144, 1.0, v144
	v_add_f32_e32 v145, 1.0, v145
	v_add_f32_e32 v146, 1.0, v146
	v_add_f32_e32 v147, 1.0, v147
	v_add_f32_e32 v126, 1.0, v126
	v_add_f32_e32 v127, 1.0, v127
	v_add_f32_e32 v128, 1.0, v128
	v_add_f32_e32 v129, 1.0, v129
	v_rcp_f32_e32 v144, v144
	v_rcp_f32_e32 v145, v145
	v_rcp_f32_e32 v146, v146
	v_rcp_f32_e32 v147, v147
	v_rcp_f32_e32 v126, v126
	v_rcp_f32_e32 v127, v127
	v_rcp_f32_e32 v128, v128
	v_rcp_f32_e32 v129, v129
	v_pk_mul_f32 v[118:119], v[118:119], v[144:145]
	v_pk_mul_f32 v[120:121], v[120:121], v[146:147]
	v_pk_mul_f32 v[110:111], v[110:111], v[126:127]
	v_pk_mul_f32 v[112:113], v[112:113], v[128:129]
	v_pk_mul_f32 v[118:119], v[118:119], v[114:115]
	v_pk_mul_f32 v[120:121], v[120:121], v[116:117]
	v_pk_mul_f32 v[110:111], v[110:111], v[106:107]
	v_pk_mul_f32 v[112:113], v[112:113], v[108:109]
	v_cvt_pk_bf16_f32 v124, v118, v119
	v_cvt_pk_bf16_f32 v125, v120, v121
	v_cvt_pk_bf16_f32 v106, v110, v111
	v_cvt_pk_bf16_f32 v107, v112, v113
	s_nop 1
	v_permlane16_swap_b32_e32 v122, v124
	v_permlane16_swap_b32_e32 v123, v125
	global_store_dwordx4 v[156:157], v[122:125], off
	v_lshl_add_u64 v[156:157], v[156:157], 0, s[56:57]
	ds_read2_b32 v[118:119], v154 offset0:128 offset1:144
	ds_read2_b32 v[120:121], v154 offset0:160 offset1:176
	v_pk_mul_f32 v[102:103], v[102:103], v[158:159] op_sel:[0,1]
	v_pk_mul_f32 v[104:105], v[104:105], v[158:159] op_sel:[0,1]
	v_pk_mul_f32 v[98:99], v[98:99], v[158:159] op_sel:[0,1]
	v_pk_mul_f32 v[100:101], v[100:101], v[158:159] op_sel:[0,1]
	v_pk_mul_f32 v[94:95], v[94:95], v[160:161] op_sel_hi:[1,0]
	v_pk_mul_f32 v[96:97], v[96:97], v[160:161] op_sel_hi:[1,0]
	v_pk_mul_f32 v[90:91], v[90:91], v[160:161] op_sel_hi:[1,0]
	v_pk_mul_f32 v[92:93], v[92:93], v[160:161] op_sel_hi:[1,0]
	v_mul_f32_e32 v144, 0xbfb8aa3b, v102
	v_mul_f32_e32 v145, 0xbfb8aa3b, v103
	v_mul_f32_e32 v146, 0xbfb8aa3b, v104
	v_mul_f32_e32 v147, 0xbfb8aa3b, v105
	v_mul_f32_e32 v126, 0xbfb8aa3b, v94
	v_mul_f32_e32 v127, 0xbfb8aa3b, v95
	v_mul_f32_e32 v128, 0xbfb8aa3b, v96
	v_mul_f32_e32 v129, 0xbfb8aa3b, v97
	v_exp_f32_e32 v144, v144
	v_exp_f32_e32 v145, v145
	v_exp_f32_e32 v146, v146
	v_exp_f32_e32 v147, v147
	v_exp_f32_e32 v126, v126
	v_exp_f32_e32 v127, v127
	v_exp_f32_e32 v128, v128
	v_exp_f32_e32 v129, v129
	v_add_f32_e32 v144, 1.0, v144
	v_add_f32_e32 v145, 1.0, v145
; DI unsigned pk2(float lo, float hi) { f32x2 v = {lo, hi}; bf2_t r = __builtin_convertvector(v, bf2_t); return __builtin_bit_cast(unsigned, r); }
; DI float silu(float x) { return x * __builtin_amdgcn_rcpf(1.f + __expf(-x)); }
; #define PG8_LAS __attribute__((address_space(3)))
;   DI void operator()(const f32x4 (&acc)[2][2][4][2], const Unit& u, int wr, int wc, int fr, int fq, const PG8_LAS float* sR) const {
;     const int row0 = u.pm * BM + wr * 64 + fr, j0 = (u.pn * BM + wc * 32) / 2 + 4 * fq;
; #pragma unroll
;     for (int ai = 0; ai < 2; ++ai)
; #pragma unroll
;       for (int m = 0; m < 4; ++m) {
;         bf16_t* rowp = Hd + (size_t)(row0 + ai * HALF + m * 16) * 2816 + j0;
;         const float rs = sR[ai * 128 + m * 16 + fr];
; #pragma unroll
;         for (int bj = 0; bj < 2; ++bj) {
;           const f32x4 g = acc[ai][bj][m][0] * rs, up = acc[ai][bj][m][1] * rs;
;           u32x2 o; o[0] = pk2(silu(g[0]) * up[0], silu(g[1]) * up[1]); o[1] = pk2(silu(g[2]) * up[2], silu(g[3]) * up[3]);
;           *(u32x2*)(rowp + bj * (HALF / 2)) = o;
;         }
;       }
	v_add_f32_e32 v146, 1.0, v146
	v_add_f32_e32 v147, 1.0, v147
	v_add_f32_e32 v126, 1.0, v126
	v_add_f32_e32 v127, 1.0, v127
	v_add_f32_e32 v128, 1.0, v128
	v_add_f32_e32 v129, 1.0, v129
	v_rcp_f32_e32 v144, v144
	v_rcp_f32_e32 v145, v145
	v_rcp_f32_e32 v146, v146
	v_rcp_f32_e32 v147, v147
	v_rcp_f32_e32 v126, v126
	v_rcp_f32_e32 v127, v127
	v_rcp_f32_e32 v128, v128
	v_rcp_f32_e32 v129, v129
	v_pk_mul_f32 v[102:103], v[102:103], v[144:145]
	v_pk_mul_f32 v[104:105], v[104:105], v[146:147]
	v_pk_mul_f32 v[94:95], v[94:95], v[126:127]
	v_pk_mul_f32 v[96:97], v[96:97], v[128:129]
	v_pk_mul_f32 v[102:103], v[102:103], v[98:99]
	v_pk_mul_f32 v[104:105], v[104:105], v[100:101]
	v_pk_mul_f32 v[94:95], v[94:95], v[90:91]
	v_pk_mul_f32 v[96:97], v[96:97], v[92:93]
	v_cvt_pk_bf16_f32 v108, v102, v103
	v_cvt_pk_bf16_f32 v109, v104, v105
	v_cvt_pk_bf16_f32 v90, v94, v95
	v_cvt_pk_bf16_f32 v91, v96, v97
	s_nop 1
	v_permlane16_swap_b32_e32 v106, v108
	v_permlane16_swap_b32_e32 v107, v109
	global_store_dwordx4 v[156:157], v[106:109], off
	v_lshl_add_u64 v[156:157], v[156:157], 0, s[56:57]
	v_pk_mul_f32 v[86:87], v[86:87], v[160:161] op_sel_hi:[1,0]
	v_pk_mul_f32 v[88:89], v[88:89], v[160:161] op_sel_hi:[1,0]
	v_pk_mul_f32 v[82:83], v[82:83], v[160:161] op_sel_hi:[1,0]
	v_pk_mul_f32 v[84:85], v[84:85], v[160:161] op_sel_hi:[1,0]
	v_pk_mul_f32 v[78:79], v[78:79], v[160:161] op_sel:[0,1]
	v_pk_mul_f32 v[80:81], v[80:81], v[160:161] op_sel:[0,1]
	v_pk_mul_f32 v[74:75], v[74:75], v[160:161] op_sel:[0,1]
	v_pk_mul_f32 v[76:77], v[76:77], v[160:161] op_sel:[0,1]
	v_mul_f32_e32 v144, 0xbfb8aa3b, v86
	v_mul_f32_e32 v145, 0xbfb8aa3b, v87
	v_mul_f32_e32 v146, 0xbfb8aa3b, v88
	v_mul_f32_e32 v147, 0xbfb8aa3b, v89
	v_mul_f32_e32 v126, 0xbfb8aa3b, v78
	v_mul_f32_e32 v127, 0xbfb8aa3b, v79
	v_mul_f32_e32 v128, 0xbfb8aa3b, v80
	v_mul_f32_e32 v129, 0xbfb8aa3b, v81
	v_exp_f32_e32 v144, v144
	v_exp_f32_e32 v145, v145
	v_exp_f32_e32 v146, v146
	v_exp_f32_e32 v147, v147
	v_exp_f32_e32 v126, v126
	v_exp_f32_e32 v127, v127
	v_exp_f32_e32 v128, v128
	v_exp_f32_e32 v129, v129
	v_add_f32_e32 v144, 1.0, v144
	v_add_f32_e32 v145, 1.0, v145
	v_add_f32_e32 v146, 1.0, v146
	v_add_f32_e32 v147, 1.0, v147
	v_add_f32_e32 v126, 1.0, v126
	v_add_f32_e32 v127, 1.0, v127
	v_add_f32_e32 v128, 1.0, v128
	v_add_f32_e32 v129, 1.0, v129
	v_rcp_f32_e32 v144, v144
	v_rcp_f32_e32 v145, v145
	v_rcp_f32_e32 v146, v146
	v_rcp_f32_e32 v147, v147
	v_rcp_f32_e32 v126, v126
	v_rcp_f32_e32 v127, v127
	v_rcp_f32_e32 v128, v128
	v_rcp_f32_e32 v129, v129
	v_pk_mul_f32 v[86:87], v[86:87], v[144:145]
	v_pk_mul_f32 v[88:89], v[88:89], v[146:147]
	v_pk_mul_f32 v[78:79], v[78:79], v[126:127]
	v_pk_mul_f32 v[80:81], v[80:81], v[128:129]
	v_pk_mul_f32 v[86:87], v[86:87], v[82:83]
	v_pk_mul_f32 v[88:89], v[88:89], v[84:85]
	v_pk_mul_f32 v[78:79], v[78:79], v[74:75]
	v_pk_mul_f32 v[80:81], v[80:81], v[76:77]
	v_cvt_pk_bf16_f32 v92, v86, v87
	v_cvt_pk_bf16_f32 v93, v88, v89
	v_cvt_pk_bf16_f32 v74, v78, v79
	v_cvt_pk_bf16_f32 v75, v80, v81
	s_nop 1
	v_permlane16_swap_b32_e32 v90, v92
	v_permlane16_swap_b32_e32 v91, v93
	global_store_dwordx4 v[156:157], v[90:93], off
	v_lshl_add_u64 v[156:157], v[156:157], 0, s[56:57]
	s_waitcnt lgkmcnt(0)
	v_pk_mul_f32 v[70:71], v[70:71], v[160:161] op_sel:[0,1]
	v_pk_mul_f32 v[72:73], v[72:73], v[160:161] op_sel:[0,1]
	v_pk_mul_f32 v[66:67], v[66:67], v[160:161] op_sel:[0,1]
	v_pk_mul_f32 v[68:69], v[68:69], v[160:161] op_sel:[0,1]
	v_pk_mul_f32 v[62:63], v[62:63], v[118:119] op_sel_hi:[1,0]
	v_pk_mul_f32 v[64:65], v[64:65], v[118:119] op_sel_hi:[1,0]
	v_pk_mul_f32 v[58:59], v[58:59], v[118:119] op_sel_hi:[1,0]
	v_pk_mul_f32 v[60:61], v[60:61], v[118:119] op_sel_hi:[1,0]
	v_mul_f32_e32 v144, 0xbfb8aa3b, v70
	v_mul_f32_e32 v145, 0xbfb8aa3b, v71
	v_mul_f32_e32 v146, 0xbfb8aa3b, v72
	v_mul_f32_e32 v147, 0xbfb8aa3b, v73
	v_mul_f32_e32 v126, 0xbfb8aa3b, v62
	v_mul_f32_e32 v127, 0xbfb8aa3b, v63
	v_mul_f32_e32 v128, 0xbfb8aa3b, v64
	v_mul_f32_e32 v129, 0xbfb8aa3b, v65
	v_exp_f32_e32 v144, v144
	v_exp_f32_e32 v145, v145
	v_exp_f32_e32 v146, v146
	v_exp_f32_e32 v147, v147
	v_exp_f32_e32 v126, v126
	v_exp_f32_e32 v127, v127
	v_exp_f32_e32 v128, v128
	v_exp_f32_e32 v129, v129
	v_add_f32_e32 v144, 1.0, v144
	v_add_f32_e32 v145, 1.0, v145
	v_add_f32_e32 v146, 1.0, v146
	v_add_f32_e32 v147, 1.0, v147
	v_add_f32_e32 v126, 1.0, v126
	v_add_f32_e32 v127, 1.0, v127
	v_add_f32_e32 v128, 1.0, v128
	v_add_f32_e32 v129, 1.0, v129
	v_rcp_f32_e32 v144, v144
	v_rcp_f32_e32 v145, v145
	v_rcp_f32_e32 v146, v146
	v_rcp_f32_e32 v147, v147
	v_rcp_f32_e32 v126, v126
	v_rcp_f32_e32 v127, v127
	v_rcp_f32_e32 v128, v128
	v_rcp_f32_e32 v129, v129
	v_pk_mul_f32 v[70:71], v[70:71], v[144:145]
	v_pk_mul_f32 v[72:73], v[72:73], v[146:147]
	v_pk_mul_f32 v[62:63], v[62:63], v[126:127]
	v_pk_mul_f32 v[64:65], v[64:65], v[128:129]
	v_pk_mul_f32 v[70:71], v[70:71], v[66:67]
	v_pk_mul_f32 v[72:73], v[72:73], v[68:69]
	v_pk_mul_f32 v[62:63], v[62:63], v[58:59]
	v_pk_mul_f32 v[64:65], v[64:65], v[60:61]
	v_cvt_pk_bf16_f32 v76, v70, v71
	v_cvt_pk_bf16_f32 v77, v72, v73
	v_cvt_pk_bf16_f32 v58, v62, v63
	v_cvt_pk_bf16_f32 v59, v64, v65
	s_nop 1
	v_permlane16_swap_b32_e32 v74, v76
	v_permlane16_swap_b32_e32 v75, v77
	global_store_dwordx4 v[156:157], v[74:77], off
	s_mov_b32 s56, 0x6e000
	v_lshl_add_u64 v[156:157], v[156:157], 0, s[56:57]
	s_mov_b32 s56, 0x16000
	v_pk_mul_f32 v[54:55], v[54:55], v[118:119] op_sel_hi:[1,0]
	v_pk_mul_f32 v[56:57], v[56:57], v[118:119] op_sel_hi:[1,0]
	v_pk_mul_f32 v[50:51], v[50:51], v[118:119] op_sel_hi:[1,0]
	v_pk_mul_f32 v[52:53], v[52:53], v[118:119] op_sel_hi:[1,0]
	v_pk_mul_f32 v[46:47], v[46:47], v[118:119] op_sel:[0,1]
; DI unsigned pk2(float lo, float hi) { f32x2 v = {lo, hi}; bf2_t r = __builtin_convertvector(v, bf2_t); return __builtin_bit_cast(unsigned, r); }
; DI float silu(float x) { return x * __builtin_amdgcn_rcpf(1.f + __expf(-x)); }
; #define PG8_LAS __attribute__((address_space(3)))
;   DI void operator()(const f32x4 (&acc)[2][2][4][2], const Unit& u, int wr, int wc, int fr, int fq, const PG8_LAS float* sR) const {
;     const int row0 = u.pm * BM + wr * 64 + fr, j0 = (u.pn * BM + wc * 32) / 2 + 4 * fq;
; #pragma unroll
;     for (int ai = 0; ai < 2; ++ai)
; #pragma unroll
;       for (int m = 0; m < 4; ++m) {
;         bf16_t* rowp = Hd + (size_t)(row0 + ai * HALF + m * 16) * 2816 + j0;
;         const float rs = sR[ai * 128 + m * 16 + fr];
; #pragma unroll
;         for (int bj = 0; bj < 2; ++bj) {
;           const f32x4 g = acc[ai][bj][m][0] * rs, up = acc[ai][bj][m][1] * rs;
;           u32x2 o; o[0] = pk2(silu(g[0]) * up[0], silu(g[1]) * up[1]); o[1] = pk2(silu(g[2]) * up[2], silu(g[3]) * up[3]);
;           *(u32x2*)(rowp + bj * (HALF / 2)) = o;
;         }
;       }
	v_pk_mul_f32 v[48:49], v[48:49], v[118:119] op_sel:[0,1]
	v_pk_mul_f32 v[42:43], v[42:43], v[118:119] op_sel:[0,1]
	v_pk_mul_f32 v[44:45], v[44:45], v[118:119] op_sel:[0,1]
	v_mul_f32_e32 v144, 0xbfb8aa3b, v54
	v_mul_f32_e32 v145, 0xbfb8aa3b, v55
	v_mul_f32_e32 v146, 0xbfb8aa3b, v56
	v_mul_f32_e32 v147, 0xbfb8aa3b, v57
	v_mul_f32_e32 v126, 0xbfb8aa3b, v46
	v_mul_f32_e32 v127, 0xbfb8aa3b, v47
	v_mul_f32_e32 v128, 0xbfb8aa3b, v48
	v_mul_f32_e32 v129, 0xbfb8aa3b, v49
	v_exp_f32_e32 v144, v144
	v_exp_f32_e32 v145, v145
	v_exp_f32_e32 v146, v146
	v_exp_f32_e32 v147, v147
	v_exp_f32_e32 v126, v126
	v_exp_f32_e32 v127, v127
	v_exp_f32_e32 v128, v128
	v_exp_f32_e32 v129, v129
	v_add_f32_e32 v144, 1.0, v144
	v_add_f32_e32 v145, 1.0, v145
	v_add_f32_e32 v146, 1.0, v146
	v_add_f32_e32 v147, 1.0, v147
	v_add_f32_e32 v126, 1.0, v126
	v_add_f32_e32 v127, 1.0, v127
	v_add_f32_e32 v128, 1.0, v128
	v_add_f32_e32 v129, 1.0, v129
	v_rcp_f32_e32 v144, v144
	v_rcp_f32_e32 v145, v145
	v_rcp_f32_e32 v146, v146
	v_rcp_f32_e32 v147, v147
	v_rcp_f32_e32 v126, v126
	v_rcp_f32_e32 v127, v127
	v_rcp_f32_e32 v128, v128
	v_rcp_f32_e32 v129, v129
	v_pk_mul_f32 v[54:55], v[54:55], v[144:145]
	v_pk_mul_f32 v[56:57], v[56:57], v[146:147]
	v_pk_mul_f32 v[46:47], v[46:47], v[126:127]
	v_pk_mul_f32 v[48:49], v[48:49], v[128:129]
	v_pk_mul_f32 v[54:55], v[54:55], v[50:51]
	v_pk_mul_f32 v[56:57], v[56:57], v[52:53]
	v_pk_mul_f32 v[46:47], v[46:47], v[42:43]
	v_pk_mul_f32 v[48:49], v[48:49], v[44:45]
	v_cvt_pk_bf16_f32 v60, v54, v55
	v_cvt_pk_bf16_f32 v61, v56, v57
	v_cvt_pk_bf16_f32 v42, v46, v47
	v_cvt_pk_bf16_f32 v43, v48, v49
	s_nop 1
	v_permlane16_swap_b32_e32 v58, v60
	v_permlane16_swap_b32_e32 v59, v61
	global_store_dwordx4 v[156:157], v[58:61], off
	v_lshl_add_u64 v[156:157], v[156:157], 0, s[56:57]
	v_pk_mul_f32 v[38:39], v[38:39], v[118:119] op_sel:[0,1]
	v_pk_mul_f32 v[40:41], v[40:41], v[118:119] op_sel:[0,1]
	v_pk_mul_f32 v[34:35], v[34:35], v[118:119] op_sel:[0,1]
	v_pk_mul_f32 v[36:37], v[36:37], v[118:119] op_sel:[0,1]
	v_pk_mul_f32 v[30:31], v[30:31], v[120:121] op_sel_hi:[1,0]
	v_pk_mul_f32 v[32:33], v[32:33], v[120:121] op_sel_hi:[1,0]
	v_pk_mul_f32 v[26:27], v[26:27], v[120:121] op_sel_hi:[1,0]
	v_pk_mul_f32 v[28:29], v[28:29], v[120:121] op_sel_hi:[1,0]
	v_mul_f32_e32 v144, 0xbfb8aa3b, v38
	v_mul_f32_e32 v145, 0xbfb8aa3b, v39
	v_mul_f32_e32 v146, 0xbfb8aa3b, v40
	v_mul_f32_e32 v147, 0xbfb8aa3b, v41
	v_mul_f32_e32 v126, 0xbfb8aa3b, v30
	v_mul_f32_e32 v127, 0xbfb8aa3b, v31
	v_mul_f32_e32 v128, 0xbfb8aa3b, v32
	v_mul_f32_e32 v129, 0xbfb8aa3b, v33
	v_exp_f32_e32 v144, v144
	v_exp_f32_e32 v145, v145
	v_exp_f32_e32 v146, v146
	v_exp_f32_e32 v147, v147
	v_exp_f32_e32 v126, v126
	v_exp_f32_e32 v127, v127
	v_exp_f32_e32 v128, v128
	v_exp_f32_e32 v129, v129
	v_add_f32_e32 v144, 1.0, v144
	v_add_f32_e32 v145, 1.0, v145
	v_add_f32_e32 v146, 1.0, v146
	v_add_f32_e32 v147, 1.0, v147
	v_add_f32_e32 v126, 1.0, v126
	v_add_f32_e32 v127, 1.0, v127
	v_add_f32_e32 v128, 1.0, v128
	v_add_f32_e32 v129, 1.0, v129
	v_rcp_f32_e32 v144, v144
	v_rcp_f32_e32 v145, v145
	v_rcp_f32_e32 v146, v146
	v_rcp_f32_e32 v147, v147
	v_rcp_f32_e32 v126, v126
	v_rcp_f32_e32 v127, v127
	v_rcp_f32_e32 v128, v128
	v_rcp_f32_e32 v129, v129
	v_pk_mul_f32 v[38:39], v[38:39], v[144:145]
	v_pk_mul_f32 v[40:41], v[40:41], v[146:147]
	v_pk_mul_f32 v[30:31], v[30:31], v[126:127]
	v_pk_mul_f32 v[32:33], v[32:33], v[128:129]
	v_pk_mul_f32 v[38:39], v[38:39], v[34:35]
	v_pk_mul_f32 v[40:41], v[40:41], v[36:37]
	v_pk_mul_f32 v[30:31], v[30:31], v[26:27]
	v_pk_mul_f32 v[32:33], v[32:33], v[28:29]
	v_cvt_pk_bf16_f32 v44, v38, v39
; DI unsigned pk2(float lo, float hi) { f32x2 v = {lo, hi}; bf2_t r = __builtin_convertvector(v, bf2_t); return __builtin_bit_cast(unsigned, r); }
; DI float silu(float x) { return x * __builtin_amdgcn_rcpf(1.f + __expf(-x)); }
; #define PG8_WAIT_V(n) asm volatile("s_waitcnt vmcnt(" #n ")" ::: "memory")
; #define PG8_BAR __builtin_amdgcn_s_barrier()
;   DI void operator()(const f32x4 (&acc)[2][2][4][2], const Unit& u, int wr, int wc, int fr, int fq, const PG8_LAS float* sR) const {
;     ...
;       for (int m = 0; m < 4; ++m) {
;         bf16_t* rowp = Hd + (size_t)(row0 + ai * HALF + m * 16) * 2816 + j0;
;         const float rs = sR[ai * 128 + m * 16 + fr];
; #pragma unroll
;         for (int bj = 0; bj < 2; ++bj) {
;           const f32x4 g = acc[ai][bj][m][0] * rs, up = acc[ai][bj][m][1] * rs;
;           u32x2 o; o[0] = pk2(silu(g[0]) * up[0], silu(g[1]) * up[1]); o[1] = pk2(silu(g[2]) * up[2], silu(g[3]) * up[3]);
;           *(u32x2*)(rowp + bj * (HALF / 2)) = o;
;         }
;       }
; template <class Epi>
; DI void gemm_phase(PG8_LAS unsigned char* lds, const Gemm g, const StaticOrder& S, const Epi& E) {
;     ...
;   PG8_WAIT_V(0);
;   if (wr == 0) PG8_BAR;
;   PG8_BAR;
	v_cvt_pk_bf16_f32 v45, v40, v41
	v_cvt_pk_bf16_f32 v26, v30, v31
	v_cvt_pk_bf16_f32 v27, v32, v33
	s_nop 1
	v_permlane16_swap_b32_e32 v42, v44
	v_permlane16_swap_b32_e32 v43, v45
	global_store_dwordx4 v[156:157], v[42:45], off
	v_lshl_add_u64 v[156:157], v[156:157], 0, s[56:57]
	v_pk_mul_f32 v[22:23], v[22:23], v[120:121] op_sel_hi:[1,0]
	v_pk_mul_f32 v[24:25], v[24:25], v[120:121] op_sel_hi:[1,0]
	v_pk_mul_f32 v[18:19], v[18:19], v[120:121] op_sel_hi:[1,0]
	v_pk_mul_f32 v[20:21], v[20:21], v[120:121] op_sel_hi:[1,0]
	v_pk_mul_f32 v[14:15], v[14:15], v[120:121] op_sel:[0,1]
	v_pk_mul_f32 v[16:17], v[16:17], v[120:121] op_sel:[0,1]
	v_pk_mul_f32 v[10:11], v[10:11], v[120:121] op_sel:[0,1]
	v_pk_mul_f32 v[12:13], v[12:13], v[120:121] op_sel:[0,1]
	v_mul_f32_e32 v144, 0xbfb8aa3b, v22
	v_mul_f32_e32 v145, 0xbfb8aa3b, v23
	v_mul_f32_e32 v146, 0xbfb8aa3b, v24
	v_mul_f32_e32 v147, 0xbfb8aa3b, v25
	v_mul_f32_e32 v126, 0xbfb8aa3b, v14
	v_mul_f32_e32 v127, 0xbfb8aa3b, v15
	v_mul_f32_e32 v128, 0xbfb8aa3b, v16
	v_mul_f32_e32 v129, 0xbfb8aa3b, v17
	v_exp_f32_e32 v144, v144
	v_exp_f32_e32 v145, v145
	v_exp_f32_e32 v146, v146
	v_exp_f32_e32 v147, v147
	v_exp_f32_e32 v126, v126
	v_exp_f32_e32 v127, v127
	v_exp_f32_e32 v128, v128
	v_exp_f32_e32 v129, v129
	v_add_f32_e32 v144, 1.0, v144
	v_add_f32_e32 v145, 1.0, v145
	v_add_f32_e32 v146, 1.0, v146
	v_add_f32_e32 v147, 1.0, v147
	v_add_f32_e32 v126, 1.0, v126
	v_add_f32_e32 v127, 1.0, v127
	v_add_f32_e32 v128, 1.0, v128
	v_add_f32_e32 v129, 1.0, v129
	v_rcp_f32_e32 v144, v144
	v_rcp_f32_e32 v145, v145
	v_rcp_f32_e32 v146, v146
	v_rcp_f32_e32 v147, v147
	v_rcp_f32_e32 v126, v126
	v_rcp_f32_e32 v127, v127
	v_rcp_f32_e32 v128, v128
	v_rcp_f32_e32 v129, v129
	v_pk_mul_f32 v[22:23], v[22:23], v[144:145]
	v_pk_mul_f32 v[24:25], v[24:25], v[146:147]
	v_pk_mul_f32 v[14:15], v[14:15], v[126:127]
	v_pk_mul_f32 v[16:17], v[16:17], v[128:129]
	v_pk_mul_f32 v[22:23], v[22:23], v[18:19]
	v_pk_mul_f32 v[24:25], v[24:25], v[20:21]
	v_pk_mul_f32 v[14:15], v[14:15], v[10:11]
	v_pk_mul_f32 v[16:17], v[16:17], v[12:13]
	v_cvt_pk_bf16_f32 v28, v22, v23
	v_cvt_pk_bf16_f32 v29, v24, v25
	v_cvt_pk_bf16_f32 v10, v14, v15
	v_cvt_pk_bf16_f32 v11, v16, v17
	s_nop 1
	v_permlane16_swap_b32_e32 v26, v28
	v_permlane16_swap_b32_e32 v27, v29
	global_store_dwordx4 v[156:157], v[26:29], off
	v_lshl_add_u64 v[156:157], v[156:157], 0, s[56:57]
	v_pk_mul_f32 v[6:7], v[6:7], v[120:121] op_sel:[0,1]
	v_pk_mul_f32 v[8:9], v[8:9], v[120:121] op_sel:[0,1]
	v_pk_mul_f32 v[2:3], v[2:3], v[120:121] op_sel:[0,1]
	v_pk_mul_f32 v[4:5], v[4:5], v[120:121] op_sel:[0,1]
	v_mul_f32_e32 v144, 0xbfb8aa3b, v6
	v_mul_f32_e32 v145, 0xbfb8aa3b, v7
	v_mul_f32_e32 v146, 0xbfb8aa3b, v8
	v_mul_f32_e32 v147, 0xbfb8aa3b, v9
	v_exp_f32_e32 v144, v144
	v_exp_f32_e32 v145, v145
	v_exp_f32_e32 v146, v146
	v_exp_f32_e32 v147, v147
	v_add_f32_e32 v144, 1.0, v144
	v_add_f32_e32 v145, 1.0, v145
	v_add_f32_e32 v146, 1.0, v146
	v_add_f32_e32 v147, 1.0, v147
	v_rcp_f32_e32 v144, v144
	v_rcp_f32_e32 v145, v145
	v_rcp_f32_e32 v146, v146
	v_rcp_f32_e32 v147, v147
	v_pk_mul_f32 v[6:7], v[6:7], v[144:145]
	v_pk_mul_f32 v[8:9], v[8:9], v[146:147]
	v_pk_mul_f32 v[6:7], v[6:7], v[2:3]
	v_pk_mul_f32 v[8:9], v[8:9], v[4:5]
	v_cvt_pk_bf16_f32 v12, v6, v7
	v_cvt_pk_bf16_f32 v13, v8, v9
	s_nop 1
	v_permlane16_swap_b32_e32 v10, v12
	v_permlane16_swap_b32_e32 v11, v13
	global_store_dwordx4 v[156:157], v[10:13], off
	s_mov_b32 s69, s68
	s_mov_b64 s[56:57], s[52:53]
	s_and_b64 vcc, exec, s[40:41]
	s_cbranch_vccz .LBB0_49
	s_waitcnt vmcnt(0)
	s_cmpk_gt_u32 s28, 0xff
	s_cbranch_scc1 .LBB0_56
	s_barrier

; #define PG8_STAGE(bufoff, gbase, voff) do { _Pragma("unroll") for (int _i = 0; _i < 2; ++_i) \
;     __builtin_amdgcn_global_load_lds((const unsigned*)((const char*)(gbase) + (voff)[_i]), (PG8_LAS unsigned*)(lds + (bufoff) + ldsw + _i * 8192), 16, 0, 0); } while (0)
; #define PG8_LDA(dst, b, h) do { _Pragma("unroll") for (int m = 0; m < 4; ++m) _Pragma("unroll") for (int k = 0; k < 2; ++k) dst[m][k] = *(const PG8_LAS bf16x8*)(lds + PG8_SA(b, h) + aoff + m * 2048 + k * 1024); } while (0)
; #define PG8_LDB(dst, b, h) do { _Pragma("unroll") for (int n = 0; n < 2; ++n) _Pragma("unroll") for (int k = 0; k < 2; ++k) dst[n][k] = *(const PG8_LAS bf16x8*)(lds + PG8_SB(b, h) + boff + n * 2048 + k * 1024); } while (0)
; #define PG8_MMA(ai, bj, At, Bt) do { __builtin_amdgcn_s_setprio(1); _Pragma("unroll") for (int m = 0; m < 4; ++m) _Pragma("unroll") for (int n = 0; n < 2; ++n) _Pragma("unroll") for (int k = 0; k < 2; ++k) \
;     acc[ai][bj][m][n] = __builtin_amdgcn_mfma_f32_16x16x32_bf16(Bt[n][k], At[m][k], acc[ai][bj][m][n], 0, 0, 0); __builtin_amdgcn_s_setprio(0); } while (0)
; #define PG8_WAIT_L(n) asm volatile("s_waitcnt lgkmcnt(" #n ")" ::: "memory")
; #define PG8_BAR __builtin_amdgcn_s_barrier()
; #define PG8_SCHED __builtin_amdgcn_sched_barrier(0)
; template <class Epi>
; DI void gemm_phase(PG8_LAS unsigned char* lds, const Gemm g, const StaticOrder& S, const Epi& E) {
;     ...
;     const bool has_next = S.next(ui + 1, nxt);
;     const char* nA = has_next ? (const char*)g.A + (size_t)nxt.pm * tstepA : cA; const char* nB = has_next ? (const char*)g.Bt + (size_t)nxt.pn * tstepB : cB;
;     for (int t = 0; t < nt; t += 2) {
;       const bool last = (t == nt - 2);
;       const char* a1 = cA + (size_t)(t + 1) * kstep;
;       const char* a2 = last ? nA : cA + (size_t)(t + 2) * kstep; const char* b2 = last ? nB : cB + (size_t)(t + 2) * kstep;
;       const char* a3 = a2 + kstep; const char* b3 = b2 + kstep;
;       PG8_LDB(B0, 0, 0); PG8_SCHED; PG8_LDA(At, 0, 0); PG8_STAGE(PG8_SA(1, 1), a1 + hstepA, voffA);
;       PG8_WAIT_L(8); PG8_BAR; PG8_WAIT_L(0); PG8_MMA(0, 0, At, B0); PG8_BAR; PG8_SCHED;
;       PG8_LDB(B1, 0, 1); PG8_STAGE(PG8_SB(0, 0), b2, voffB);
;       PG8_BAR; PG8_WAIT_L(0); PG8_MMA(0, 1, At, B1); PG8_BAR;
;       PG8_LDA(At, 0, 1); PG8_STAGE(PG8_SA(0, 0), a2, voffA);
;       PG8_BAR; PG8_WAIT_L(0); PG8_MMA(1, 0, At, B0); PG8_BAR; PG8_SCHED;
.LBB0_834:
	s_add_u32 s44, s58, 0x80
	s_addc_u32 s45, s59, 0
	s_add_u32 s79, s56, 0x100
	v_mov_b32_e32 v2, 0
	s_addc_u32 s80, s57, 0
	s_mov_b32 s56, 0
	s_add_i32 s81, s56, 2
	s_add_u32 s58, s44, 0x80
	s_addc_u32 s57, s45, 0
	s_add_i32 s82, 0, 0x10000
	v_add_u32_e32 v160, s82, v223
	ds_read_b128 v[130:133], v160
	ds_read_b128 v[152:155], v160 offset:1024
	ds_read_b128 v[156:159], v160 offset:2048
	ds_read_b128 v[160:163], v160 offset:3072
	s_cmp_eq_u32 s75, s56
	s_cselect_b32 s56, s0, s58
	s_cselect_b32 s57, s1, s57
	s_cselect_b32 s59, s55, s80
	s_cselect_b32 s58, s54, s79
	v_lshl_add_u64 v[196:197], s[44:45], 0, v[148:149]
	s_add_i32 m0, s66, 0xc000
	ds_read_b128 v[164:167], v225
	ds_read_b128 v[168:171], v225 offset:1024
	ds_read_b128 v[172:175], v225 offset:2048
	ds_read_b128 v[176:179], v225 offset:3072
	ds_read_b128 v[180:183], v225 offset:4096
	ds_read_b128 v[184:187], v225 offset:5120
	ds_read_b128 v[188:191], v225 offset:6144
	ds_read_b128 v[192:195], v225 offset:7168
	global_load_lds_dwordx4 v[196:197], off
	v_lshl_add_u64 v[196:197], s[44:45], 0, v[150:151]
	s_add_i32 m0, s66, 0xe000
	s_nop 0
	global_load_lds_dwordx4 v[196:197], off
	s_waitcnt lgkmcnt(8)
	s_barrier
	s_waitcnt lgkmcnt(0)
	s_waitcnt lgkmcnt(0)
	v_mfma_f32_16x16x32_bf16 v[126:129], v[130:133], v[164:167], 0
	v_mfma_f32_16x16x32_bf16 v[122:125], v[156:159], v[164:167], 0
	v_mfma_f32_16x16x32_bf16 v[110:113], v[130:133], v[172:175], 0
	v_mfma_f32_16x16x32_bf16 v[106:109], v[156:159], v[172:175], 0
	v_mfma_f32_16x16x32_bf16 v[94:97], v[130:133], v[180:183], 0
	v_mfma_f32_16x16x32_bf16 v[90:93], v[156:159], v[180:183], 0
	v_mfma_f32_16x16x32_bf16 v[78:81], v[130:133], v[188:191], 0
	v_mfma_f32_16x16x32_bf16 v[74:77], v[156:159], v[188:191], 0
	v_mfma_f32_16x16x32_bf16 v[126:129], v[152:155], v[168:171], v[126:129]
	v_mfma_f32_16x16x32_bf16 v[122:125], v[160:163], v[168:171], v[122:125]
	v_mfma_f32_16x16x32_bf16 v[110:113], v[152:155], v[176:179], v[110:113]
	v_mfma_f32_16x16x32_bf16 v[106:109], v[160:163], v[176:179], v[106:109]
	v_mfma_f32_16x16x32_bf16 v[94:97], v[152:155], v[184:187], v[94:97]
	v_mfma_f32_16x16x32_bf16 v[90:93], v[160:163], v[184:187], v[90:93]
	v_mfma_f32_16x16x32_bf16 v[78:81], v[152:155], v[192:195], v[78:81]
	v_mfma_f32_16x16x32_bf16 v[74:77], v[160:163], v[192:195], v[74:77]
	s_barrier
	s_add_i32 s83, 0, 0x14000
	s_add_i32 s82, s82, s65
	v_add_u32_e32 v234, s83, v223
	v_lshl_add_u64 v[238:239], s[58:59], 0, v[0:1]
	s_mov_b32 m0, s82
	ds_read_b128 v[196:199], v234
	ds_read_b128 v[226:229], v234 offset:1024
	ds_read_b128 v[230:233], v234 offset:2048
	ds_read_b128 v[234:237], v234 offset:3072
	global_load_lds_dwordx4 v[238:239], off
	v_lshl_add_u64 v[240:241], s[58:59], 0, v[142:143]
	s_add_i32 m0, s82, 0x2000
	s_nop 0
	global_load_lds_dwordx4 v[240:241], off
	s_barrier
	s_waitcnt lgkmcnt(0)
	s_waitcnt lgkmcnt(0)
	v_mfma_f32_16x16x32_bf16 v[118:121], v[196:199], v[164:167], 0
	v_mfma_f32_16x16x32_bf16 v[114:117], v[230:233], v[164:167], 0
	v_mfma_f32_16x16x32_bf16 v[102:105], v[196:199], v[172:175], 0
	v_mfma_f32_16x16x32_bf16 v[98:101], v[230:233], v[172:175], 0
	v_mfma_f32_16x16x32_bf16 v[86:89], v[196:199], v[180:183], 0
	v_mfma_f32_16x16x32_bf16 v[82:85], v[230:233], v[180:183], 0
	v_mfma_f32_16x16x32_bf16 v[70:73], v[196:199], v[188:191], 0
	v_mfma_f32_16x16x32_bf16 v[66:69], v[230:233], v[188:191], 0
	v_mfma_f32_16x16x32_bf16 v[118:121], v[226:229], v[168:171], v[118:121]
	v_mfma_f32_16x16x32_bf16 v[114:117], v[234:237], v[168:171], v[114:117]
	v_mfma_f32_16x16x32_bf16 v[102:105], v[226:229], v[176:179], v[102:105]
	v_mfma_f32_16x16x32_bf16 v[98:101], v[234:237], v[176:179], v[98:101]
	v_mfma_f32_16x16x32_bf16 v[86:89], v[226:229], v[184:187], v[86:89]
	v_mfma_f32_16x16x32_bf16 v[82:85], v[234:237], v[184:187], v[82:85]
	v_mfma_f32_16x16x32_bf16 v[70:73], v[226:229], v[192:195], v[70:73]
	v_mfma_f32_16x16x32_bf16 v[66:69], v[234:237], v[192:195], v[66:69]
	s_mov_b32 m0, s66
	v_lshl_add_u64 v[242:243], s[56:57], 0, v[146:147]
	s_barrier
	ds_read_b128 v[164:167], v225 offset:16384
	ds_read_b128 v[168:171], v225 offset:17408
	ds_read_b128 v[172:175], v225 offset:18432
	ds_read_b128 v[176:179], v225 offset:19456
	ds_read_b128 v[180:183], v225 offset:20480
	ds_read_b128 v[184:187], v225 offset:21504
	ds_read_b128 v[188:191], v225 offset:22528
	ds_read_b128 v[192:195], v225 offset:23552
	global_load_lds_dwordx4 v[242:243], off
	v_lshl_add_u64 v[244:245], s[56:57], 0, v[144:145]
	s_mov_b32 m0, s67
	s_nop 0
	global_load_lds_dwordx4 v[244:245], off
	s_barrier
	s_waitcnt lgkmcnt(0)
	s_waitcnt lgkmcnt(0)
	v_mfma_f32_16x16x32_bf16 v[62:65], v[130:133], v[164:167], 0
	v_mfma_f32_16x16x32_bf16 v[58:61], v[156:159], v[164:167], 0
	v_mfma_f32_16x16x32_bf16 v[46:49], v[130:133], v[172:175], 0
	v_mfma_f32_16x16x32_bf16 v[42:45], v[156:159], v[172:175], 0
	v_mfma_f32_16x16x32_bf16 v[30:33], v[130:133], v[180:183], 0
	v_mfma_f32_16x16x32_bf16 v[26:29], v[156:159], v[180:183], 0
	v_mfma_f32_16x16x32_bf16 v[14:17], v[130:133], v[188:191], 0
	v_mfma_f32_16x16x32_bf16 v[10:13], v[156:159], v[188:191], 0
	v_mfma_f32_16x16x32_bf16 v[62:65], v[152:155], v[168:171], v[62:65]
	v_mfma_f32_16x16x32_bf16 v[58:61], v[160:163], v[168:171], v[58:61]
	v_mfma_f32_16x16x32_bf16 v[46:49], v[152:155], v[176:179], v[46:49]
	v_mfma_f32_16x16x32_bf16 v[42:45], v[160:163], v[176:179], v[42:45]
	v_mfma_f32_16x16x32_bf16 v[30:33], v[152:155], v[184:187], v[30:33]
	v_mfma_f32_16x16x32_bf16 v[26:29], v[160:163], v[184:187], v[26:29]
	v_mfma_f32_16x16x32_bf16 v[14:17], v[152:155], v[192:195], v[14:17]
	v_mfma_f32_16x16x32_bf16 v[10:13], v[160:163], v[192:195], v[10:13]
	s_barrier
; #define PG8_STAGE(bufoff, gbase, voff) do { _Pragma("unroll") for (int _i = 0; _i < 2; ++_i) \
;     __builtin_amdgcn_global_load_lds((const unsigned*)((const char*)(gbase) + (voff)[_i]), (PG8_LAS unsigned*)(lds + (bufoff) + ldsw + _i * 8192), 16, 0, 0); } while (0)
; #define PG8_LDA(dst, b, h) do { _Pragma("unroll") for (int m = 0; m < 4; ++m) _Pragma("unroll") for (int k = 0; k < 2; ++k) dst[m][k] = *(const PG8_LAS bf16x8*)(lds + PG8_SA(b, h) + aoff + m * 2048 + k * 1024); } while (0)
; #define PG8_LDB(dst, b, h) do { _Pragma("unroll") for (int n = 0; n < 2; ++n) _Pragma("unroll") for (int k = 0; k < 2; ++k) dst[n][k] = *(const PG8_LAS bf16x8*)(lds + PG8_SB(b, h) + boff + n * 2048 + k * 1024); } while (0)
; #define PG8_MMA(ai, bj, At, Bt) do { __builtin_amdgcn_s_setprio(1); _Pragma("unroll") for (int m = 0; m < 4; ++m) _Pragma("unroll") for (int n = 0; n < 2; ++n) _Pragma("unroll") for (int k = 0; k < 2; ++k) \
;     acc[ai][bj][m][n] = __builtin_amdgcn_mfma_f32_16x16x32_bf16(Bt[n][k], At[m][k], acc[ai][bj][m][n], 0, 0, 0); __builtin_amdgcn_s_setprio(0); } while (0)
; #define PG8_WAIT_V(n) asm volatile("s_waitcnt vmcnt(" #n ")" ::: "memory")
; #define PG8_WAIT_L(n) asm volatile("s_waitcnt lgkmcnt(" #n ")" ::: "memory")
; #define PG8_BAR __builtin_amdgcn_s_barrier()
; #define PG8_SCHED __builtin_amdgcn_sched_barrier(0)
; template <class Epi>
; DI void gemm_phase(PG8_LAS unsigned char* lds, const Gemm g, const StaticOrder& S, const Epi& E) {
;     ...
;       PG8_BAR; PG8_WAIT_L(0); PG8_MMA(1, 0, At, B0); PG8_BAR; PG8_SCHED;
;       PG8_STAGE(PG8_SB(0, 1), b2 + hstepB, voffB);
;       PG8_WAIT_V(6); PG8_BAR; PG8_MMA(1, 1, At, B1); PG8_BAR;
;       PG8_LDB(B0, 1, 0); PG8_SCHED; PG8_LDA(At, 1, 0); PG8_STAGE(PG8_SA(0, 1), a2 + hstepA, voffA);
;       PG8_WAIT_L(8); PG8_BAR; PG8_WAIT_L(0); PG8_MMA(0, 0, At, B0); PG8_BAR; PG8_SCHED;
;       PG8_LDB(B1, 1, 1); PG8_STAGE(PG8_SB(1, 0), b3, voffB);
;       PG8_BAR; PG8_WAIT_L(0); PG8_MMA(0, 1, At, B1); PG8_BAR;
;       PG8_LDA(At, 1, 1); PG8_STAGE(PG8_SA(1, 0), a3, voffA);
	s_add_u32 s58, s58, s62
	s_addc_u32 s59, s59, 0
	s_add_i32 s82, s83, s65
	v_lshl_add_u64 v[246:247], s[58:59], 0, v[0:1]
	s_mov_b32 m0, s82
	v_lshl_add_u64 v[248:249], s[58:59], 0, v[142:143]
	global_load_lds_dwordx4 v[246:247], off
	s_add_i32 m0, s82, 0x2000
	s_nop 0
	global_load_lds_dwordx4 v[248:249], off
	s_waitcnt vmcnt(6)
	s_barrier
	v_mfma_f32_16x16x32_bf16 v[54:57], v[196:199], v[164:167], 0
	v_mfma_f32_16x16x32_bf16 v[50:53], v[230:233], v[164:167], 0
	v_mfma_f32_16x16x32_bf16 v[38:41], v[196:199], v[172:175], 0
	v_mfma_f32_16x16x32_bf16 v[34:37], v[230:233], v[172:175], 0
	v_mfma_f32_16x16x32_bf16 v[22:25], v[196:199], v[180:183], 0
	v_mfma_f32_16x16x32_bf16 v[18:21], v[230:233], v[180:183], 0
	v_mfma_f32_16x16x32_bf16 v[6:9], v[196:199], v[188:191], 0
	v_mfma_f32_16x16x32_bf16 v[2:5], v[230:233], v[188:191], 0
	v_mfma_f32_16x16x32_bf16 v[54:57], v[226:229], v[168:171], v[54:57]
	v_mfma_f32_16x16x32_bf16 v[50:53], v[234:237], v[168:171], v[50:53]
	v_mfma_f32_16x16x32_bf16 v[38:41], v[226:229], v[176:179], v[38:41]
	v_mfma_f32_16x16x32_bf16 v[34:37], v[234:237], v[176:179], v[34:37]
	v_mfma_f32_16x16x32_bf16 v[22:25], v[226:229], v[184:187], v[22:25]
	v_mfma_f32_16x16x32_bf16 v[18:21], v[234:237], v[184:187], v[18:21]
	v_mfma_f32_16x16x32_bf16 v[6:9], v[226:229], v[192:195], v[6:9]
	v_mfma_f32_16x16x32_bf16 v[2:5], v[234:237], v[192:195], v[2:5]
	s_add_i32 s58, 0, 0x18000
	v_add_u32_e32 v160, s58, v223
	s_barrier
	ds_read_b128 v[130:133], v160
	ds_read_b128 v[152:155], v160 offset:1024
	ds_read_b128 v[156:159], v160 offset:2048
	ds_read_b128 v[160:163], v160 offset:3072
	s_add_u32 s56, s56, s50
	s_addc_u32 s57, s57, 0
	s_mov_b32 m0, s68
	v_lshl_add_u64 v[196:197], s[56:57], 0, v[146:147]
	ds_read_b128 v[164:167], v225 offset:32768
	ds_read_b128 v[168:171], v225 offset:33792
	ds_read_b128 v[172:175], v225 offset:34816
	ds_read_b128 v[176:179], v225 offset:35840
	ds_read_b128 v[180:183], v225 offset:36864
	ds_read_b128 v[184:187], v225 offset:37888
	ds_read_b128 v[188:191], v225 offset:38912
	ds_read_b128 v[192:195], v225 offset:39936
	global_load_lds_dwordx4 v[196:197], off
	v_lshl_add_u64 v[196:197], s[56:57], 0, v[144:145]
	s_mov_b32 m0, s69
	s_nop 0
	global_load_lds_dwordx4 v[196:197], off
	s_waitcnt lgkmcnt(8)
	s_barrier
	s_waitcnt lgkmcnt(0)
	s_waitcnt lgkmcnt(0)
	v_mfma_f32_16x16x32_bf16 v[126:129], v[130:133], v[164:167], v[126:129]
	v_mfma_f32_16x16x32_bf16 v[122:125], v[156:159], v[164:167], v[122:125]
	v_mfma_f32_16x16x32_bf16 v[110:113], v[130:133], v[172:175], v[110:113]
	v_mfma_f32_16x16x32_bf16 v[106:109], v[156:159], v[172:175], v[106:109]
	v_mfma_f32_16x16x32_bf16 v[94:97], v[130:133], v[180:183], v[94:97]
	v_mfma_f32_16x16x32_bf16 v[90:93], v[156:159], v[180:183], v[90:93]
	v_mfma_f32_16x16x32_bf16 v[78:81], v[130:133], v[188:191], v[78:81]
	v_mfma_f32_16x16x32_bf16 v[74:77], v[156:159], v[188:191], v[74:77]
	v_mfma_f32_16x16x32_bf16 v[126:129], v[152:155], v[168:171], v[126:129]
	v_mfma_f32_16x16x32_bf16 v[122:125], v[160:163], v[168:171], v[122:125]
	v_mfma_f32_16x16x32_bf16 v[110:113], v[152:155], v[176:179], v[110:113]
	v_mfma_f32_16x16x32_bf16 v[106:109], v[160:163], v[176:179], v[106:109]
	v_mfma_f32_16x16x32_bf16 v[94:97], v[152:155], v[184:187], v[94:97]
	v_mfma_f32_16x16x32_bf16 v[90:93], v[160:163], v[184:187], v[90:93]
	v_mfma_f32_16x16x32_bf16 v[78:81], v[152:155], v[192:195], v[78:81]
	v_mfma_f32_16x16x32_bf16 v[74:77], v[160:163], v[192:195], v[74:77]
	s_barrier
	s_add_i32 s56, 0, 0x1c000
	s_add_i32 s57, s58, s65
	v_add_u32_e32 v234, s56, v223
	v_lshl_add_u64 v[238:239], v[238:239], 0, s[86:87]
	s_mov_b32 m0, s57
	ds_read_b128 v[196:199], v234
	ds_read_b128 v[226:229], v234 offset:1024
	ds_read_b128 v[230:233], v234 offset:2048
	ds_read_b128 v[234:237], v234 offset:3072
	global_load_lds_dwordx4 v[238:239], off
	v_lshl_add_u64 v[238:239], v[240:241], 0, s[86:87]
	s_add_i32 m0, s57, 0x2000
	s_nop 0
	global_load_lds_dwordx4 v[238:239], off
	s_barrier
; #define PG8_STAGE(bufoff, gbase, voff) do { _Pragma("unroll") for (int _i = 0; _i < 2; ++_i) \
;     __builtin_amdgcn_global_load_lds((const unsigned*)((const char*)(gbase) + (voff)[_i]), (PG8_LAS unsigned*)(lds + (bufoff) + ldsw + _i * 8192), 16, 0, 0); } while (0)
; #define PG8_LDA(dst, b, h) do { _Pragma("unroll") for (int m = 0; m < 4; ++m) _Pragma("unroll") for (int k = 0; k < 2; ++k) dst[m][k] = *(const PG8_LAS bf16x8*)(lds + PG8_SA(b, h) + aoff + m * 2048 + k * 1024); } while (0)
; #define PG8_MMA(ai, bj, At, Bt) do { __builtin_amdgcn_s_setprio(1); _Pragma("unroll") for (int m = 0; m < 4; ++m) _Pragma("unroll") for (int n = 0; n < 2; ++n) _Pragma("unroll") for (int k = 0; k < 2; ++k) \
;     acc[ai][bj][m][n] = __builtin_amdgcn_mfma_f32_16x16x32_bf16(Bt[n][k], At[m][k], acc[ai][bj][m][n], 0, 0, 0); __builtin_amdgcn_s_setprio(0); } while (0)
; #define PG8_WAIT_V(n) asm volatile("s_waitcnt vmcnt(" #n ")" ::: "memory")
; #define PG8_WAIT_L(n) asm volatile("s_waitcnt lgkmcnt(" #n ")" ::: "memory")
; #define PG8_BAR __builtin_amdgcn_s_barrier()
; #define PG8_SCHED __builtin_amdgcn_sched_barrier(0)
; template <class Epi>
; DI void gemm_phase(PG8_LAS unsigned char* lds, const Gemm g, const StaticOrder& S, const Epi& E) {
;     ...
;       PG8_BAR; PG8_WAIT_L(0); PG8_MMA(0, 1, At, B1); PG8_BAR;
;       PG8_LDA(At, 1, 1); PG8_STAGE(PG8_SA(1, 0), a3, voffA);
;       PG8_BAR; PG8_WAIT_L(0); PG8_MMA(1, 0, At, B0); PG8_BAR; PG8_SCHED;
;       PG8_STAGE(PG8_SB(1, 1), b3 + hstepB, voffB);
;       PG8_WAIT_V(6); PG8_BAR; PG8_MMA(1, 1, At, B1); PG8_BAR;
;     }
	s_waitcnt lgkmcnt(0)
	s_waitcnt lgkmcnt(0)
	v_mfma_f32_16x16x32_bf16 v[118:121], v[196:199], v[164:167], v[118:121]
	v_mfma_f32_16x16x32_bf16 v[114:117], v[230:233], v[164:167], v[114:117]
	v_mfma_f32_16x16x32_bf16 v[102:105], v[196:199], v[172:175], v[102:105]
	v_mfma_f32_16x16x32_bf16 v[98:101], v[230:233], v[172:175], v[98:101]
	v_mfma_f32_16x16x32_bf16 v[86:89], v[196:199], v[180:183], v[86:89]
	v_mfma_f32_16x16x32_bf16 v[82:85], v[230:233], v[180:183], v[82:85]
	v_mfma_f32_16x16x32_bf16 v[70:73], v[196:199], v[188:191], v[70:73]
	v_mfma_f32_16x16x32_bf16 v[66:69], v[230:233], v[188:191], v[66:69]
	v_mfma_f32_16x16x32_bf16 v[118:121], v[226:229], v[168:171], v[118:121]
	v_mfma_f32_16x16x32_bf16 v[114:117], v[234:237], v[168:171], v[114:117]
	v_mfma_f32_16x16x32_bf16 v[102:105], v[226:229], v[176:179], v[102:105]
	v_mfma_f32_16x16x32_bf16 v[98:101], v[234:237], v[176:179], v[98:101]
	v_mfma_f32_16x16x32_bf16 v[86:89], v[226:229], v[184:187], v[86:89]
	v_mfma_f32_16x16x32_bf16 v[82:85], v[234:237], v[184:187], v[82:85]
	v_mfma_f32_16x16x32_bf16 v[70:73], v[226:229], v[192:195], v[70:73]
	v_mfma_f32_16x16x32_bf16 v[66:69], v[234:237], v[192:195], v[66:69]
	s_mov_b32 m0, s72
	v_lshl_add_u64 v[238:239], v[242:243], 0, s[86:87]
	s_barrier
	ds_read_b128 v[164:167], v225 offset:49152
	ds_read_b128 v[168:171], v225 offset:50176
	ds_read_b128 v[172:175], v225 offset:51200
	ds_read_b128 v[176:179], v225 offset:52224
	ds_read_b128 v[180:183], v225 offset:53248
	ds_read_b128 v[184:187], v225 offset:54272
	ds_read_b128 v[188:191], v225 offset:55296
	ds_read_b128 v[192:195], v225 offset:56320
	global_load_lds_dwordx4 v[238:239], off
	v_lshl_add_u64 v[238:239], v[244:245], 0, s[86:87]
	s_mov_b32 m0, s73
	s_nop 0
	global_load_lds_dwordx4 v[238:239], off
	s_barrier
	s_waitcnt lgkmcnt(0)
	s_waitcnt lgkmcnt(0)
	v_mfma_f32_16x16x32_bf16 v[62:65], v[130:133], v[164:167], v[62:65]
	v_mfma_f32_16x16x32_bf16 v[58:61], v[156:159], v[164:167], v[58:61]
	v_mfma_f32_16x16x32_bf16 v[46:49], v[130:133], v[172:175], v[46:49]
	v_mfma_f32_16x16x32_bf16 v[42:45], v[156:159], v[172:175], v[42:45]
	v_mfma_f32_16x16x32_bf16 v[30:33], v[130:133], v[180:183], v[30:33]
	v_mfma_f32_16x16x32_bf16 v[26:29], v[156:159], v[180:183], v[26:29]
	v_mfma_f32_16x16x32_bf16 v[14:17], v[130:133], v[188:191], v[14:17]
	v_mfma_f32_16x16x32_bf16 v[10:13], v[156:159], v[188:191], v[10:13]
	v_mfma_f32_16x16x32_bf16 v[62:65], v[152:155], v[168:171], v[62:65]
	v_mfma_f32_16x16x32_bf16 v[58:61], v[160:163], v[168:171], v[58:61]
	v_mfma_f32_16x16x32_bf16 v[46:49], v[152:155], v[176:179], v[46:49]
	v_mfma_f32_16x16x32_bf16 v[42:45], v[160:163], v[176:179], v[42:45]
	v_mfma_f32_16x16x32_bf16 v[30:33], v[152:155], v[184:187], v[30:33]
	v_mfma_f32_16x16x32_bf16 v[26:29], v[160:163], v[184:187], v[26:29]
	v_mfma_f32_16x16x32_bf16 v[14:17], v[152:155], v[192:195], v[14:17]
	v_mfma_f32_16x16x32_bf16 v[10:13], v[160:163], v[192:195], v[10:13]
	s_barrier
	s_add_i32 s56, s56, s65
	v_lshl_add_u64 v[130:131], v[246:247], 0, s[86:87]
	s_mov_b32 m0, s56
	s_nop 0
	global_load_lds_dwordx4 v[130:131], off
	v_lshl_add_u64 v[130:131], v[248:249], 0, s[86:87]
	s_add_i32 m0, s56, 0x2000
	s_nop 0
	global_load_lds_dwordx4 v[130:131], off
	s_waitcnt vmcnt(6)
	s_barrier
	v_mfma_f32_16x16x32_bf16 v[54:57], v[196:199], v[164:167], v[54:57]
	v_mfma_f32_16x16x32_bf16 v[50:53], v[230:233], v[164:167], v[50:53]
	v_mfma_f32_16x16x32_bf16 v[38:41], v[196:199], v[172:175], v[38:41]
	v_mfma_f32_16x16x32_bf16 v[34:37], v[230:233], v[172:175], v[34:37]
	v_mfma_f32_16x16x32_bf16 v[22:25], v[196:199], v[180:183], v[22:25]
	v_mfma_f32_16x16x32_bf16 v[18:21], v[230:233], v[180:183], v[18:21]
	v_mfma_f32_16x16x32_bf16 v[6:9], v[196:199], v[188:191], v[6:9]
	v_mfma_f32_16x16x32_bf16 v[2:5], v[230:233], v[188:191], v[2:5]
	v_mfma_f32_16x16x32_bf16 v[54:57], v[226:229], v[168:171], v[54:57]
	v_mfma_f32_16x16x32_bf16 v[50:53], v[234:237], v[168:171], v[50:53]
	v_mfma_f32_16x16x32_bf16 v[38:41], v[226:229], v[176:179], v[38:41]
	v_mfma_f32_16x16x32_bf16 v[34:37], v[234:237], v[176:179], v[34:37]
	v_mfma_f32_16x16x32_bf16 v[22:25], v[226:229], v[184:187], v[22:25]
	v_mfma_f32_16x16x32_bf16 v[18:21], v[234:237], v[184:187], v[18:21]
	v_mfma_f32_16x16x32_bf16 v[6:9], v[226:229], v[192:195], v[6:9]
	v_mfma_f32_16x16x32_bf16 v[2:5], v[234:237], v[192:195], v[2:5]
	s_add_u32 s44, s44, 0x100
	s_addc_u32 s45, s45, 0
	s_add_u32 s79, s79, 0x100
	s_addc_u32 s80, s80, 0
	s_cmp_ge_u32 s81, s71
	s_mov_b32 s56, s81
	s_barrier
	s_cbranch_scc1 .Lpeel_exit_1

; DI float bflo(unsigned u) { return __uint_as_float(u << 16); }
; DI float bfhi(unsigned u) { return __uint_as_float(u & 0xffff0000u); }
; #define PG8_LAS __attribute__((address_space(3)))
;   DI void operator()(const f32x4 (&acc)[2][2][4][2], const Unit& u, int wr, int wc, int fr, int fq, const PG8_LAS float* sR) const {
;     const int row0 = u.pm * BM + wr * 64 + fr, col0 = u.pn * BM + wc * 32 + 4 * fq;
; #pragma unroll
;     for (int ai = 0; ai < 2; ++ai) {
;       u32x2 sv[4][2][2];
;       if (X0 == nullptr) {
; #pragma unroll
;         for (int m = 0; m < 4; ++m)
; #pragma unroll
;           for (int bj = 0; bj < 2; ++bj)
; #pragma unroll
;             for (int n = 0; n < 2; ++n) sv[m][bj][n] = *(const u32x2*)(S + (size_t)(row0 + ai * HALF + m * 16) * 1024 + col0 + bj * HALF + n * 16);
;       } else {
; #pragma unroll
;         for (int m = 0; m < 4; ++m)
; #pragma unroll
;           for (int bj = 0; bj < 2; ++bj)
; #pragma unroll
;             for (int n = 0; n < 2; ++n) sv[m][bj][n] = (u32x2){0u, 0u};
;       }
; #pragma unroll
;       for (int m = 0; m < 4; ++m) {
;         const int row = row0 + ai * HALF + m * 16;
;         const size_t ro = (size_t)row * 1024 + col0;
;         float ss = 0.f;
; #pragma unroll
;         for (int bj = 0; bj < 2; ++bj)
; #pragma unroll
;           for (int n = 0; n < 2; ++n) {
;             f32x4 v;
;             if (X0 != nullptr) v = *(const f32x4*)(X0 + ro + bj * HALF + n * 16);
;             else { const u32x2 q = sv[m][bj][n]; v[0] = bflo(q[0]); v[1] = bfhi(q[0]); v[2] = bflo(q[1]); v[3] = bfhi(q[1]); }
;             v += acc[ai][bj][m][n];
.Lpeel_exit_1:
	s_and_b64 vcc, exec, s[52:53]
	s_cbranch_vccnz .Lres_x0_path
	v_and_b32_e32 v248, 15, v204
	v_lshrrev_b32_e32 v249, 4, v204
	v_and_b32_e32 v246, 1, v249
	v_lshrrev_b32_e32 v247, 1, v249
	v_lshl_or_b32 v246, v246, 1, v247
	v_lshl_add_u32 v246, v248, 2, v246
	v_lshlrev_b32_e32 v246, 2, v246
	v_and_b32_e32 v248, 3, v204
	v_lshrrev_b32_e32 v249, 2, v204
	v_and_b32_e32 v247, 1, v248
	v_lshrrev_b32_e32 v152, 1, v248
	v_lshl_or_b32 v247, v247, 1, v152
	v_lshl_add_u32 v247, v247, 4, v249
	v_lshlrev_b32_e32 v247, 2, v247
	v_and_b32_e32 v152, 64, v222
	v_add_u32_e32 v152, v152, v249
	v_lshl_add_u32 v152, s78, 8, v152
	v_and_b32_e32 v153, 0x60, v224
	v_lshl_or_b32 v153, v248, 3, v153
	v_lshl_or_b32 v154, s34, 8, v153
	v_lshlrev_b32_e32 v153, 10, v152
	v_add_u32_e32 v154, v154, v153
	v_mov_b32_e32 v155, 0
	v_lshl_add_u64 v[132:133], v[154:155], 1, s[22:23]
	v_mov_b64_e32 v[130:131], v[132:133]
	v_lshl_add_u32 v152, s78, 8, v222
	v_lshlrev_b32_e32 v154, 6, v152
	s_lshl_b32 s56, s34, 4
	s_lshl_b32 s57, s70, 2
	s_add_i32 s56, s56, s57
	v_add_u32_e32 v154, s56, v154
	v_lshl_add_u64 v[250:251], v[154:155], 0, s[92:93]
	s_mov_b32 s57, 0
	global_load_dwordx4 v[152:155], v[130:131], off
	global_load_dwordx4 v[156:159], v[130:131], off offset:256
	s_mov_b32 s56, 0x8000
	v_lshl_add_u64 v[130:131], v[130:131], 0, s[56:57]
	global_load_dwordx4 v[160:163], v[130:131], off
	global_load_dwordx4 v[164:167], v[130:131], off offset:256
	s_mov_b32 s56, 0x8000
	v_lshl_add_u64 v[130:131], v[130:131], 0, s[56:57]
	global_load_dwordx4 v[168:171], v[130:131], off
	global_load_dwordx4 v[172:175], v[130:131], off offset:256
	s_mov_b32 s56, 0x8000
	v_lshl_add_u64 v[130:131], v[130:131], 0, s[56:57]
	global_load_dwordx4 v[176:179], v[130:131], off
	global_load_dwordx4 v[180:183], v[130:131], off offset:256
	s_mov_b32 s56, 0x28000
	v_lshl_add_u64 v[130:131], v[130:131], 0, s[56:57]
	global_load_dwordx4 v[184:187], v[130:131], off
	global_load_dwordx4 v[188:191], v[130:131], off offset:256
	s_mov_b32 s56, 0x8000
	v_lshl_add_u64 v[130:131], v[130:131], 0, s[56:57]
	global_load_dwordx4 v[192:195], v[130:131], off
	global_load_dwordx4 v[196:199], v[130:131], off offset:256
	s_mov_b32 s56, 0x8000
	v_lshl_add_u64 v[130:131], v[130:131], 0, s[56:57]
	global_load_dwordx4 v[226:229], v[130:131], off
	global_load_dwordx4 v[230:233], v[130:131], off offset:256
	s_mov_b32 s56, 0x8000
	v_lshl_add_u64 v[130:131], v[130:131], 0, s[56:57]
	global_load_dwordx4 v[234:237], v[130:131], off
	global_load_dwordx4 v[238:241], v[130:131], off offset:256
	v_permlane16_swap_b32_e32 v126, v122
	v_permlane16_swap_b32_e32 v127, v123
	v_permlane16_swap_b32_e32 v128, v124
	v_permlane16_swap_b32_e32 v129, v125
	v_permlane16_swap_b32_e32 v118, v114
	v_permlane16_swap_b32_e32 v119, v115
	v_permlane16_swap_b32_e32 v120, v116
	v_permlane16_swap_b32_e32 v121, v117
	v_permlane16_swap_b32_e32 v110, v106
	v_permlane16_swap_b32_e32 v111, v107
	v_permlane16_swap_b32_e32 v112, v108
	v_permlane16_swap_b32_e32 v113, v109
	v_permlane16_swap_b32_e32 v102, v98
	v_permlane16_swap_b32_e32 v103, v99
	v_permlane16_swap_b32_e32 v104, v100
	v_permlane16_swap_b32_e32 v105, v101
	v_permlane16_swap_b32_e32 v94, v90
	v_permlane16_swap_b32_e32 v95, v91
	v_permlane16_swap_b32_e32 v96, v92
	v_permlane16_swap_b32_e32 v97, v93
	v_permlane16_swap_b32_e32 v86, v82
	v_permlane16_swap_b32_e32 v87, v83
	v_permlane16_swap_b32_e32 v88, v84
	v_permlane16_swap_b32_e32 v89, v85
	v_permlane16_swap_b32_e32 v78, v74
	v_permlane16_swap_b32_e32 v79, v75
	v_permlane16_swap_b32_e32 v80, v76
	v_permlane16_swap_b32_e32 v81, v77
	v_permlane16_swap_b32_e32 v70, v66
	v_permlane16_swap_b32_e32 v71, v67
	v_permlane16_swap_b32_e32 v72, v68
	v_permlane16_swap_b32_e32 v73, v69
	v_permlane16_swap_b32_e32 v62, v58
	v_permlane16_swap_b32_e32 v63, v59
	v_permlane16_swap_b32_e32 v64, v60
	v_permlane16_swap_b32_e32 v65, v61
	v_permlane16_swap_b32_e32 v54, v50
	v_permlane16_swap_b32_e32 v55, v51
	v_permlane16_swap_b32_e32 v56, v52
	v_permlane16_swap_b32_e32 v57, v53
	v_permlane16_swap_b32_e32 v46, v42
	v_permlane16_swap_b32_e32 v47, v43
	v_permlane16_swap_b32_e32 v48, v44
	v_permlane16_swap_b32_e32 v49, v45
	v_permlane16_swap_b32_e32 v38, v34
	v_permlane16_swap_b32_e32 v39, v35
	v_permlane16_swap_b32_e32 v40, v36
	v_permlane16_swap_b32_e32 v41, v37
	v_permlane16_swap_b32_e32 v30, v26
	v_permlane16_swap_b32_e32 v31, v27
	v_permlane16_swap_b32_e32 v32, v28
	v_permlane16_swap_b32_e32 v33, v29
	v_permlane16_swap_b32_e32 v22, v18
	v_permlane16_swap_b32_e32 v23, v19
	v_permlane16_swap_b32_e32 v24, v20
	v_permlane16_swap_b32_e32 v25, v21
	v_permlane16_swap_b32_e32 v14, v10
	v_permlane16_swap_b32_e32 v15, v11
	v_permlane16_swap_b32_e32 v16, v12
	v_permlane16_swap_b32_e32 v17, v13
	v_permlane16_swap_b32_e32 v6, v2
	v_permlane16_swap_b32_e32 v7, v3
	v_permlane16_swap_b32_e32 v8, v4
	v_permlane16_swap_b32_e32 v9, v5
	s_waitcnt vmcnt(15)
	ds_bpermute_b32 v152, v246, v152
	ds_bpermute_b32 v153, v246, v153
	ds_bpermute_b32 v154, v246, v154
	ds_bpermute_b32 v155, v246, v155
	s_waitcnt vmcnt(14)
	ds_bpermute_b32 v156, v246, v156
	ds_bpermute_b32 v157, v246, v157
	ds_bpermute_b32 v158, v246, v158
	ds_bpermute_b32 v159, v246, v159
	s_waitcnt lgkmcnt(4)
; DI unsigned pk2(float lo, float hi) { f32x2 v = {lo, hi}; bf2_t r = __builtin_convertvector(v, bf2_t); return __builtin_bit_cast(unsigned, r); }
; DI float bflo(unsigned u) { return __uint_as_float(u << 16); }
; DI float bfhi(unsigned u) { return __uint_as_float(u & 0xffff0000u); }
;   DI void operator()(const f32x4 (&acc)[2][2][4][2], const Unit& u, int wr, int wc, int fr, int fq, const PG8_LAS float* sR) const {
;     ...
; #pragma unroll
;       for (int m = 0; m < 4; ++m) {
;         const int row = row0 + ai * HALF + m * 16;
;         const size_t ro = (size_t)row * 1024 + col0;
;         float ss = 0.f;
; #pragma unroll
;         for (int bj = 0; bj < 2; ++bj)
; #pragma unroll
;           for (int n = 0; n < 2; ++n) {
;             f32x4 v;
;             if (X0 != nullptr) v = *(const f32x4*)(X0 + ro + bj * HALF + n * 16);
;             else { const u32x2 q = sv[m][bj][n]; v[0] = bflo(q[0]); v[1] = bfhi(q[0]); v[2] = bflo(q[1]); v[3] = bfhi(q[1]); }
;             v += acc[ai][bj][m][n];
;             ss += v[0] * v[0] + v[1] * v[1] + v[2] * v[2] + v[3] * v[3];
;             if (!dry) { u32x2 q; q[0] = pk2(v[0], v[1]); q[1] = pk2(v[2], v[3]); *(u32x2*)(S + ro + bj * HALF + n * 16) = q; }
;           }
;         ss += __shfl_xor(ss, 16); ss += __shfl_xor(ss, 32);
;         if (!dry && fq == 0) ssq[(size_t)row * 16 + u.pn * 4 + wc] = ss;
;       }
	v_lshlrev_b32_e32 v242, 16, v152
	v_and_b32_e32 v243, 0xffff0000, v152
	v_lshlrev_b32_e32 v244, 16, v153
	v_and_b32_e32 v245, 0xffff0000, v153
	v_pk_add_f32 v[126:127], v[126:127], v[242:243]
	v_pk_add_f32 v[128:129], v[128:129], v[244:245]
	v_lshlrev_b32_e32 v242, 16, v154
	v_and_b32_e32 v243, 0xffff0000, v154
	v_lshlrev_b32_e32 v244, 16, v155
	v_and_b32_e32 v245, 0xffff0000, v155
	v_pk_add_f32 v[122:123], v[122:123], v[242:243]
	v_pk_add_f32 v[124:125], v[124:125], v[244:245]
	v_mul_f32_e32 v130, v126, v126
	v_mul_f32_e32 v131, v127, v127
	v_fmac_f32_e32 v130, v128, v128
	v_fmac_f32_e32 v131, v129, v129
	v_fmac_f32_e32 v130, v122, v122
	v_fmac_f32_e32 v131, v123, v123
	v_fmac_f32_e32 v130, v124, v124
	v_fmac_f32_e32 v131, v125, v125
	v_cvt_pk_bf16_f32 v126, v126, v127
	v_cvt_pk_bf16_f32 v127, v128, v129
	v_cvt_pk_bf16_f32 v128, v122, v123
	v_cvt_pk_bf16_f32 v129, v124, v125
	ds_bpermute_b32 v126, v247, v126
	ds_bpermute_b32 v127, v247, v127
	ds_bpermute_b32 v128, v247, v128
	ds_bpermute_b32 v129, v247, v129
	s_waitcnt vmcnt(13)
	ds_bpermute_b32 v160, v246, v160
	ds_bpermute_b32 v161, v246, v161
	ds_bpermute_b32 v162, v246, v162
	ds_bpermute_b32 v163, v246, v163
	s_waitcnt lgkmcnt(8)
	v_lshlrev_b32_e32 v242, 16, v156
	v_and_b32_e32 v243, 0xffff0000, v156
	v_lshlrev_b32_e32 v244, 16, v157
	v_and_b32_e32 v245, 0xffff0000, v157
	v_pk_add_f32 v[118:119], v[118:119], v[242:243]
	v_pk_add_f32 v[120:121], v[120:121], v[244:245]
	v_lshlrev_b32_e32 v242, 16, v158
	v_and_b32_e32 v243, 0xffff0000, v158
	v_lshlrev_b32_e32 v244, 16, v159
	v_and_b32_e32 v245, 0xffff0000, v159
	v_pk_add_f32 v[114:115], v[114:115], v[242:243]
	v_pk_add_f32 v[116:117], v[116:117], v[244:245]
	v_fmac_f32_e32 v130, v118, v118
	v_fmac_f32_e32 v131, v119, v119
	v_fmac_f32_e32 v130, v120, v120
	v_fmac_f32_e32 v131, v121, v121
	v_fmac_f32_e32 v130, v114, v114
	v_fmac_f32_e32 v131, v115, v115
	v_fmac_f32_e32 v130, v116, v116
	v_fmac_f32_e32 v131, v117, v117
	v_cvt_pk_bf16_f32 v118, v118, v119
	v_cvt_pk_bf16_f32 v119, v120, v121
	v_cvt_pk_bf16_f32 v120, v114, v115
	v_cvt_pk_bf16_f32 v121, v116, v117
	ds_bpermute_b32 v118, v247, v118
	ds_bpermute_b32 v119, v247, v119
	ds_bpermute_b32 v120, v247, v120
	ds_bpermute_b32 v121, v247, v121
	v_add_f32_e32 v130, v130, v131
	v_mov_b32_e32 v131, v130
	s_nop 1
	v_permlane16_swap_b32_e32 v130, v131
	s_nop 1
	v_add_f32_e32 v130, v130, v131
	v_mov_b32_e32 v131, v130
	s_nop 1
	v_permlane32_swap_b32_e32 v130, v131
	s_nop 1
	v_add_f32_e32 v130, v130, v131
	s_and_saveexec_b64 s[58:59], s[40:41]
	global_store_dword v[250:251], v130, off
	s_or_b64 exec, exec, s[58:59]
	s_mov_b32 s56, 0x400
	v_lshl_add_u64 v[250:251], v[250:251], 0, s[56:57]
	s_waitcnt vmcnt(13)
	ds_bpermute_b32 v164, v246, v164
	ds_bpermute_b32 v165, v246, v165
	ds_bpermute_b32 v166, v246, v166
	ds_bpermute_b32 v167, v246, v167
	s_waitcnt lgkmcnt(12)
	global_store_dwordx4 v[132:133], v[126:129], off
	s_waitcnt lgkmcnt(8)
	v_lshlrev_b32_e32 v242, 16, v160
	v_and_b32_e32 v243, 0xffff0000, v160
	v_lshlrev_b32_e32 v244, 16, v161
	v_and_b32_e32 v245, 0xffff0000, v161
	v_pk_add_f32 v[110:111], v[110:111], v[242:243]
	v_pk_add_f32 v[112:113], v[112:113], v[244:245]
	v_lshlrev_b32_e32 v242, 16, v162
	v_and_b32_e32 v243, 0xffff0000, v162
	v_lshlrev_b32_e32 v244, 16, v163
	v_and_b32_e32 v245, 0xffff0000, v163
	v_pk_add_f32 v[106:107], v[106:107], v[242:243]
	v_pk_add_f32 v[108:109], v[108:109], v[244:245]
	v_mul_f32_e32 v130, v110, v110
	v_mul_f32_e32 v131, v111, v111
	v_fmac_f32_e32 v130, v112, v112
	v_fmac_f32_e32 v131, v113, v113
	v_fmac_f32_e32 v130, v106, v106
	v_fmac_f32_e32 v131, v107, v107
	v_fmac_f32_e32 v130, v108, v108
	v_fmac_f32_e32 v131, v109, v109
	v_cvt_pk_bf16_f32 v110, v110, v111
	v_cvt_pk_bf16_f32 v111, v112, v113
	v_cvt_pk_bf16_f32 v112, v106, v107
	v_cvt_pk_bf16_f32 v113, v108, v109
	ds_bpermute_b32 v110, v247, v110
	ds_bpermute_b32 v111, v247, v111
	ds_bpermute_b32 v112, v247, v112
	ds_bpermute_b32 v113, v247, v113
	s_waitcnt vmcnt(13)
	ds_bpermute_b32 v168, v246, v168
	ds_bpermute_b32 v169, v246, v169
	ds_bpermute_b32 v170, v246, v170
	ds_bpermute_b32 v171, v246, v171
	s_waitcnt lgkmcnt(12)
	global_store_dwordx4 v[132:133], v[118:121], off offset:256
	s_mov_b32 s56, 0x8000
	v_lshl_add_u64 v[132:133], v[132:133], 0, s[56:57]
	s_waitcnt lgkmcnt(8)
	v_lshlrev_b32_e32 v242, 16, v164
	v_and_b32_e32 v243, 0xffff0000, v164
	v_lshlrev_b32_e32 v244, 16, v165
	v_and_b32_e32 v245, 0xffff0000, v165
	v_pk_add_f32 v[102:103], v[102:103], v[242:243]
	v_pk_add_f32 v[104:105], v[104:105], v[244:245]
	v_lshlrev_b32_e32 v242, 16, v166
	v_and_b32_e32 v243, 0xffff0000, v166
	v_lshlrev_b32_e32 v244, 16, v167
	v_and_b32_e32 v245, 0xffff0000, v167
	v_pk_add_f32 v[98:99], v[98:99], v[242:243]
	v_pk_add_f32 v[100:101], v[100:101], v[244:245]
	v_fmac_f32_e32 v130, v102, v102
	v_fmac_f32_e32 v131, v103, v103
	v_fmac_f32_e32 v130, v104, v104
	v_fmac_f32_e32 v131, v105, v105
	v_fmac_f32_e32 v130, v98, v98
	v_fmac_f32_e32 v131, v99, v99
	v_fmac_f32_e32 v130, v100, v100
	v_fmac_f32_e32 v131, v101, v101
	v_cvt_pk_bf16_f32 v102, v102, v103
	v_cvt_pk_bf16_f32 v103, v104, v105
	v_cvt_pk_bf16_f32 v104, v98, v99
	v_cvt_pk_bf16_f32 v105, v100, v101
	ds_bpermute_b32 v102, v247, v102
	ds_bpermute_b32 v103, v247, v103
	ds_bpermute_b32 v104, v247, v104
	ds_bpermute_b32 v105, v247, v105
	v_add_f32_e32 v130, v130, v131
	v_mov_b32_e32 v131, v130
	s_nop 1
	v_permlane16_swap_b32_e32 v130, v131
	s_nop 1
	v_add_f32_e32 v130, v130, v131
	v_mov_b32_e32 v131, v130
	s_nop 1
	v_permlane32_swap_b32_e32 v130, v131
	s_nop 1
	v_add_f32_e32 v130, v130, v131
	s_and_saveexec_b64 s[58:59], s[40:41]
	global_store_dword v[250:251], v130, off
	s_or_b64 exec, exec, s[58:59]
	s_mov_b32 s56, 0x400
	v_lshl_add_u64 v[250:251], v[250:251], 0, s[56:57]
	s_waitcnt vmcnt(14)
; DI unsigned pk2(float lo, float hi) { f32x2 v = {lo, hi}; bf2_t r = __builtin_convertvector(v, bf2_t); return __builtin_bit_cast(unsigned, r); }
; DI float bflo(unsigned u) { return __uint_as_float(u << 16); }
; DI float bfhi(unsigned u) { return __uint_as_float(u & 0xffff0000u); }
;   DI void operator()(const f32x4 (&acc)[2][2][4][2], const Unit& u, int wr, int wc, int fr, int fq, const PG8_LAS float* sR) const {
;     ...
; #pragma unroll
;       for (int m = 0; m < 4; ++m) {
;         const int row = row0 + ai * HALF + m * 16;
;         const size_t ro = (size_t)row * 1024 + col0;
;         float ss = 0.f;
; #pragma unroll
;         for (int bj = 0; bj < 2; ++bj)
; #pragma unroll
;           for (int n = 0; n < 2; ++n) {
;             f32x4 v;
;             if (X0 != nullptr) v = *(const f32x4*)(X0 + ro + bj * HALF + n * 16);
;             else { const u32x2 q = sv[m][bj][n]; v[0] = bflo(q[0]); v[1] = bfhi(q[0]); v[2] = bflo(q[1]); v[3] = bfhi(q[1]); }
;             v += acc[ai][bj][m][n];
;             ss += v[0] * v[0] + v[1] * v[1] + v[2] * v[2] + v[3] * v[3];
;             if (!dry) { u32x2 q; q[0] = pk2(v[0], v[1]); q[1] = pk2(v[2], v[3]); *(u32x2*)(S + ro + bj * HALF + n * 16) = q; }
;           }
;         ss += __shfl_xor(ss, 16); ss += __shfl_xor(ss, 32);
;         if (!dry && fq == 0) ssq[(size_t)row * 16 + u.pn * 4 + wc] = ss;
;       }
	ds_bpermute_b32 v172, v246, v172
	ds_bpermute_b32 v173, v246, v173
	ds_bpermute_b32 v174, v246, v174
	ds_bpermute_b32 v175, v246, v175
	s_waitcnt lgkmcnt(12)
	global_store_dwordx4 v[132:133], v[110:113], off
	s_waitcnt lgkmcnt(8)
	v_lshlrev_b32_e32 v242, 16, v168
	v_and_b32_e32 v243, 0xffff0000, v168
	v_lshlrev_b32_e32 v244, 16, v169
	v_and_b32_e32 v245, 0xffff0000, v169
	v_pk_add_f32 v[94:95], v[94:95], v[242:243]
	v_pk_add_f32 v[96:97], v[96:97], v[244:245]
	v_lshlrev_b32_e32 v242, 16, v170
	v_and_b32_e32 v243, 0xffff0000, v170
	v_lshlrev_b32_e32 v244, 16, v171
	v_and_b32_e32 v245, 0xffff0000, v171
	v_pk_add_f32 v[90:91], v[90:91], v[242:243]
	v_pk_add_f32 v[92:93], v[92:93], v[244:245]
	v_mul_f32_e32 v130, v94, v94
	v_mul_f32_e32 v131, v95, v95
	v_fmac_f32_e32 v130, v96, v96
	v_fmac_f32_e32 v131, v97, v97
	v_fmac_f32_e32 v130, v90, v90
	v_fmac_f32_e32 v131, v91, v91
	v_fmac_f32_e32 v130, v92, v92
	v_fmac_f32_e32 v131, v93, v93
	v_cvt_pk_bf16_f32 v94, v94, v95
	v_cvt_pk_bf16_f32 v95, v96, v97
	v_cvt_pk_bf16_f32 v96, v90, v91
	v_cvt_pk_bf16_f32 v97, v92, v93
	ds_bpermute_b32 v94, v247, v94
	ds_bpermute_b32 v95, v247, v95
	ds_bpermute_b32 v96, v247, v96
	ds_bpermute_b32 v97, v247, v97
	s_waitcnt vmcnt(14)
	ds_bpermute_b32 v176, v246, v176
	ds_bpermute_b32 v177, v246, v177
	ds_bpermute_b32 v178, v246, v178
	ds_bpermute_b32 v179, v246, v179
	s_waitcnt lgkmcnt(12)
	global_store_dwordx4 v[132:133], v[102:105], off offset:256
	s_mov_b32 s56, 0x8000
	v_lshl_add_u64 v[132:133], v[132:133], 0, s[56:57]
	s_waitcnt lgkmcnt(8)
	v_lshlrev_b32_e32 v242, 16, v172
	v_and_b32_e32 v243, 0xffff0000, v172
	v_lshlrev_b32_e32 v244, 16, v173
	v_and_b32_e32 v245, 0xffff0000, v173
	v_pk_add_f32 v[86:87], v[86:87], v[242:243]
	v_pk_add_f32 v[88:89], v[88:89], v[244:245]
	v_lshlrev_b32_e32 v242, 16, v174
	v_and_b32_e32 v243, 0xffff0000, v174
	v_lshlrev_b32_e32 v244, 16, v175
	v_and_b32_e32 v245, 0xffff0000, v175
	v_pk_add_f32 v[82:83], v[82:83], v[242:243]
	v_pk_add_f32 v[84:85], v[84:85], v[244:245]
	v_fmac_f32_e32 v130, v86, v86
	v_fmac_f32_e32 v131, v87, v87
	v_fmac_f32_e32 v130, v88, v88
	v_fmac_f32_e32 v131, v89, v89
	v_fmac_f32_e32 v130, v82, v82
	v_fmac_f32_e32 v131, v83, v83
	v_fmac_f32_e32 v130, v84, v84
	v_fmac_f32_e32 v131, v85, v85
	v_cvt_pk_bf16_f32 v86, v86, v87
	v_cvt_pk_bf16_f32 v87, v88, v89
	v_cvt_pk_bf16_f32 v88, v82, v83
	v_cvt_pk_bf16_f32 v89, v84, v85
	ds_bpermute_b32 v86, v247, v86
	ds_bpermute_b32 v87, v247, v87
	ds_bpermute_b32 v88, v247, v88
	ds_bpermute_b32 v89, v247, v89
	v_add_f32_e32 v130, v130, v131
	v_mov_b32_e32 v131, v130
	s_nop 1
	v_permlane16_swap_b32_e32 v130, v131
	s_nop 1
	v_add_f32_e32 v130, v130, v131
	v_mov_b32_e32 v131, v130
	s_nop 1
	v_permlane32_swap_b32_e32 v130, v131
	s_nop 1
	v_add_f32_e32 v130, v130, v131
	s_and_saveexec_b64 s[58:59], s[40:41]
	global_store_dword v[250:251], v130, off
	s_or_b64 exec, exec, s[58:59]
	s_mov_b32 s56, 0x400
	v_lshl_add_u64 v[250:251], v[250:251], 0, s[56:57]
	s_waitcnt vmcnt(15)
	ds_bpermute_b32 v180, v246, v180
	ds_bpermute_b32 v181, v246, v181
	ds_bpermute_b32 v182, v246, v182
	ds_bpermute_b32 v183, v246, v183
	s_waitcnt lgkmcnt(12)
	global_store_dwordx4 v[132:133], v[94:97], off
	s_waitcnt lgkmcnt(8)
	v_lshlrev_b32_e32 v242, 16, v176
	v_and_b32_e32 v243, 0xffff0000, v176
	v_lshlrev_b32_e32 v244, 16, v177
	v_and_b32_e32 v245, 0xffff0000, v177
	v_pk_add_f32 v[78:79], v[78:79], v[242:243]
	v_pk_add_f32 v[80:81], v[80:81], v[244:245]
	v_lshlrev_b32_e32 v242, 16, v178
	v_and_b32_e32 v243, 0xffff0000, v178
	v_lshlrev_b32_e32 v244, 16, v179
	v_and_b32_e32 v245, 0xffff0000, v179
	v_pk_add_f32 v[74:75], v[74:75], v[242:243]
	v_pk_add_f32 v[76:77], v[76:77], v[244:245]
	v_mul_f32_e32 v130, v78, v78
	v_mul_f32_e32 v131, v79, v79
	v_fmac_f32_e32 v130, v80, v80
	v_fmac_f32_e32 v131, v81, v81
	v_fmac_f32_e32 v130, v74, v74
	v_fmac_f32_e32 v131, v75, v75
	v_fmac_f32_e32 v130, v76, v76
	v_fmac_f32_e32 v131, v77, v77
	v_cvt_pk_bf16_f32 v78, v78, v79
	v_cvt_pk_bf16_f32 v79, v80, v81
	v_cvt_pk_bf16_f32 v80, v74, v75
	v_cvt_pk_bf16_f32 v81, v76, v77
	ds_bpermute_b32 v78, v247, v78
	ds_bpermute_b32 v79, v247, v79
	ds_bpermute_b32 v80, v247, v80
	ds_bpermute_b32 v81, v247, v81
	s_waitcnt vmcnt(15)
	ds_bpermute_b32 v184, v246, v184
	ds_bpermute_b32 v185, v246, v185
	ds_bpermute_b32 v186, v246, v186
	ds_bpermute_b32 v187, v246, v187
	s_waitcnt lgkmcnt(12)
	global_store_dwordx4 v[132:133], v[86:89], off offset:256
	s_mov_b32 s56, 0x8000
	v_lshl_add_u64 v[132:133], v[132:133], 0, s[56:57]
	s_waitcnt lgkmcnt(8)
	v_lshlrev_b32_e32 v242, 16, v180
	v_and_b32_e32 v243, 0xffff0000, v180
	v_lshlrev_b32_e32 v244, 16, v181
	v_and_b32_e32 v245, 0xffff0000, v181
	v_pk_add_f32 v[70:71], v[70:71], v[242:243]
	v_pk_add_f32 v[72:73], v[72:73], v[244:245]
	v_lshlrev_b32_e32 v242, 16, v182
	v_and_b32_e32 v243, 0xffff0000, v182
	v_lshlrev_b32_e32 v244, 16, v183
	v_and_b32_e32 v245, 0xffff0000, v183
	v_pk_add_f32 v[66:67], v[66:67], v[242:243]
	v_pk_add_f32 v[68:69], v[68:69], v[244:245]
	v_fmac_f32_e32 v130, v70, v70
	v_fmac_f32_e32 v131, v71, v71
	v_fmac_f32_e32 v130, v72, v72
	v_fmac_f32_e32 v131, v73, v73
	v_fmac_f32_e32 v130, v66, v66
	v_fmac_f32_e32 v131, v67, v67
	v_fmac_f32_e32 v130, v68, v68
	v_fmac_f32_e32 v131, v69, v69
	v_cvt_pk_bf16_f32 v70, v70, v71
	v_cvt_pk_bf16_f32 v71, v72, v73
	v_cvt_pk_bf16_f32 v72, v66, v67
	v_cvt_pk_bf16_f32 v73, v68, v69
	ds_bpermute_b32 v70, v247, v70
	ds_bpermute_b32 v71, v247, v71
	ds_bpermute_b32 v72, v247, v72
	ds_bpermute_b32 v73, v247, v73
	v_add_f32_e32 v130, v130, v131
	v_mov_b32_e32 v131, v130
	s_nop 1
	v_permlane16_swap_b32_e32 v130, v131
	s_nop 1
	v_add_f32_e32 v130, v130, v131
	v_mov_b32_e32 v131, v130
	s_nop 1
	v_permlane32_swap_b32_e32 v130, v131
	s_nop 1
	v_add_f32_e32 v130, v130, v131
	s_and_saveexec_b64 s[58:59], s[40:41]
	global_store_dword v[250:251], v130, off
	s_or_b64 exec, exec, s[58:59]
	s_mov_b32 s56, 0x1400
	v_lshl_add_u64 v[250:251], v[250:251], 0, s[56:57]
	s_waitcnt vmcnt(16)
; DI unsigned pk2(float lo, float hi) { f32x2 v = {lo, hi}; bf2_t r = __builtin_convertvector(v, bf2_t); return __builtin_bit_cast(unsigned, r); }
; DI float bflo(unsigned u) { return __uint_as_float(u << 16); }
; DI float bfhi(unsigned u) { return __uint_as_float(u & 0xffff0000u); }
;   DI void operator()(const f32x4 (&acc)[2][2][4][2], const Unit& u, int wr, int wc, int fr, int fq, const PG8_LAS float* sR) const {
;     ...
; #pragma unroll
;       for (int m = 0; m < 4; ++m) {
;         const int row = row0 + ai * HALF + m * 16;
;         const size_t ro = (size_t)row * 1024 + col0;
;         float ss = 0.f;
; #pragma unroll
;         for (int bj = 0; bj < 2; ++bj)
; #pragma unroll
;           for (int n = 0; n < 2; ++n) {
;             f32x4 v;
;             if (X0 != nullptr) v = *(const f32x4*)(X0 + ro + bj * HALF + n * 16);
;             else { const u32x2 q = sv[m][bj][n]; v[0] = bflo(q[0]); v[1] = bfhi(q[0]); v[2] = bflo(q[1]); v[3] = bfhi(q[1]); }
;             v += acc[ai][bj][m][n];
;             ss += v[0] * v[0] + v[1] * v[1] + v[2] * v[2] + v[3] * v[3];
;             if (!dry) { u32x2 q; q[0] = pk2(v[0], v[1]); q[1] = pk2(v[2], v[3]); *(u32x2*)(S + ro + bj * HALF + n * 16) = q; }
;           }
;         ss += __shfl_xor(ss, 16); ss += __shfl_xor(ss, 32);
;         if (!dry && fq == 0) ssq[(size_t)row * 16 + u.pn * 4 + wc] = ss;
;       }
	ds_bpermute_b32 v188, v246, v188
	ds_bpermute_b32 v189, v246, v189
	ds_bpermute_b32 v190, v246, v190
	ds_bpermute_b32 v191, v246, v191
	s_waitcnt lgkmcnt(12)
	global_store_dwordx4 v[132:133], v[78:81], off
	s_waitcnt lgkmcnt(8)
	v_lshlrev_b32_e32 v242, 16, v184
	v_and_b32_e32 v243, 0xffff0000, v184
	v_lshlrev_b32_e32 v244, 16, v185
	v_and_b32_e32 v245, 0xffff0000, v185
	v_pk_add_f32 v[62:63], v[62:63], v[242:243]
	v_pk_add_f32 v[64:65], v[64:65], v[244:245]
	v_lshlrev_b32_e32 v242, 16, v186
	v_and_b32_e32 v243, 0xffff0000, v186
	v_lshlrev_b32_e32 v244, 16, v187
	v_and_b32_e32 v245, 0xffff0000, v187
	v_pk_add_f32 v[58:59], v[58:59], v[242:243]
	v_pk_add_f32 v[60:61], v[60:61], v[244:245]
	v_mul_f32_e32 v130, v62, v62
	v_mul_f32_e32 v131, v63, v63
	v_fmac_f32_e32 v130, v64, v64
	v_fmac_f32_e32 v131, v65, v65
	v_fmac_f32_e32 v130, v58, v58
	v_fmac_f32_e32 v131, v59, v59
	v_fmac_f32_e32 v130, v60, v60
	v_fmac_f32_e32 v131, v61, v61
	v_cvt_pk_bf16_f32 v62, v62, v63
	v_cvt_pk_bf16_f32 v63, v64, v65
	v_cvt_pk_bf16_f32 v64, v58, v59
	v_cvt_pk_bf16_f32 v65, v60, v61
	ds_bpermute_b32 v62, v247, v62
	ds_bpermute_b32 v63, v247, v63
	ds_bpermute_b32 v64, v247, v64
	ds_bpermute_b32 v65, v247, v65
	s_waitcnt vmcnt(16)
	ds_bpermute_b32 v192, v246, v192
	ds_bpermute_b32 v193, v246, v193
	ds_bpermute_b32 v194, v246, v194
	ds_bpermute_b32 v195, v246, v195
	s_waitcnt lgkmcnt(12)
	global_store_dwordx4 v[132:133], v[70:73], off offset:256
	s_mov_b32 s56, 0x28000
	v_lshl_add_u64 v[132:133], v[132:133], 0, s[56:57]
	s_waitcnt lgkmcnt(8)
	v_lshlrev_b32_e32 v242, 16, v188
	v_and_b32_e32 v243, 0xffff0000, v188
	v_lshlrev_b32_e32 v244, 16, v189
	v_and_b32_e32 v245, 0xffff0000, v189
	v_pk_add_f32 v[54:55], v[54:55], v[242:243]
	v_pk_add_f32 v[56:57], v[56:57], v[244:245]
	v_lshlrev_b32_e32 v242, 16, v190
	v_and_b32_e32 v243, 0xffff0000, v190
	v_lshlrev_b32_e32 v244, 16, v191
	v_and_b32_e32 v245, 0xffff0000, v191
	v_pk_add_f32 v[50:51], v[50:51], v[242:243]
	v_pk_add_f32 v[52:53], v[52:53], v[244:245]
	v_fmac_f32_e32 v130, v54, v54
	v_fmac_f32_e32 v131, v55, v55
	v_fmac_f32_e32 v130, v56, v56
	v_fmac_f32_e32 v131, v57, v57
	v_fmac_f32_e32 v130, v50, v50
	v_fmac_f32_e32 v131, v51, v51
	v_fmac_f32_e32 v130, v52, v52
	v_fmac_f32_e32 v131, v53, v53
	v_cvt_pk_bf16_f32 v54, v54, v55
	v_cvt_pk_bf16_f32 v55, v56, v57
	v_cvt_pk_bf16_f32 v56, v50, v51
	v_cvt_pk_bf16_f32 v57, v52, v53
	ds_bpermute_b32 v54, v247, v54
	ds_bpermute_b32 v55, v247, v55
	ds_bpermute_b32 v56, v247, v56
	ds_bpermute_b32 v57, v247, v57
	v_add_f32_e32 v130, v130, v131
	v_mov_b32_e32 v131, v130
	s_nop 1
	v_permlane16_swap_b32_e32 v130, v131
	s_nop 1
	v_add_f32_e32 v130, v130, v131
	v_mov_b32_e32 v131, v130
	s_nop 1
	v_permlane32_swap_b32_e32 v130, v131
	s_nop 1
	v_add_f32_e32 v130, v130, v131
	s_and_saveexec_b64 s[58:59], s[40:41]
	global_store_dword v[250:251], v130, off
	s_or_b64 exec, exec, s[58:59]
	s_mov_b32 s56, 0x400
	v_lshl_add_u64 v[250:251], v[250:251], 0, s[56:57]
	s_waitcnt vmcnt(17)
	ds_bpermute_b32 v196, v246, v196
	ds_bpermute_b32 v197, v246, v197
	ds_bpermute_b32 v198, v246, v198
	ds_bpermute_b32 v199, v246, v199
	s_waitcnt lgkmcnt(12)
	global_store_dwordx4 v[132:133], v[62:65], off
	s_waitcnt lgkmcnt(8)
	v_lshlrev_b32_e32 v242, 16, v192
	v_and_b32_e32 v243, 0xffff0000, v192
	v_lshlrev_b32_e32 v244, 16, v193
	v_and_b32_e32 v245, 0xffff0000, v193
	v_pk_add_f32 v[46:47], v[46:47], v[242:243]
	v_pk_add_f32 v[48:49], v[48:49], v[244:245]
	v_lshlrev_b32_e32 v242, 16, v194
	v_and_b32_e32 v243, 0xffff0000, v194
	v_lshlrev_b32_e32 v244, 16, v195
	v_and_b32_e32 v245, 0xffff0000, v195
	v_pk_add_f32 v[42:43], v[42:43], v[242:243]
	v_pk_add_f32 v[44:45], v[44:45], v[244:245]
	v_mul_f32_e32 v130, v46, v46
	v_mul_f32_e32 v131, v47, v47
	v_fmac_f32_e32 v130, v48, v48
	v_fmac_f32_e32 v131, v49, v49
	v_fmac_f32_e32 v130, v42, v42
	v_fmac_f32_e32 v131, v43, v43
	v_fmac_f32_e32 v130, v44, v44
	v_fmac_f32_e32 v131, v45, v45
	v_cvt_pk_bf16_f32 v46, v46, v47
	v_cvt_pk_bf16_f32 v47, v48, v49
	v_cvt_pk_bf16_f32 v48, v42, v43
	v_cvt_pk_bf16_f32 v49, v44, v45
	ds_bpermute_b32 v46, v247, v46
	ds_bpermute_b32 v47, v247, v47
	ds_bpermute_b32 v48, v247, v48
	ds_bpermute_b32 v49, v247, v49
	s_waitcnt vmcnt(17)
	ds_bpermute_b32 v226, v246, v226
	ds_bpermute_b32 v227, v246, v227
	ds_bpermute_b32 v228, v246, v228
	ds_bpermute_b32 v229, v246, v229
	s_waitcnt lgkmcnt(12)
	global_store_dwordx4 v[132:133], v[54:57], off offset:256
	s_mov_b32 s56, 0x8000
	v_lshl_add_u64 v[132:133], v[132:133], 0, s[56:57]
	s_waitcnt lgkmcnt(8)
	v_lshlrev_b32_e32 v242, 16, v196
	v_and_b32_e32 v243, 0xffff0000, v196
	v_lshlrev_b32_e32 v244, 16, v197
	v_and_b32_e32 v245, 0xffff0000, v197
	v_pk_add_f32 v[38:39], v[38:39], v[242:243]
	v_pk_add_f32 v[40:41], v[40:41], v[244:245]
	v_lshlrev_b32_e32 v242, 16, v198
	v_and_b32_e32 v243, 0xffff0000, v198
	v_lshlrev_b32_e32 v244, 16, v199
	v_and_b32_e32 v245, 0xffff0000, v199
	v_pk_add_f32 v[34:35], v[34:35], v[242:243]
	v_pk_add_f32 v[36:37], v[36:37], v[244:245]
	v_fmac_f32_e32 v130, v38, v38
	v_fmac_f32_e32 v131, v39, v39
	v_fmac_f32_e32 v130, v40, v40
	v_fmac_f32_e32 v131, v41, v41
	v_fmac_f32_e32 v130, v34, v34
	v_fmac_f32_e32 v131, v35, v35
	v_fmac_f32_e32 v130, v36, v36
	v_fmac_f32_e32 v131, v37, v37
	v_cvt_pk_bf16_f32 v38, v38, v39
	v_cvt_pk_bf16_f32 v39, v40, v41
	v_cvt_pk_bf16_f32 v40, v34, v35
	v_cvt_pk_bf16_f32 v41, v36, v37
	ds_bpermute_b32 v38, v247, v38
	ds_bpermute_b32 v39, v247, v39
	ds_bpermute_b32 v40, v247, v40
	ds_bpermute_b32 v41, v247, v41
	v_add_f32_e32 v130, v130, v131
	v_mov_b32_e32 v131, v130
	s_nop 1
	v_permlane16_swap_b32_e32 v130, v131
	s_nop 1
	v_add_f32_e32 v130, v130, v131
	v_mov_b32_e32 v131, v130
	s_nop 1
	v_permlane32_swap_b32_e32 v130, v131
	s_nop 1
	v_add_f32_e32 v130, v130, v131
	s_and_saveexec_b64 s[58:59], s[40:41]
	global_store_dword v[250:251], v130, off
	s_or_b64 exec, exec, s[58:59]
	s_mov_b32 s56, 0x400
	v_lshl_add_u64 v[250:251], v[250:251], 0, s[56:57]
	s_waitcnt vmcnt(18)
; DI unsigned pk2(float lo, float hi) { f32x2 v = {lo, hi}; bf2_t r = __builtin_convertvector(v, bf2_t); return __builtin_bit_cast(unsigned, r); }
; DI float bflo(unsigned u) { return __uint_as_float(u << 16); }
; DI float bfhi(unsigned u) { return __uint_as_float(u & 0xffff0000u); }
;   DI void operator()(const f32x4 (&acc)[2][2][4][2], const Unit& u, int wr, int wc, int fr, int fq, const PG8_LAS float* sR) const {
;     ...
; #pragma unroll
;       for (int m = 0; m < 4; ++m) {
;         const int row = row0 + ai * HALF + m * 16;
;         const size_t ro = (size_t)row * 1024 + col0;
;         float ss = 0.f;
; #pragma unroll
;         for (int bj = 0; bj < 2; ++bj)
; #pragma unroll
;           for (int n = 0; n < 2; ++n) {
;             f32x4 v;
;             if (X0 != nullptr) v = *(const f32x4*)(X0 + ro + bj * HALF + n * 16);
;             else { const u32x2 q = sv[m][bj][n]; v[0] = bflo(q[0]); v[1] = bfhi(q[0]); v[2] = bflo(q[1]); v[3] = bfhi(q[1]); }
;             v += acc[ai][bj][m][n];
;             ss += v[0] * v[0] + v[1] * v[1] + v[2] * v[2] + v[3] * v[3];
;             if (!dry) { u32x2 q; q[0] = pk2(v[0], v[1]); q[1] = pk2(v[2], v[3]); *(u32x2*)(S + ro + bj * HALF + n * 16) = q; }
;           }
;         ss += __shfl_xor(ss, 16); ss += __shfl_xor(ss, 32);
;         if (!dry && fq == 0) ssq[(size_t)row * 16 + u.pn * 4 + wc] = ss;
;       }
;     }
;   }
	ds_bpermute_b32 v230, v246, v230
	ds_bpermute_b32 v231, v246, v231
	ds_bpermute_b32 v232, v246, v232
	ds_bpermute_b32 v233, v246, v233
	s_waitcnt lgkmcnt(12)
	global_store_dwordx4 v[132:133], v[46:49], off
	s_waitcnt lgkmcnt(8)
	v_lshlrev_b32_e32 v242, 16, v226
	v_and_b32_e32 v243, 0xffff0000, v226
	v_lshlrev_b32_e32 v244, 16, v227
	v_and_b32_e32 v245, 0xffff0000, v227
	v_pk_add_f32 v[30:31], v[30:31], v[242:243]
	v_pk_add_f32 v[32:33], v[32:33], v[244:245]
	v_lshlrev_b32_e32 v242, 16, v228
	v_and_b32_e32 v243, 0xffff0000, v228
	v_lshlrev_b32_e32 v244, 16, v229
	v_and_b32_e32 v245, 0xffff0000, v229
	v_pk_add_f32 v[26:27], v[26:27], v[242:243]
	v_pk_add_f32 v[28:29], v[28:29], v[244:245]
	v_mul_f32_e32 v130, v30, v30
	v_mul_f32_e32 v131, v31, v31
	v_fmac_f32_e32 v130, v32, v32
	v_fmac_f32_e32 v131, v33, v33
	v_fmac_f32_e32 v130, v26, v26
	v_fmac_f32_e32 v131, v27, v27
	v_fmac_f32_e32 v130, v28, v28
	v_fmac_f32_e32 v131, v29, v29
	v_cvt_pk_bf16_f32 v30, v30, v31
	v_cvt_pk_bf16_f32 v31, v32, v33
	v_cvt_pk_bf16_f32 v32, v26, v27
	v_cvt_pk_bf16_f32 v33, v28, v29
	ds_bpermute_b32 v30, v247, v30
	ds_bpermute_b32 v31, v247, v31
	ds_bpermute_b32 v32, v247, v32
	ds_bpermute_b32 v33, v247, v33
	s_waitcnt vmcnt(18)
	ds_bpermute_b32 v234, v246, v234
	ds_bpermute_b32 v235, v246, v235
	ds_bpermute_b32 v236, v246, v236
	ds_bpermute_b32 v237, v246, v237
	s_waitcnt lgkmcnt(12)
	global_store_dwordx4 v[132:133], v[38:41], off offset:256
	s_mov_b32 s56, 0x8000
	v_lshl_add_u64 v[132:133], v[132:133], 0, s[56:57]
	s_waitcnt lgkmcnt(8)
	v_lshlrev_b32_e32 v242, 16, v230
	v_and_b32_e32 v243, 0xffff0000, v230
	v_lshlrev_b32_e32 v244, 16, v231
	v_and_b32_e32 v245, 0xffff0000, v231
	v_pk_add_f32 v[22:23], v[22:23], v[242:243]
	v_pk_add_f32 v[24:25], v[24:25], v[244:245]
	v_lshlrev_b32_e32 v242, 16, v232
	v_and_b32_e32 v243, 0xffff0000, v232
	v_lshlrev_b32_e32 v244, 16, v233
	v_and_b32_e32 v245, 0xffff0000, v233
	v_pk_add_f32 v[18:19], v[18:19], v[242:243]
	v_pk_add_f32 v[20:21], v[20:21], v[244:245]
	v_fmac_f32_e32 v130, v22, v22
	v_fmac_f32_e32 v131, v23, v23
	v_fmac_f32_e32 v130, v24, v24
	v_fmac_f32_e32 v131, v25, v25
	v_fmac_f32_e32 v130, v18, v18
	v_fmac_f32_e32 v131, v19, v19
	v_fmac_f32_e32 v130, v20, v20
	v_fmac_f32_e32 v131, v21, v21
	v_cvt_pk_bf16_f32 v22, v22, v23
	v_cvt_pk_bf16_f32 v23, v24, v25
	v_cvt_pk_bf16_f32 v24, v18, v19
	v_cvt_pk_bf16_f32 v25, v20, v21
	ds_bpermute_b32 v22, v247, v22
	ds_bpermute_b32 v23, v247, v23
	ds_bpermute_b32 v24, v247, v24
	ds_bpermute_b32 v25, v247, v25
	v_add_f32_e32 v130, v130, v131
	v_mov_b32_e32 v131, v130
	s_nop 1
	v_permlane16_swap_b32_e32 v130, v131
	s_nop 1
	v_add_f32_e32 v130, v130, v131
	v_mov_b32_e32 v131, v130
	s_nop 1
	v_permlane32_swap_b32_e32 v130, v131
	s_nop 1
	v_add_f32_e32 v130, v130, v131
	s_and_saveexec_b64 s[58:59], s[40:41]
	global_store_dword v[250:251], v130, off
	s_or_b64 exec, exec, s[58:59]
	s_mov_b32 s56, 0x400
	v_lshl_add_u64 v[250:251], v[250:251], 0, s[56:57]
	s_waitcnt vmcnt(19)
	ds_bpermute_b32 v238, v246, v238
	ds_bpermute_b32 v239, v246, v239
	ds_bpermute_b32 v240, v246, v240
	ds_bpermute_b32 v241, v246, v241
	s_waitcnt lgkmcnt(12)
	global_store_dwordx4 v[132:133], v[30:33], off
	s_waitcnt lgkmcnt(8)
	v_lshlrev_b32_e32 v242, 16, v234
	v_and_b32_e32 v243, 0xffff0000, v234
	v_lshlrev_b32_e32 v244, 16, v235
	v_and_b32_e32 v245, 0xffff0000, v235
	v_pk_add_f32 v[14:15], v[14:15], v[242:243]
	v_pk_add_f32 v[16:17], v[16:17], v[244:245]
	v_lshlrev_b32_e32 v242, 16, v236
	v_and_b32_e32 v243, 0xffff0000, v236
	v_lshlrev_b32_e32 v244, 16, v237
	v_and_b32_e32 v245, 0xffff0000, v237
	v_pk_add_f32 v[10:11], v[10:11], v[242:243]
	v_pk_add_f32 v[12:13], v[12:13], v[244:245]
	v_mul_f32_e32 v130, v14, v14
	v_mul_f32_e32 v131, v15, v15
	v_fmac_f32_e32 v130, v16, v16
	v_fmac_f32_e32 v131, v17, v17
	v_fmac_f32_e32 v130, v10, v10
	v_fmac_f32_e32 v131, v11, v11
	v_fmac_f32_e32 v130, v12, v12
	v_fmac_f32_e32 v131, v13, v13
	v_cvt_pk_bf16_f32 v14, v14, v15
	v_cvt_pk_bf16_f32 v15, v16, v17
	v_cvt_pk_bf16_f32 v16, v10, v11
	v_cvt_pk_bf16_f32 v17, v12, v13
	ds_bpermute_b32 v14, v247, v14
	ds_bpermute_b32 v15, v247, v15
	ds_bpermute_b32 v16, v247, v16
	ds_bpermute_b32 v17, v247, v17
	s_waitcnt lgkmcnt(8)
	global_store_dwordx4 v[132:133], v[22:25], off offset:256
	s_mov_b32 s56, 0x8000
	v_lshl_add_u64 v[132:133], v[132:133], 0, s[56:57]
	s_waitcnt lgkmcnt(4)
	v_lshlrev_b32_e32 v242, 16, v238
	v_and_b32_e32 v243, 0xffff0000, v238
	v_lshlrev_b32_e32 v244, 16, v239
	v_and_b32_e32 v245, 0xffff0000, v239
	v_pk_add_f32 v[6:7], v[6:7], v[242:243]
	v_pk_add_f32 v[8:9], v[8:9], v[244:245]
	v_lshlrev_b32_e32 v242, 16, v240
	v_and_b32_e32 v243, 0xffff0000, v240
	v_lshlrev_b32_e32 v244, 16, v241
	v_and_b32_e32 v245, 0xffff0000, v241
	v_pk_add_f32 v[2:3], v[2:3], v[242:243]
	v_pk_add_f32 v[4:5], v[4:5], v[244:245]
	v_fmac_f32_e32 v130, v6, v6
	v_fmac_f32_e32 v131, v7, v7
	v_fmac_f32_e32 v130, v8, v8
	v_fmac_f32_e32 v131, v9, v9
	v_fmac_f32_e32 v130, v2, v2
	v_fmac_f32_e32 v131, v3, v3
	v_fmac_f32_e32 v130, v4, v4
	v_fmac_f32_e32 v131, v5, v5
	v_cvt_pk_bf16_f32 v6, v6, v7
	v_cvt_pk_bf16_f32 v7, v8, v9
	v_cvt_pk_bf16_f32 v8, v2, v3
	v_cvt_pk_bf16_f32 v9, v4, v5
	ds_bpermute_b32 v6, v247, v6
	ds_bpermute_b32 v7, v247, v7
	ds_bpermute_b32 v8, v247, v8
	ds_bpermute_b32 v9, v247, v9
	v_add_f32_e32 v130, v130, v131
	v_mov_b32_e32 v131, v130
	s_nop 1
	v_permlane16_swap_b32_e32 v130, v131
	s_nop 1
	v_add_f32_e32 v130, v130, v131
	v_mov_b32_e32 v131, v130
	s_nop 1
	v_permlane32_swap_b32_e32 v130, v131
	s_nop 1
	v_add_f32_e32 v130, v130, v131
	s_and_saveexec_b64 s[58:59], s[40:41]
	global_store_dword v[250:251], v130, off
	s_or_b64 exec, exec, s[58:59]
	s_waitcnt lgkmcnt(4)
	global_store_dwordx4 v[132:133], v[14:17], off
	s_waitcnt lgkmcnt(0)
	global_store_dwordx4 v[132:133], v[6:9], off offset:256
	v_readlane_b32 s4, v253, 56
	v_readlane_b32 s5, v253, 57
	v_readlane_b32 s6, v253, 58
	v_readlane_b32 s7, v253, 59
	v_readlane_b32 s8, v253, 60
	v_readlane_b32 s9, v253, 61
	v_readlane_b32 s10, v253, 62
	v_readlane_b32 s11, v253, 63
	v_readlane_b32 s12, v254, 0
	v_readlane_b32 s13, v254, 1
	v_readlane_b32 s14, v254, 2
	v_readlane_b32 s15, v254, 3
	v_readlane_b32 s16, v254, 4
	v_readlane_b32 s17, v254, 5
	v_readlane_b32 s18, v254, 6
	v_readlane_b32 s19, v254, 7
	s_mov_b64 s[44:45], exec
	s_branch .LBB0_823

; #define PG8_STAGE(bufoff, gbase, voff) do { _Pragma("unroll") for (int _i = 0; _i < 2; ++_i) \
;     __builtin_amdgcn_global_load_lds((const unsigned*)((const char*)(gbase) + (voff)[_i]), (PG8_LAS unsigned*)(lds + (bufoff) + ldsw + _i * 8192), 16, 0, 0); } while (0)
; #define PG8_LDA(dst, b, h) do { _Pragma("unroll") for (int m = 0; m < 4; ++m) _Pragma("unroll") for (int k = 0; k < 2; ++k) dst[m][k] = *(const PG8_LAS bf16x8*)(lds + PG8_SA(b, h) + aoff + m * 2048 + k * 1024); } while (0)
; #define PG8_LDB(dst, b, h) do { _Pragma("unroll") for (int n = 0; n < 2; ++n) _Pragma("unroll") for (int k = 0; k < 2; ++k) dst[n][k] = *(const PG8_LAS bf16x8*)(lds + PG8_SB(b, h) + boff + n * 2048 + k * 1024); } while (0)
; #define PG8_MMA(ai, bj, At, Bt) do { __builtin_amdgcn_s_setprio(1); _Pragma("unroll") for (int m = 0; m < 4; ++m) _Pragma("unroll") for (int n = 0; n < 2; ++n) _Pragma("unroll") for (int k = 0; k < 2; ++k) \
;     acc[ai][bj][m][n] = __builtin_amdgcn_mfma_f32_16x16x32_bf16(Bt[n][k], At[m][k], acc[ai][bj][m][n], 0, 0, 0); __builtin_amdgcn_s_setprio(0); } while (0)
; #define PG8_WAIT_L(n) asm volatile("s_waitcnt lgkmcnt(" #n ")" ::: "memory")
; #define PG8_BAR __builtin_amdgcn_s_barrier()
; #define PG8_SCHED __builtin_amdgcn_sched_barrier(0)
; template <class Epi>
; DI void gemm_phase(PG8_LAS unsigned char* lds, const Gemm g, const StaticOrder& S, const Epi& E) {
;     ...
;     const bool has_next = S.next(ui + 1, nxt);
;     const char* nA = has_next ? (const char*)g.A + (size_t)nxt.pm * tstepA : cA; const char* nB = has_next ? (const char*)g.Bt + (size_t)nxt.pn * tstepB : cB;
;     for (int t = 0; t < nt; t += 2) {
;       const bool last = (t == nt - 2);
;       const char* a1 = cA + (size_t)(t + 1) * kstep;
;       const char* a2 = last ? nA : cA + (size_t)(t + 2) * kstep; const char* b2 = last ? nB : cB + (size_t)(t + 2) * kstep;
;       const char* a3 = a2 + kstep; const char* b3 = b2 + kstep;
;       PG8_LDB(B0, 0, 0); PG8_SCHED; PG8_LDA(At, 0, 0); PG8_STAGE(PG8_SA(1, 1), a1 + hstepA, voffA);
;       PG8_WAIT_L(8); PG8_BAR; PG8_WAIT_L(0); PG8_MMA(0, 0, At, B0); PG8_BAR; PG8_SCHED;
;       PG8_LDB(B1, 0, 1); PG8_STAGE(PG8_SB(0, 0), b2, voffB);
;       PG8_BAR; PG8_WAIT_L(0); PG8_MMA(0, 1, At, B1); PG8_BAR;
;       PG8_LDA(At, 0, 1); PG8_STAGE(PG8_SA(0, 0), a2, voffA);
;       PG8_BAR; PG8_WAIT_L(0); PG8_MMA(1, 0, At, B0); PG8_BAR; PG8_SCHED;
.LBB0_1174:
	s_ashr_i32 s47, s46, 31
	v_cmp_lt_i64_e32 vcc, s[48:49], v[136:137]
	s_lshl_b64 s[48:49], s[46:47], 19
	s_add_u32 s48, s22, s48
	s_addc_u32 s49, s23, s49
	s_and_b64 s[50:51], vcc, exec
	s_cselect_b32 s47, s49, s31
	s_cselect_b32 s66, s48, s30
	s_ashr_i32 s45, s44, 31
	v_readlane_b32 s4, v253, 16
	s_lshl_b64 s[50:51], s[44:45], 19
	v_readlane_b32 s14, v253, 26
	v_readlane_b32 s15, v253, 27
	s_add_u32 s50, s14, s50
	s_addc_u32 s51, s15, s51
	s_and_b64 s[54:55], vcc, exec
	s_cselect_b32 s45, s51, s53
	s_cselect_b32 s67, s50, s52
	s_add_u32 s30, s30, 0x40080
	s_addc_u32 s31, s31, 0
	s_add_u32 s68, s52, 0x100
	v_mov_b32_e32 v18, 0
	s_addc_u32 s69, s53, 0
	s_mov_b32 s70, -2
	v_readlane_b32 s5, v253, 17
	v_readlane_b32 s6, v253, 18
	v_readlane_b32 s7, v253, 19
	v_readlane_b32 s8, v253, 20
	v_readlane_b32 s9, v253, 21
	v_readlane_b32 s10, v253, 22
	v_readlane_b32 s11, v253, 23
	v_readlane_b32 s12, v253, 24
	v_readlane_b32 s13, v253, 25
	v_readlane_b32 s16, v253, 28
	v_readlane_b32 s17, v253, 29
	v_readlane_b32 s18, v253, 30
	v_readlane_b32 s19, v253, 31
	s_add_u32 s52, s30, 0xfffc0080
	s_addc_u32 s53, s31, -1
	s_add_i32 s71, 0, 0x10000
	v_add_u32_e32 v156, s71, v160
	ds_read_b128 v[152:155], v156
	ds_read_b128 v[164:167], v156 offset:1024
	ds_read_b128 v[168:171], v156 offset:2048
	ds_read_b128 v[172:175], v156 offset:3072
	s_cmp_eq_u32 s70, 12
	s_cselect_b32 s55, s47, s53
	s_cselect_b32 s54, s66, s52
	s_cselect_b32 s53, s45, s69
	s_cselect_b32 s52, s67, s68
	v_lshl_add_u64 v[156:157], s[30:31], 0, v[148:149]
	s_add_i32 m0, s58, 0xc000
	ds_read_b128 v[176:179], v162
	ds_read_b128 v[180:183], v162 offset:1024
	ds_read_b128 v[184:187], v162 offset:2048
	ds_read_b128 v[188:191], v162 offset:3072
	ds_read_b128 v[192:195], v162 offset:4096
	ds_read_b128 v[196:199], v162 offset:5120
	ds_read_b128 v[222:225], v162 offset:6144
	ds_read_b128 v[226:229], v162 offset:7168
	global_load_lds_dwordx4 v[156:157], off
	v_lshl_add_u64 v[156:157], s[30:31], 0, v[150:151]
	s_add_i32 m0, s58, 0xe000
	s_nop 0
	global_load_lds_dwordx4 v[156:157], off
	s_waitcnt lgkmcnt(8)
	s_barrier
	s_waitcnt lgkmcnt(0)
	s_waitcnt lgkmcnt(0)
	v_mfma_f32_16x16x32_bf16 v[70:73], v[152:155], v[176:179], 0
	v_mfma_f32_16x16x32_bf16 v[66:69], v[168:171], v[176:179], 0
	v_mfma_f32_16x16x32_bf16 v[62:65], v[152:155], v[184:187], 0
	v_mfma_f32_16x16x32_bf16 v[58:61], v[168:171], v[184:187], 0
	v_mfma_f32_16x16x32_bf16 v[54:57], v[152:155], v[192:195], 0
	v_mfma_f32_16x16x32_bf16 v[50:53], v[168:171], v[192:195], 0
	v_mfma_f32_16x16x32_bf16 v[46:49], v[152:155], v[222:225], 0
	v_mfma_f32_16x16x32_bf16 v[42:45], v[168:171], v[222:225], 0
	v_mfma_f32_16x16x32_bf16 v[70:73], v[164:167], v[180:183], v[70:73]
	v_mfma_f32_16x16x32_bf16 v[66:69], v[172:175], v[180:183], v[66:69]
	v_mfma_f32_16x16x32_bf16 v[62:65], v[164:167], v[188:191], v[62:65]
	v_mfma_f32_16x16x32_bf16 v[58:61], v[172:175], v[188:191], v[58:61]
	v_mfma_f32_16x16x32_bf16 v[54:57], v[164:167], v[196:199], v[54:57]
	v_mfma_f32_16x16x32_bf16 v[50:53], v[172:175], v[196:199], v[50:53]
	v_mfma_f32_16x16x32_bf16 v[46:49], v[164:167], v[226:229], v[46:49]
	v_mfma_f32_16x16x32_bf16 v[42:45], v[172:175], v[226:229], v[42:45]
	s_barrier
	s_add_i32 s74, 0, 0x14000
	v_add_u32_e32 v156, s74, v160
	s_add_i32 s71, s71, s57
	ds_read_b128 v[230:233], v156
	ds_read_b128 v[234:237], v156 offset:1024
	ds_read_b128 v[238:241], v156 offset:2048
	ds_read_b128 v[242:245], v156 offset:3072
	v_lshl_add_u64 v[156:157], s[52:53], 0, v[0:1]
	s_mov_b32 m0, s71
	v_lshl_add_u64 v[246:247], s[52:53], 0, v[130:131]
	global_load_lds_dwordx4 v[156:157], off
	s_add_i32 m0, s71, 0x2000
	s_nop 0
	global_load_lds_dwordx4 v[246:247], off
	s_barrier
	s_waitcnt lgkmcnt(0)
	s_waitcnt lgkmcnt(0)
	v_mfma_f32_16x16x32_bf16 v[126:129], v[230:233], v[176:179], 0
	v_mfma_f32_16x16x32_bf16 v[122:125], v[238:241], v[176:179], 0
	v_mfma_f32_16x16x32_bf16 v[118:121], v[230:233], v[184:187], 0
	v_mfma_f32_16x16x32_bf16 v[114:117], v[238:241], v[184:187], 0
	v_mfma_f32_16x16x32_bf16 v[110:113], v[230:233], v[192:195], 0
	v_mfma_f32_16x16x32_bf16 v[106:109], v[238:241], v[192:195], 0
	v_mfma_f32_16x16x32_bf16 v[102:105], v[230:233], v[222:225], 0
	v_mfma_f32_16x16x32_bf16 v[98:101], v[238:241], v[222:225], 0
	v_mfma_f32_16x16x32_bf16 v[126:129], v[234:237], v[180:183], v[126:129]
	v_mfma_f32_16x16x32_bf16 v[122:125], v[242:245], v[180:183], v[122:125]
	v_mfma_f32_16x16x32_bf16 v[118:121], v[234:237], v[188:191], v[118:121]
	v_mfma_f32_16x16x32_bf16 v[114:117], v[242:245], v[188:191], v[114:117]
	v_mfma_f32_16x16x32_bf16 v[110:113], v[234:237], v[196:199], v[110:113]
	v_mfma_f32_16x16x32_bf16 v[106:109], v[242:245], v[196:199], v[106:109]
	v_mfma_f32_16x16x32_bf16 v[102:105], v[234:237], v[226:229], v[102:105]
	v_mfma_f32_16x16x32_bf16 v[98:101], v[242:245], v[226:229], v[98:101]
	s_mov_b32 m0, s58
	v_lshl_add_u64 v[248:249], s[54:55], 0, v[142:143]
	s_barrier
	ds_read_b128 v[176:179], v162 offset:16384
	ds_read_b128 v[180:183], v162 offset:17408
	ds_read_b128 v[184:187], v162 offset:18432
	ds_read_b128 v[188:191], v162 offset:19456
	ds_read_b128 v[192:195], v162 offset:20480
	ds_read_b128 v[196:199], v162 offset:21504
	ds_read_b128 v[222:225], v162 offset:22528
	ds_read_b128 v[226:229], v162 offset:23552
	global_load_lds_dwordx4 v[248:249], off
	v_lshl_add_u64 v[250:251], s[54:55], 0, v[132:133]
	s_mov_b32 m0, s59
	s_nop 0
	global_load_lds_dwordx4 v[250:251], off
	s_barrier
; #define PG8_STAGE(bufoff, gbase, voff) do { _Pragma("unroll") for (int _i = 0; _i < 2; ++_i) \
;     __builtin_amdgcn_global_load_lds((const unsigned*)((const char*)(gbase) + (voff)[_i]), (PG8_LAS unsigned*)(lds + (bufoff) + ldsw + _i * 8192), 16, 0, 0); } while (0)
; #define PG8_LDA(dst, b, h) do { _Pragma("unroll") for (int m = 0; m < 4; ++m) _Pragma("unroll") for (int k = 0; k < 2; ++k) dst[m][k] = *(const PG8_LAS bf16x8*)(lds + PG8_SA(b, h) + aoff + m * 2048 + k * 1024); } while (0)
; #define PG8_LDB(dst, b, h) do { _Pragma("unroll") for (int n = 0; n < 2; ++n) _Pragma("unroll") for (int k = 0; k < 2; ++k) dst[n][k] = *(const PG8_LAS bf16x8*)(lds + PG8_SB(b, h) + boff + n * 2048 + k * 1024); } while (0)
; #define PG8_MMA(ai, bj, At, Bt) do { __builtin_amdgcn_s_setprio(1); _Pragma("unroll") for (int m = 0; m < 4; ++m) _Pragma("unroll") for (int n = 0; n < 2; ++n) _Pragma("unroll") for (int k = 0; k < 2; ++k) \
;     acc[ai][bj][m][n] = __builtin_amdgcn_mfma_f32_16x16x32_bf16(Bt[n][k], At[m][k], acc[ai][bj][m][n], 0, 0, 0); __builtin_amdgcn_s_setprio(0); } while (0)
; #define PG8_WAIT_V(n) asm volatile("s_waitcnt vmcnt(" #n ")" ::: "memory")
; #define PG8_WAIT_L(n) asm volatile("s_waitcnt lgkmcnt(" #n ")" ::: "memory")
; #define PG8_BAR __builtin_amdgcn_s_barrier()
; #define PG8_SCHED __builtin_amdgcn_sched_barrier(0)
; template <class Epi>
; DI void gemm_phase(PG8_LAS unsigned char* lds, const Gemm g, const StaticOrder& S, const Epi& E) {
;     ...
;       PG8_BAR; PG8_WAIT_L(0); PG8_MMA(1, 0, At, B0); PG8_BAR; PG8_SCHED;
;       PG8_STAGE(PG8_SB(0, 1), b2 + hstepB, voffB);
;       PG8_WAIT_V(6); PG8_BAR; PG8_MMA(1, 1, At, B1); PG8_BAR;
;       PG8_LDB(B0, 1, 0); PG8_SCHED; PG8_LDA(At, 1, 0); PG8_STAGE(PG8_SA(0, 1), a2 + hstepA, voffA);
;       PG8_WAIT_L(8); PG8_BAR; PG8_WAIT_L(0); PG8_MMA(0, 0, At, B0); PG8_BAR; PG8_SCHED;
;       PG8_LDB(B1, 1, 1); PG8_STAGE(PG8_SB(1, 0), b3, voffB);
;       PG8_BAR; PG8_WAIT_L(0); PG8_MMA(0, 1, At, B1); PG8_BAR;
;       PG8_LDA(At, 1, 1); PG8_STAGE(PG8_SA(1, 0), a3, voffA);
	s_waitcnt lgkmcnt(0)
	s_waitcnt lgkmcnt(0)
	v_mfma_f32_16x16x32_bf16 v[38:41], v[152:155], v[176:179], 0
	v_mfma_f32_16x16x32_bf16 v[34:37], v[168:171], v[176:179], 0
	v_mfma_f32_16x16x32_bf16 v[30:33], v[152:155], v[184:187], 0
	v_mfma_f32_16x16x32_bf16 v[26:29], v[168:171], v[184:187], 0
	v_mfma_f32_16x16x32_bf16 v[14:17], v[152:155], v[192:195], 0
	v_mfma_f32_16x16x32_bf16 v[10:13], v[168:171], v[192:195], 0
	v_mfma_f32_16x16x32_bf16 v[6:9], v[152:155], v[222:225], 0
	v_mfma_f32_16x16x32_bf16 v[2:5], v[168:171], v[222:225], 0
	v_mfma_f32_16x16x32_bf16 v[38:41], v[164:167], v[180:183], v[38:41]
	v_mfma_f32_16x16x32_bf16 v[34:37], v[172:175], v[180:183], v[34:37]
	v_mfma_f32_16x16x32_bf16 v[30:33], v[164:167], v[188:191], v[30:33]
	v_mfma_f32_16x16x32_bf16 v[26:29], v[172:175], v[188:191], v[26:29]
	v_mfma_f32_16x16x32_bf16 v[14:17], v[164:167], v[196:199], v[14:17]
	v_mfma_f32_16x16x32_bf16 v[10:13], v[172:175], v[196:199], v[10:13]
	v_mfma_f32_16x16x32_bf16 v[6:9], v[164:167], v[226:229], v[6:9]
	v_mfma_f32_16x16x32_bf16 v[2:5], v[172:175], v[226:229], v[2:5]
	s_barrier
	s_add_u32 s72, s52, 0x40000
	s_addc_u32 s73, s53, 0
	s_add_i32 s71, s74, s57
	v_lshl_add_u64 v[152:153], s[72:73], 0, v[0:1]
	s_mov_b32 m0, s71
	s_nop 0
	global_load_lds_dwordx4 v[152:153], off
	v_lshl_add_u64 v[152:153], s[72:73], 0, v[130:131]
	s_add_i32 m0, s71, 0x2000
	s_nop 0
	global_load_lds_dwordx4 v[152:153], off
	s_waitcnt vmcnt(6)
	s_barrier
	v_mfma_f32_16x16x32_bf16 v[94:97], v[230:233], v[176:179], 0
	v_mfma_f32_16x16x32_bf16 v[90:93], v[238:241], v[176:179], 0
	v_mfma_f32_16x16x32_bf16 v[86:89], v[230:233], v[184:187], 0
	v_mfma_f32_16x16x32_bf16 v[82:85], v[238:241], v[184:187], 0
	v_mfma_f32_16x16x32_bf16 v[78:81], v[230:233], v[192:195], 0
	v_mfma_f32_16x16x32_bf16 v[74:77], v[238:241], v[192:195], 0
	v_mfma_f32_16x16x32_bf16 v[22:25], v[230:233], v[222:225], 0
	v_mfma_f32_16x16x32_bf16 v[18:21], v[238:241], v[222:225], 0
	v_mfma_f32_16x16x32_bf16 v[94:97], v[234:237], v[180:183], v[94:97]
	v_mfma_f32_16x16x32_bf16 v[90:93], v[242:245], v[180:183], v[90:93]
	v_mfma_f32_16x16x32_bf16 v[86:89], v[234:237], v[188:191], v[86:89]
	v_mfma_f32_16x16x32_bf16 v[82:85], v[242:245], v[188:191], v[82:85]
	v_mfma_f32_16x16x32_bf16 v[78:81], v[234:237], v[196:199], v[78:81]
	v_mfma_f32_16x16x32_bf16 v[74:77], v[242:245], v[196:199], v[74:77]
	v_mfma_f32_16x16x32_bf16 v[22:25], v[234:237], v[226:229], v[22:25]
	v_mfma_f32_16x16x32_bf16 v[18:21], v[242:245], v[226:229], v[18:21]
	s_add_i32 s71, 0, 0x18000
	v_add_u32_e32 v163, s71, v160
	s_barrier
	ds_read_b128 v[152:155], v163
	ds_read_b128 v[164:167], v163 offset:1024
	ds_read_b128 v[168:171], v163 offset:2048
	ds_read_b128 v[172:175], v163 offset:3072
	s_add_u32 s54, s54, 0x40000
	s_addc_u32 s55, s55, 0
	s_mov_b32 m0, s60
	v_lshl_add_u64 v[230:231], s[54:55], 0, v[142:143]
	ds_read_b128 v[176:179], v162 offset:32768
	ds_read_b128 v[180:183], v162 offset:33792
	ds_read_b128 v[184:187], v162 offset:34816
	ds_read_b128 v[188:191], v162 offset:35840
	ds_read_b128 v[192:195], v162 offset:36864
	ds_read_b128 v[196:199], v162 offset:37888
	ds_read_b128 v[222:225], v162 offset:38912
	ds_read_b128 v[226:229], v162 offset:39936
	global_load_lds_dwordx4 v[230:231], off
	v_lshl_add_u64 v[230:231], s[54:55], 0, v[132:133]
	s_mov_b32 m0, s61
	s_nop 0
	global_load_lds_dwordx4 v[230:231], off
	s_waitcnt lgkmcnt(8)
	s_barrier
	s_waitcnt lgkmcnt(0)
	s_waitcnt lgkmcnt(0)
	v_mfma_f32_16x16x32_bf16 v[70:73], v[152:155], v[176:179], v[70:73]
	v_mfma_f32_16x16x32_bf16 v[66:69], v[168:171], v[176:179], v[66:69]
	v_mfma_f32_16x16x32_bf16 v[62:65], v[152:155], v[184:187], v[62:65]
	v_mfma_f32_16x16x32_bf16 v[58:61], v[168:171], v[184:187], v[58:61]
	v_mfma_f32_16x16x32_bf16 v[54:57], v[152:155], v[192:195], v[54:57]
	v_mfma_f32_16x16x32_bf16 v[50:53], v[168:171], v[192:195], v[50:53]
	v_mfma_f32_16x16x32_bf16 v[46:49], v[152:155], v[222:225], v[46:49]
	v_mfma_f32_16x16x32_bf16 v[42:45], v[168:171], v[222:225], v[42:45]
	v_mfma_f32_16x16x32_bf16 v[70:73], v[164:167], v[180:183], v[70:73]
	v_mfma_f32_16x16x32_bf16 v[66:69], v[172:175], v[180:183], v[66:69]
	v_mfma_f32_16x16x32_bf16 v[62:65], v[164:167], v[188:191], v[62:65]
	v_mfma_f32_16x16x32_bf16 v[58:61], v[172:175], v[188:191], v[58:61]
	v_mfma_f32_16x16x32_bf16 v[54:57], v[164:167], v[196:199], v[54:57]
	v_mfma_f32_16x16x32_bf16 v[50:53], v[172:175], v[196:199], v[50:53]
	v_mfma_f32_16x16x32_bf16 v[46:49], v[164:167], v[226:229], v[46:49]
	v_mfma_f32_16x16x32_bf16 v[42:45], v[172:175], v[226:229], v[42:45]
	s_barrier
	s_add_i32 s54, 0, 0x1c000
	s_add_i32 s55, s71, s57
	v_add_u32_e32 v163, s54, v160
	v_lshl_add_u64 v[156:157], v[156:157], 0, s[86:87]
	s_mov_b32 m0, s55
	ds_read_b128 v[230:233], v163
	ds_read_b128 v[234:237], v163 offset:1024
	ds_read_b128 v[238:241], v163 offset:2048
	ds_read_b128 v[242:245], v163 offset:3072
	global_load_lds_dwordx4 v[156:157], off
	v_lshl_add_u64 v[156:157], v[246:247], 0, s[86:87]
	s_add_i32 m0, s55, 0x2000
	s_nop 0
	global_load_lds_dwordx4 v[156:157], off
	s_barrier
; #define PG8_STAGE(bufoff, gbase, voff) do { _Pragma("unroll") for (int _i = 0; _i < 2; ++_i) \
;     __builtin_amdgcn_global_load_lds((const unsigned*)((const char*)(gbase) + (voff)[_i]), (PG8_LAS unsigned*)(lds + (bufoff) + ldsw + _i * 8192), 16, 0, 0); } while (0)
; #define PG8_LDA(dst, b, h) do { _Pragma("unroll") for (int m = 0; m < 4; ++m) _Pragma("unroll") for (int k = 0; k < 2; ++k) dst[m][k] = *(const PG8_LAS bf16x8*)(lds + PG8_SA(b, h) + aoff + m * 2048 + k * 1024); } while (0)
; #define PG8_MMA(ai, bj, At, Bt) do { __builtin_amdgcn_s_setprio(1); _Pragma("unroll") for (int m = 0; m < 4; ++m) _Pragma("unroll") for (int n = 0; n < 2; ++n) _Pragma("unroll") for (int k = 0; k < 2; ++k) \
;     acc[ai][bj][m][n] = __builtin_amdgcn_mfma_f32_16x16x32_bf16(Bt[n][k], At[m][k], acc[ai][bj][m][n], 0, 0, 0); __builtin_amdgcn_s_setprio(0); } while (0)
; #define PG8_WAIT_V(n) asm volatile("s_waitcnt vmcnt(" #n ")" ::: "memory")
; #define PG8_WAIT_L(n) asm volatile("s_waitcnt lgkmcnt(" #n ")" ::: "memory")
; #define PG8_BAR __builtin_amdgcn_s_barrier()
; #define PG8_SCHED __builtin_amdgcn_sched_barrier(0)
; template <class Epi>
; DI void gemm_phase(PG8_LAS unsigned char* lds, const Gemm g, const StaticOrder& S, const Epi& E) {
;     ...
;       PG8_BAR; PG8_WAIT_L(0); PG8_MMA(0, 1, At, B1); PG8_BAR;
;       PG8_LDA(At, 1, 1); PG8_STAGE(PG8_SA(1, 0), a3, voffA);
;       PG8_BAR; PG8_WAIT_L(0); PG8_MMA(1, 0, At, B0); PG8_BAR; PG8_SCHED;
;       PG8_STAGE(PG8_SB(1, 1), b3 + hstepB, voffB);
;       PG8_WAIT_V(6); PG8_BAR; PG8_MMA(1, 1, At, B1); PG8_BAR;
;     }
	s_waitcnt lgkmcnt(0)
	s_waitcnt lgkmcnt(0)
	v_mfma_f32_16x16x32_bf16 v[126:129], v[230:233], v[176:179], v[126:129]
	v_mfma_f32_16x16x32_bf16 v[122:125], v[238:241], v[176:179], v[122:125]
	v_mfma_f32_16x16x32_bf16 v[118:121], v[230:233], v[184:187], v[118:121]
	v_mfma_f32_16x16x32_bf16 v[114:117], v[238:241], v[184:187], v[114:117]
	v_mfma_f32_16x16x32_bf16 v[110:113], v[230:233], v[192:195], v[110:113]
	v_mfma_f32_16x16x32_bf16 v[106:109], v[238:241], v[192:195], v[106:109]
	v_mfma_f32_16x16x32_bf16 v[102:105], v[230:233], v[222:225], v[102:105]
	v_mfma_f32_16x16x32_bf16 v[98:101], v[238:241], v[222:225], v[98:101]
	v_mfma_f32_16x16x32_bf16 v[126:129], v[234:237], v[180:183], v[126:129]
	v_mfma_f32_16x16x32_bf16 v[122:125], v[242:245], v[180:183], v[122:125]
	v_mfma_f32_16x16x32_bf16 v[118:121], v[234:237], v[188:191], v[118:121]
	v_mfma_f32_16x16x32_bf16 v[114:117], v[242:245], v[188:191], v[114:117]
	v_mfma_f32_16x16x32_bf16 v[110:113], v[234:237], v[196:199], v[110:113]
	v_mfma_f32_16x16x32_bf16 v[106:109], v[242:245], v[196:199], v[106:109]
	v_mfma_f32_16x16x32_bf16 v[102:105], v[234:237], v[226:229], v[102:105]
	v_mfma_f32_16x16x32_bf16 v[98:101], v[242:245], v[226:229], v[98:101]
	s_mov_b32 m0, s34
	v_lshl_add_u64 v[156:157], v[248:249], 0, s[86:87]
	s_barrier
	ds_read_b128 v[176:179], v162 offset:49152
	ds_read_b128 v[180:183], v162 offset:50176
	ds_read_b128 v[184:187], v162 offset:51200
	ds_read_b128 v[188:191], v162 offset:52224
	ds_read_b128 v[192:195], v162 offset:53248
	ds_read_b128 v[196:199], v162 offset:54272
	ds_read_b128 v[222:225], v162 offset:55296
	ds_read_b128 v[226:229], v162 offset:56320
	global_load_lds_dwordx4 v[156:157], off
	v_lshl_add_u64 v[156:157], v[250:251], 0, s[86:87]
	s_mov_b32 m0, s62
	s_nop 0
	global_load_lds_dwordx4 v[156:157], off
	s_barrier
	s_waitcnt lgkmcnt(0)
	s_waitcnt lgkmcnt(0)
	v_mfma_f32_16x16x32_bf16 v[38:41], v[152:155], v[176:179], v[38:41]
	v_mfma_f32_16x16x32_bf16 v[34:37], v[168:171], v[176:179], v[34:37]
	v_mfma_f32_16x16x32_bf16 v[30:33], v[152:155], v[184:187], v[30:33]
	v_mfma_f32_16x16x32_bf16 v[26:29], v[168:171], v[184:187], v[26:29]
	v_mfma_f32_16x16x32_bf16 v[14:17], v[152:155], v[192:195], v[14:17]
	v_mfma_f32_16x16x32_bf16 v[10:13], v[168:171], v[192:195], v[10:13]
	v_mfma_f32_16x16x32_bf16 v[6:9], v[152:155], v[222:225], v[6:9]
	v_mfma_f32_16x16x32_bf16 v[2:5], v[168:171], v[222:225], v[2:5]
	v_mfma_f32_16x16x32_bf16 v[38:41], v[164:167], v[180:183], v[38:41]
	v_mfma_f32_16x16x32_bf16 v[34:37], v[172:175], v[180:183], v[34:37]
	v_mfma_f32_16x16x32_bf16 v[30:33], v[164:167], v[188:191], v[30:33]
	v_mfma_f32_16x16x32_bf16 v[26:29], v[172:175], v[188:191], v[26:29]
	v_mfma_f32_16x16x32_bf16 v[14:17], v[164:167], v[196:199], v[14:17]
	v_mfma_f32_16x16x32_bf16 v[10:13], v[172:175], v[196:199], v[10:13]
	v_mfma_f32_16x16x32_bf16 v[6:9], v[164:167], v[226:229], v[6:9]
	v_mfma_f32_16x16x32_bf16 v[2:5], v[172:175], v[226:229], v[2:5]
	s_barrier
	s_add_u32 s52, s52, 0x40080
	s_addc_u32 s53, s53, 0
	s_add_i32 s54, s54, s57
	v_lshl_add_u64 v[152:153], s[52:53], 0, v[0:1]
	s_mov_b32 m0, s54
	s_nop 0
	global_load_lds_dwordx4 v[152:153], off
	v_lshl_add_u64 v[152:153], s[52:53], 0, v[130:131]
	s_add_i32 m0, s54, 0x2000
	s_nop 0
	global_load_lds_dwordx4 v[152:153], off
	s_waitcnt vmcnt(6)
	s_barrier
	v_mfma_f32_16x16x32_bf16 v[94:97], v[230:233], v[176:179], v[94:97]
	v_mfma_f32_16x16x32_bf16 v[90:93], v[238:241], v[176:179], v[90:93]
	v_mfma_f32_16x16x32_bf16 v[86:89], v[230:233], v[184:187], v[86:89]
	v_mfma_f32_16x16x32_bf16 v[82:85], v[238:241], v[184:187], v[82:85]
	v_mfma_f32_16x16x32_bf16 v[78:81], v[230:233], v[192:195], v[78:81]
	v_mfma_f32_16x16x32_bf16 v[74:77], v[238:241], v[192:195], v[74:77]
	v_mfma_f32_16x16x32_bf16 v[22:25], v[230:233], v[222:225], v[22:25]
	v_mfma_f32_16x16x32_bf16 v[18:21], v[238:241], v[222:225], v[18:21]
	v_mfma_f32_16x16x32_bf16 v[94:97], v[234:237], v[180:183], v[94:97]
	v_mfma_f32_16x16x32_bf16 v[90:93], v[242:245], v[180:183], v[90:93]
	v_mfma_f32_16x16x32_bf16 v[86:89], v[234:237], v[188:191], v[86:89]
	v_mfma_f32_16x16x32_bf16 v[82:85], v[242:245], v[188:191], v[82:85]
	v_mfma_f32_16x16x32_bf16 v[78:81], v[234:237], v[196:199], v[78:81]
	v_mfma_f32_16x16x32_bf16 v[74:77], v[242:245], v[196:199], v[74:77]
	v_mfma_f32_16x16x32_bf16 v[22:25], v[234:237], v[226:229], v[22:25]
	v_mfma_f32_16x16x32_bf16 v[18:21], v[242:245], v[226:229], v[18:21]
	s_add_i32 s70, s70, 2
	s_add_u32 s30, s30, 0x100
	s_addc_u32 s31, s31, 0
	s_add_u32 s68, s68, 0x100
	s_addc_u32 s69, s69, 0
	s_cmp_gt_u32 s70, 13
	s_barrier
	s_cbranch_scc1 .Lpeel_exit_2

; DI unsigned pk2(float lo, float hi) { f32x2 v = {lo, hi}; bf2_t r = __builtin_convertvector(v, bf2_t); return __builtin_bit_cast(unsigned, r); }
;   DI void operator()(const f32x4 (&acc)[2][2][4][2], const Unit& u, int wr, int wc, int fr, int fq, const PG8_LAS float* sR) const {
;     const int row0 = u.pm * BM + wr * 64 + fr;
;     if (dt != nullptr && u.pn == 20) {
;     ...
;     const int col0 = u.pn * BM + wc * 32 + 8 * fq;
; #pragma unroll
;     for (int ai = 0; ai < 2; ++ai)
; #pragma unroll
;       for (int m = 0; m < 4; ++m) {
;         bf16_t* rowp = C + (size_t)(row0 + ai * HALF + m * 16) * ldc + col0;
;         const float rs = sR[ai * 128 + m * 16 + fr];
; #pragma unroll
;         for (int bj = 0; bj < 2; ++bj) {
;           const f32x4 v0 = acc[ai][bj][m][0] * rs, v1 = acc[ai][bj][m][1] * rs;
;           u32x4 w; w[0] = pk2(v0[0], v0[1]); w[1] = pk2(v0[2], v0[3]); w[2] = pk2(v1[0], v1[1]); w[3] = pk2(v1[2], v1[3]);
;           *(u32x4*)(rowp + bj * HALF) = w;
;         }
;       }
.Lpeel_exit_2:
	s_lshl_b32 s28, s28, 10
	s_add_i32 s28, s63, s28
	s_cmp_eq_u32 s37, 20
	v_readlane_b32 s4, v252, 63
	s_cselect_b64 s[30:31], -1, 0
	v_readlane_b32 s5, v253, 0
	s_and_b64 s[30:31], s[4:5], s[30:31]
	v_lshl_add_u32 v152, s65, 8, v159
	s_andn2_b64 vcc, exec, s[30:31]
	s_mov_b64 s[30:31], -1
	s_cbranch_vccz .LBB0_1178
	v_lshl_add_u32 v153, v158, 2, s28
	ds_read2_b32 v[168:169], v153 offset1:16
	v_readlane_b32 s4, v253, 16
	v_lshl_or_b32 v156, s37, 8, v161
	v_readlane_b32 s18, v253, 30
	v_readlane_b32 s19, v253, 31
	v_ashrrev_i32_e32 v157, 31, v156
	v_lshlrev_b64 v[156:157], 1, v[156:157]
	v_mov_b64_e32 v[154:155], s[18:19]
	v_mad_i64_i32 v[164:165], s[30:31], v152, s96, v[154:155]
	v_lshl_add_u64 v[170:171], v[164:165], 0, v[156:157]
	s_waitcnt lgkmcnt(0)
	v_pk_mul_f32 v[166:167], v[72:73], v[168:169] op_sel_hi:[1,0]
	v_pk_mul_f32 v[164:165], v[70:71], v[168:169] op_sel_hi:[1,0]
	v_pk_mul_f32 v[172:173], v[68:69], v[168:169] op_sel_hi:[1,0]
	v_pk_mul_f32 v[174:175], v[66:67], v[168:169] op_sel_hi:[1,0]
	v_cvt_pk_bf16_f32 v164, v164, v165
	v_cvt_pk_bf16_f32 v165, v166, v167
	v_cvt_pk_bf16_f32 v166, v174, v175
	v_cvt_pk_bf16_f32 v167, v172, v173
	global_store_dwordx4 v[170:171], v[164:167], off
	v_pk_mul_f32 v[128:129], v[128:129], v[168:169] op_sel_hi:[1,0]
	v_pk_mul_f32 v[126:127], v[126:127], v[168:169] op_sel_hi:[1,0]
	v_pk_mul_f32 v[164:165], v[124:125], v[168:169] op_sel_hi:[1,0]
	v_pk_mul_f32 v[124:125], v[122:123], v[168:169] op_sel_hi:[1,0]
	v_cvt_pk_bf16_f32 v122, v126, v127
	v_cvt_pk_bf16_f32 v123, v128, v129
	v_cvt_pk_bf16_f32 v124, v124, v125
	v_cvt_pk_bf16_f32 v125, v164, v165
	global_store_dwordx4 v[170:171], v[122:125], off offset:256
	v_mov_b32_e32 v128, v169
	v_pk_mul_f32 v[164:165], v[60:61], v[128:129] op_sel_hi:[1,0]
	v_or_b32_e32 v122, 16, v152
	v_mad_i64_i32 v[122:123], s[30:31], v122, s96, v[154:155]
	v_lshl_add_u64 v[126:127], v[122:123], 0, v[156:157]
	v_pk_mul_f32 v[124:125], v[64:65], v[128:129] op_sel_hi:[1,0]
	v_pk_mul_f32 v[122:123], v[62:63], v[128:129] op_sel_hi:[1,0]
	v_pk_mul_f32 v[166:167], v[58:59], v[128:129] op_sel_hi:[1,0]
	v_cvt_pk_bf16_f32 v122, v122, v123
	v_cvt_pk_bf16_f32 v123, v124, v125
	v_cvt_pk_bf16_f32 v124, v166, v167
	v_cvt_pk_bf16_f32 v125, v164, v165
	v_pk_mul_f32 v[118:119], v[118:119], v[128:129] op_sel_hi:[1,0]
	global_store_dwordx4 v[126:127], v[122:125], off
	v_pk_mul_f32 v[120:121], v[120:121], v[128:129] op_sel_hi:[1,0]
	v_readlane_b32 s5, v253, 17
	v_pk_mul_f32 v[122:123], v[116:117], v[128:129] op_sel_hi:[1,0]
	v_pk_mul_f32 v[116:117], v[114:115], v[128:129] op_sel_hi:[1,0]
	v_cvt_pk_bf16_f32 v114, v118, v119
	ds_read2_b32 v[118:119], v153 offset0:32 offset1:48
	v_cvt_pk_bf16_f32 v115, v120, v121
	v_cvt_pk_bf16_f32 v116, v116, v117
	v_cvt_pk_bf16_f32 v117, v122, v123
	global_store_dwordx4 v[126:127], v[114:117], off offset:256
	s_waitcnt lgkmcnt(0)
	v_pk_mul_f32 v[122:123], v[52:53], v[118:119] op_sel_hi:[1,0]
	v_pk_mul_f32 v[124:125], v[50:51], v[118:119] op_sel_hi:[1,0]
	v_or_b32_e32 v114, 32, v152
	v_mad_i64_i32 v[114:115], s[30:31], v114, s96, v[154:155]
	v_lshl_add_u64 v[120:121], v[114:115], 0, v[156:157]
	v_pk_mul_f32 v[116:117], v[56:57], v[118:119] op_sel_hi:[1,0]
	v_pk_mul_f32 v[114:115], v[54:55], v[118:119] op_sel_hi:[1,0]
	v_pk_mul_f32 v[112:113], v[112:113], v[118:119] op_sel_hi:[1,0]
	v_cvt_pk_bf16_f32 v114, v114, v115
	v_cvt_pk_bf16_f32 v115, v116, v117
	v_cvt_pk_bf16_f32 v116, v124, v125
	v_cvt_pk_bf16_f32 v117, v122, v123
	global_store_dwordx4 v[120:121], v[114:117], off
	v_pk_mul_f32 v[110:111], v[110:111], v[118:119] op_sel_hi:[1,0]
	v_readlane_b32 s6, v253, 18
	v_pk_mul_f32 v[114:115], v[108:109], v[118:119] op_sel_hi:[1,0]
	v_pk_mul_f32 v[108:109], v[106:107], v[118:119] op_sel_hi:[1,0]
	v_cvt_pk_bf16_f32 v106, v110, v111
	v_cvt_pk_bf16_f32 v107, v112, v113
	v_cvt_pk_bf16_f32 v108, v108, v109
	v_cvt_pk_bf16_f32 v109, v114, v115
	global_store_dwordx4 v[120:121], v[106:109], off offset:256
	v_mov_b32_e32 v112, v119
	v_pk_mul_f32 v[114:115], v[44:45], v[112:113] op_sel_hi:[1,0]
	v_or_b32_e32 v106, 48, v152
	v_mad_i64_i32 v[106:107], s[30:31], v106, s96, v[154:155]
	v_lshl_add_u64 v[110:111], v[106:107], 0, v[156:157]
	v_pk_mul_f32 v[108:109], v[48:49], v[112:113] op_sel_hi:[1,0]
	v_pk_mul_f32 v[106:107], v[46:47], v[112:113] op_sel_hi:[1,0]
	v_pk_mul_f32 v[116:117], v[42:43], v[112:113] op_sel_hi:[1,0]
	v_cvt_pk_bf16_f32 v106, v106, v107
	v_cvt_pk_bf16_f32 v107, v108, v109
	v_cvt_pk_bf16_f32 v108, v116, v117
	v_cvt_pk_bf16_f32 v109, v114, v115
	v_pk_mul_f32 v[102:103], v[102:103], v[112:113] op_sel_hi:[1,0]
	global_store_dwordx4 v[110:111], v[106:109], off
	v_pk_mul_f32 v[104:105], v[104:105], v[112:113] op_sel_hi:[1,0]
	v_readlane_b32 s7, v253, 19
	v_pk_mul_f32 v[106:107], v[100:101], v[112:113] op_sel_hi:[1,0]
	v_pk_mul_f32 v[100:101], v[98:99], v[112:113] op_sel_hi:[1,0]
	v_cvt_pk_bf16_f32 v98, v102, v103
	ds_read2_b32 v[102:103], v153 offset0:128 offset1:144
	v_cvt_pk_bf16_f32 v99, v104, v105
	v_cvt_pk_bf16_f32 v100, v100, v101
	v_cvt_pk_bf16_f32 v101, v106, v107
	global_store_dwordx4 v[110:111], v[98:101], off offset:256
	s_waitcnt lgkmcnt(0)
; DI unsigned pk2(float lo, float hi) { f32x2 v = {lo, hi}; bf2_t r = __builtin_convertvector(v, bf2_t); return __builtin_bit_cast(unsigned, r); }
;   DI void operator()(const f32x4 (&acc)[2][2][4][2], const Unit& u, int wr, int wc, int fr, int fq, const PG8_LAS float* sR) const {
;     ...
; #pragma unroll
;     for (int ai = 0; ai < 2; ++ai)
; #pragma unroll
;       for (int m = 0; m < 4; ++m) {
;         bf16_t* rowp = C + (size_t)(row0 + ai * HALF + m * 16) * ldc + col0;
;         const float rs = sR[ai * 128 + m * 16 + fr];
; #pragma unroll
;         for (int bj = 0; bj < 2; ++bj) {
;           const f32x4 v0 = acc[ai][bj][m][0] * rs, v1 = acc[ai][bj][m][1] * rs;
;           u32x4 w; w[0] = pk2(v0[0], v0[1]); w[1] = pk2(v0[2], v0[3]); w[2] = pk2(v1[0], v1[1]); w[3] = pk2(v1[2], v1[3]);
;           *(u32x4*)(rowp + bj * HALF) = w;
;         }
;       }
	v_pk_mul_f32 v[106:107], v[36:37], v[102:103] op_sel_hi:[1,0]
	v_pk_mul_f32 v[108:109], v[34:35], v[102:103] op_sel_hi:[1,0]
	v_add_u32_e32 v98, 0x80, v152
	v_mad_i64_i32 v[98:99], s[30:31], v98, s96, v[154:155]
	v_lshl_add_u64 v[104:105], v[98:99], 0, v[156:157]
	v_pk_mul_f32 v[100:101], v[40:41], v[102:103] op_sel_hi:[1,0]
	v_pk_mul_f32 v[98:99], v[38:39], v[102:103] op_sel_hi:[1,0]
	v_pk_mul_f32 v[96:97], v[96:97], v[102:103] op_sel_hi:[1,0]
	v_cvt_pk_bf16_f32 v98, v98, v99
	v_cvt_pk_bf16_f32 v99, v100, v101
	v_cvt_pk_bf16_f32 v100, v108, v109
	v_cvt_pk_bf16_f32 v101, v106, v107
	global_store_dwordx4 v[104:105], v[98:101], off
	v_pk_mul_f32 v[94:95], v[94:95], v[102:103] op_sel_hi:[1,0]
	v_readlane_b32 s8, v253, 20
	v_pk_mul_f32 v[98:99], v[92:93], v[102:103] op_sel_hi:[1,0]
	v_pk_mul_f32 v[92:93], v[90:91], v[102:103] op_sel_hi:[1,0]
	v_cvt_pk_bf16_f32 v90, v94, v95
	v_cvt_pk_bf16_f32 v91, v96, v97
	v_cvt_pk_bf16_f32 v92, v92, v93
	v_cvt_pk_bf16_f32 v93, v98, v99
	global_store_dwordx4 v[104:105], v[90:93], off offset:256
	v_mov_b32_e32 v96, v103
	v_pk_mul_f32 v[98:99], v[28:29], v[96:97] op_sel_hi:[1,0]
	v_add_u32_e32 v90, 0x90, v152
	v_mad_i64_i32 v[90:91], s[30:31], v90, s96, v[154:155]
	v_lshl_add_u64 v[94:95], v[90:91], 0, v[156:157]
	v_pk_mul_f32 v[92:93], v[32:33], v[96:97] op_sel_hi:[1,0]
	v_pk_mul_f32 v[90:91], v[30:31], v[96:97] op_sel_hi:[1,0]
	v_pk_mul_f32 v[100:101], v[26:27], v[96:97] op_sel_hi:[1,0]
	v_cvt_pk_bf16_f32 v90, v90, v91
	v_cvt_pk_bf16_f32 v91, v92, v93
	v_cvt_pk_bf16_f32 v92, v100, v101
	v_cvt_pk_bf16_f32 v93, v98, v99
	v_pk_mul_f32 v[86:87], v[86:87], v[96:97] op_sel_hi:[1,0]
	global_store_dwordx4 v[94:95], v[90:93], off
	v_pk_mul_f32 v[88:89], v[88:89], v[96:97] op_sel_hi:[1,0]
	v_readlane_b32 s9, v253, 21
	v_pk_mul_f32 v[90:91], v[84:85], v[96:97] op_sel_hi:[1,0]
	v_pk_mul_f32 v[84:85], v[82:83], v[96:97] op_sel_hi:[1,0]
	v_cvt_pk_bf16_f32 v82, v86, v87
	ds_read2_b32 v[86:87], v153 offset0:160 offset1:176
	v_cvt_pk_bf16_f32 v83, v88, v89
	v_cvt_pk_bf16_f32 v84, v84, v85
	v_cvt_pk_bf16_f32 v85, v90, v91
	global_store_dwordx4 v[94:95], v[82:85], off offset:256
	s_waitcnt lgkmcnt(0)
	v_pk_mul_f32 v[90:91], v[12:13], v[86:87] op_sel_hi:[1,0]
	v_pk_mul_f32 v[92:93], v[10:11], v[86:87] op_sel_hi:[1,0]
	v_add_u32_e32 v82, 0xa0, v152
	v_mad_i64_i32 v[82:83], s[30:31], v82, s96, v[154:155]
	v_lshl_add_u64 v[88:89], v[82:83], 0, v[156:157]
	v_pk_mul_f32 v[84:85], v[16:17], v[86:87] op_sel_hi:[1,0]
	v_pk_mul_f32 v[82:83], v[14:15], v[86:87] op_sel_hi:[1,0]
	v_pk_mul_f32 v[80:81], v[80:81], v[86:87] op_sel_hi:[1,0]
	v_cvt_pk_bf16_f32 v82, v82, v83
	v_cvt_pk_bf16_f32 v83, v84, v85
	v_cvt_pk_bf16_f32 v84, v92, v93
	v_cvt_pk_bf16_f32 v85, v90, v91
	global_store_dwordx4 v[88:89], v[82:85], off
	v_pk_mul_f32 v[78:79], v[78:79], v[86:87] op_sel_hi:[1,0]
	v_readlane_b32 s10, v253, 22
	v_pk_mul_f32 v[82:83], v[76:77], v[86:87] op_sel_hi:[1,0]
	v_pk_mul_f32 v[76:77], v[74:75], v[86:87] op_sel_hi:[1,0]
	v_cvt_pk_bf16_f32 v74, v78, v79
	v_cvt_pk_bf16_f32 v75, v80, v81
	v_cvt_pk_bf16_f32 v76, v76, v77
	v_cvt_pk_bf16_f32 v77, v82, v83
	global_store_dwordx4 v[88:89], v[74:77], off offset:256
	v_mov_b32_e32 v80, v87
	v_pk_mul_f32 v[82:83], v[4:5], v[80:81] op_sel_hi:[1,0]
	v_add_u32_e32 v74, 0xb0, v152
	v_mad_i64_i32 v[74:75], s[30:31], v74, s96, v[154:155]
	v_lshl_add_u64 v[78:79], v[74:75], 0, v[156:157]
	v_pk_mul_f32 v[76:77], v[8:9], v[80:81] op_sel_hi:[1,0]
	v_pk_mul_f32 v[74:75], v[6:7], v[80:81] op_sel_hi:[1,0]
	v_pk_mul_f32 v[84:85], v[2:3], v[80:81] op_sel_hi:[1,0]
	v_cvt_pk_bf16_f32 v74, v74, v75
	v_cvt_pk_bf16_f32 v75, v76, v77
	v_cvt_pk_bf16_f32 v76, v84, v85
	v_cvt_pk_bf16_f32 v77, v82, v83
	global_store_dwordx4 v[78:79], v[74:77], off
	v_pk_mul_f32 v[24:25], v[24:25], v[80:81] op_sel_hi:[1,0]
	v_pk_mul_f32 v[22:23], v[22:23], v[80:81] op_sel_hi:[1,0]
	v_pk_mul_f32 v[74:75], v[20:21], v[80:81] op_sel_hi:[1,0]
	v_pk_mul_f32 v[20:21], v[18:19], v[80:81] op_sel_hi:[1,0]
	v_cvt_pk_bf16_f32 v18, v22, v23
	v_cvt_pk_bf16_f32 v19, v24, v25
	v_cvt_pk_bf16_f32 v20, v20, v21
	v_cvt_pk_bf16_f32 v21, v74, v75
	v_readlane_b32 s11, v253, 23
	v_readlane_b32 s12, v253, 24
	v_readlane_b32 s13, v253, 25
	v_readlane_b32 s14, v253, 26
	v_readlane_b32 s15, v253, 27
	v_readlane_b32 s16, v253, 28
	v_readlane_b32 s17, v253, 29
	global_store_dwordx4 v[78:79], v[18:21], off offset:256
	s_mov_b64 s[30:31], 0

; #define PG8_STAGE(bufoff, gbase, voff) do { _Pragma("unroll") for (int _i = 0; _i < 2; ++_i) \
;     __builtin_amdgcn_global_load_lds((const unsigned*)((const char*)(gbase) + (voff)[_i]), (PG8_LAS unsigned*)(lds + (bufoff) + ldsw + _i * 8192), 16, 0, 0); } while (0)
; #define PG8_LDA(dst, b, h) do { _Pragma("unroll") for (int m = 0; m < 4; ++m) _Pragma("unroll") for (int k = 0; k < 2; ++k) dst[m][k] = *(const PG8_LAS bf16x8*)(lds + PG8_SA(b, h) + aoff + m * 2048 + k * 1024); } while (0)
; #define PG8_LDB(dst, b, h) do { _Pragma("unroll") for (int n = 0; n < 2; ++n) _Pragma("unroll") for (int k = 0; k < 2; ++k) dst[n][k] = *(const PG8_LAS bf16x8*)(lds + PG8_SB(b, h) + boff + n * 2048 + k * 1024); } while (0)
; #define PG8_MMA(ai, bj, At, Bt) do { __builtin_amdgcn_s_setprio(1); _Pragma("unroll") for (int m = 0; m < 4; ++m) _Pragma("unroll") for (int n = 0; n < 2; ++n) _Pragma("unroll") for (int k = 0; k < 2; ++k) \
;     acc[ai][bj][m][n] = __builtin_amdgcn_mfma_f32_16x16x32_bf16(Bt[n][k], At[m][k], acc[ai][bj][m][n], 0, 0, 0); __builtin_amdgcn_s_setprio(0); } while (0)
; #define PG8_WAIT_L(n) asm volatile("s_waitcnt lgkmcnt(" #n ")" ::: "memory")
; #define PG8_BAR __builtin_amdgcn_s_barrier()
; #define PG8_SCHED __builtin_amdgcn_sched_barrier(0)
; template <class Epi>
; DI void gemm_phase(PG8_LAS unsigned char* lds, const Gemm g, const StaticOrder& S, const Epi& E) {
;     ...
;     const bool has_next = S.next(ui + 1, nxt);
;     const char* nA = has_next ? (const char*)g.A + (size_t)nxt.pm * tstepA : cA; const char* nB = has_next ? (const char*)g.Bt + (size_t)nxt.pn * tstepB : cB;
;     for (int t = 0; t < nt; t += 2) {
;       const bool last = (t == nt - 2);
;       const char* a1 = cA + (size_t)(t + 1) * kstep;
;       const char* a2 = last ? nA : cA + (size_t)(t + 2) * kstep; const char* b2 = last ? nB : cB + (size_t)(t + 2) * kstep;
;       const char* a3 = a2 + kstep; const char* b3 = b2 + kstep;
;       PG8_LDB(B0, 0, 0); PG8_SCHED; PG8_LDA(At, 0, 0); PG8_STAGE(PG8_SA(1, 1), a1 + hstepA, voffA);
;       PG8_WAIT_L(8); PG8_BAR; PG8_WAIT_L(0); PG8_MMA(0, 0, At, B0); PG8_BAR; PG8_SCHED;
;       PG8_LDB(B1, 0, 1); PG8_STAGE(PG8_SB(0, 0), b2, voffB);
;       PG8_BAR; PG8_WAIT_L(0); PG8_MMA(0, 1, At, B1); PG8_BAR;
;       PG8_LDA(At, 0, 1); PG8_STAGE(PG8_SA(0, 0), a2, voffA);
;       PG8_BAR; PG8_WAIT_L(0); PG8_MMA(1, 0, At, B0); PG8_BAR; PG8_SCHED;
.LBB0_1196:
	s_ashr_i32 s43, s42, 31
	v_cmp_lt_i64_e32 vcc, s[44:45], v[140:141]
	s_lshl_b64 s[44:45], s[42:43], 19
	s_add_u32 s44, s22, s44
	s_addc_u32 s45, s23, s45
	s_and_b64 s[46:47], vcc, exec
	s_cselect_b32 s43, s45, s49
	s_cselect_b32 s63, s44, s48
	s_ashr_i32 s31, s30, 31
	v_readlane_b32 s4, v253, 16
	s_lshl_b64 s[46:47], s[30:31], 19
	v_readlane_b32 s14, v253, 26
	v_readlane_b32 s15, v253, 27
	s_add_u32 s46, s14, s46
	s_addc_u32 s47, s15, s47
	s_and_b64 s[52:53], vcc, exec
	s_cselect_b32 s31, s47, s51
	s_cselect_b32 s64, s46, s50
	s_add_u32 s48, s48, 0x40080
	s_addc_u32 s49, s49, 0
	s_add_u32 s65, s50, 0x100
	v_mov_b32_e32 v2, 0
	s_addc_u32 s66, s51, 0
	s_mov_b32 s67, -2
	v_readlane_b32 s5, v253, 17
	v_readlane_b32 s6, v253, 18
	v_readlane_b32 s7, v253, 19
	v_readlane_b32 s8, v253, 20
	v_readlane_b32 s9, v253, 21
	v_readlane_b32 s10, v253, 22
	v_readlane_b32 s11, v253, 23
	v_readlane_b32 s12, v253, 24
	v_readlane_b32 s13, v253, 25
	v_readlane_b32 s16, v253, 28
	v_readlane_b32 s17, v253, 29
	v_readlane_b32 s18, v253, 30
	v_readlane_b32 s19, v253, 31
	s_add_u32 s50, s48, 0xfffc0080
	s_addc_u32 s51, s49, -1
	s_add_i32 s68, 0, 0x10000
	v_add_u32_e32 v157, s68, v153
	ds_read_b128 v[148:151], v157
	ds_read_b128 v[158:161], v157 offset:1024
	ds_read_b128 v[162:165], v157 offset:2048
	ds_read_b128 v[166:169], v157 offset:3072
	s_cmp_eq_u32 s67, 12
	s_cselect_b32 s53, s43, s51
	s_cselect_b32 s52, s63, s50
	s_cselect_b32 s51, s31, s66
	s_cselect_b32 s50, s64, s65
	v_lshl_add_u64 v[198:199], s[48:49], 0, v[144:145]
	s_add_i32 m0, s37, 0xc000
	ds_read_b128 v[170:173], v156
	ds_read_b128 v[174:177], v156 offset:1024
	ds_read_b128 v[178:181], v156 offset:2048
	ds_read_b128 v[182:185], v156 offset:3072
	ds_read_b128 v[186:189], v156 offset:4096
	ds_read_b128 v[190:193], v156 offset:5120
	ds_read_b128 v[194:197], v156 offset:6144
	ds_read_b128 v[222:225], v156 offset:7168
	global_load_lds_dwordx4 v[198:199], off
	v_lshl_add_u64 v[198:199], s[48:49], 0, v[146:147]
	s_add_i32 m0, s37, 0xe000
	s_nop 0
	global_load_lds_dwordx4 v[198:199], off
	s_waitcnt lgkmcnt(8)
	s_barrier
	s_waitcnt lgkmcnt(0)
	s_waitcnt lgkmcnt(0)
	v_mfma_f32_16x16x32_bf16 v[126:129], v[148:151], v[170:173], 0
	v_mfma_f32_16x16x32_bf16 v[122:125], v[162:165], v[170:173], 0
	v_mfma_f32_16x16x32_bf16 v[118:121], v[148:151], v[178:181], 0
	v_mfma_f32_16x16x32_bf16 v[110:113], v[162:165], v[178:181], 0
	v_mfma_f32_16x16x32_bf16 v[94:97], v[148:151], v[186:189], 0
	v_mfma_f32_16x16x32_bf16 v[90:93], v[162:165], v[186:189], 0
	v_mfma_f32_16x16x32_bf16 v[86:89], v[148:151], v[194:197], 0
	v_mfma_f32_16x16x32_bf16 v[78:81], v[162:165], v[194:197], 0
	v_mfma_f32_16x16x32_bf16 v[126:129], v[158:161], v[174:177], v[126:129]
	v_mfma_f32_16x16x32_bf16 v[122:125], v[166:169], v[174:177], v[122:125]
	v_mfma_f32_16x16x32_bf16 v[118:121], v[158:161], v[182:185], v[118:121]
	v_mfma_f32_16x16x32_bf16 v[110:113], v[166:169], v[182:185], v[110:113]
	v_mfma_f32_16x16x32_bf16 v[94:97], v[158:161], v[190:193], v[94:97]
	v_mfma_f32_16x16x32_bf16 v[90:93], v[166:169], v[190:193], v[90:93]
	v_mfma_f32_16x16x32_bf16 v[86:89], v[158:161], v[222:225], v[86:89]
	v_mfma_f32_16x16x32_bf16 v[78:81], v[166:169], v[222:225], v[78:81]
	s_barrier
	s_add_i32 s70, 0, 0x14000
	s_add_i32 s68, s68, s34
	v_add_u32_e32 v157, s70, v153
	v_lshl_add_u64 v[198:199], s[50:51], 0, v[0:1]
	s_mov_b32 m0, s68
	ds_read_b128 v[226:229], v157
	ds_read_b128 v[230:233], v157 offset:1024
	ds_read_b128 v[234:237], v157 offset:2048
	ds_read_b128 v[238:241], v157 offset:3072
	global_load_lds_dwordx4 v[198:199], off
	v_lshl_add_u64 v[242:243], s[50:51], 0, v[130:131]
	s_add_i32 m0, s68, 0x2000
	s_nop 0
	global_load_lds_dwordx4 v[242:243], off
	s_barrier
	s_waitcnt lgkmcnt(0)
	s_waitcnt lgkmcnt(0)
	v_mfma_f32_16x16x32_bf16 v[114:117], v[226:229], v[170:173], 0
	v_mfma_f32_16x16x32_bf16 v[106:109], v[234:237], v[170:173], 0
	v_mfma_f32_16x16x32_bf16 v[102:105], v[226:229], v[178:181], 0
	v_mfma_f32_16x16x32_bf16 v[98:101], v[234:237], v[178:181], 0
	v_mfma_f32_16x16x32_bf16 v[82:85], v[226:229], v[186:189], 0
	v_mfma_f32_16x16x32_bf16 v[74:77], v[234:237], v[186:189], 0
	v_mfma_f32_16x16x32_bf16 v[70:73], v[226:229], v[194:197], 0
	v_mfma_f32_16x16x32_bf16 v[66:69], v[234:237], v[194:197], 0
	v_mfma_f32_16x16x32_bf16 v[114:117], v[230:233], v[174:177], v[114:117]
	v_mfma_f32_16x16x32_bf16 v[106:109], v[238:241], v[174:177], v[106:109]
	v_mfma_f32_16x16x32_bf16 v[102:105], v[230:233], v[182:185], v[102:105]
	v_mfma_f32_16x16x32_bf16 v[98:101], v[238:241], v[182:185], v[98:101]
	v_mfma_f32_16x16x32_bf16 v[82:85], v[230:233], v[190:193], v[82:85]
	v_mfma_f32_16x16x32_bf16 v[74:77], v[238:241], v[190:193], v[74:77]
	v_mfma_f32_16x16x32_bf16 v[70:73], v[230:233], v[222:225], v[70:73]
	v_mfma_f32_16x16x32_bf16 v[66:69], v[238:241], v[222:225], v[66:69]
	s_mov_b32 m0, s37
	v_lshl_add_u64 v[244:245], s[52:53], 0, v[142:143]
	s_barrier
	ds_read_b128 v[170:173], v156 offset:16384
	ds_read_b128 v[174:177], v156 offset:17408
	ds_read_b128 v[178:181], v156 offset:18432
	ds_read_b128 v[182:185], v156 offset:19456
	ds_read_b128 v[186:189], v156 offset:20480
	ds_read_b128 v[190:193], v156 offset:21504
	ds_read_b128 v[194:197], v156 offset:22528
	ds_read_b128 v[222:225], v156 offset:23552
	global_load_lds_dwordx4 v[244:245], off
	v_lshl_add_u64 v[246:247], s[52:53], 0, v[132:133]
	s_mov_b32 m0, s54
	s_nop 0
	global_load_lds_dwordx4 v[246:247], off
	s_barrier
; #define PG8_STAGE(bufoff, gbase, voff) do { _Pragma("unroll") for (int _i = 0; _i < 2; ++_i) \
;     __builtin_amdgcn_global_load_lds((const unsigned*)((const char*)(gbase) + (voff)[_i]), (PG8_LAS unsigned*)(lds + (bufoff) + ldsw + _i * 8192), 16, 0, 0); } while (0)
; #define PG8_LDA(dst, b, h) do { _Pragma("unroll") for (int m = 0; m < 4; ++m) _Pragma("unroll") for (int k = 0; k < 2; ++k) dst[m][k] = *(const PG8_LAS bf16x8*)(lds + PG8_SA(b, h) + aoff + m * 2048 + k * 1024); } while (0)
; #define PG8_LDB(dst, b, h) do { _Pragma("unroll") for (int n = 0; n < 2; ++n) _Pragma("unroll") for (int k = 0; k < 2; ++k) dst[n][k] = *(const PG8_LAS bf16x8*)(lds + PG8_SB(b, h) + boff + n * 2048 + k * 1024); } while (0)
; #define PG8_MMA(ai, bj, At, Bt) do { __builtin_amdgcn_s_setprio(1); _Pragma("unroll") for (int m = 0; m < 4; ++m) _Pragma("unroll") for (int n = 0; n < 2; ++n) _Pragma("unroll") for (int k = 0; k < 2; ++k) \
;     acc[ai][bj][m][n] = __builtin_amdgcn_mfma_f32_16x16x32_bf16(Bt[n][k], At[m][k], acc[ai][bj][m][n], 0, 0, 0); __builtin_amdgcn_s_setprio(0); } while (0)
; #define PG8_WAIT_V(n) asm volatile("s_waitcnt vmcnt(" #n ")" ::: "memory")
; #define PG8_WAIT_L(n) asm volatile("s_waitcnt lgkmcnt(" #n ")" ::: "memory")
; #define PG8_BAR __builtin_amdgcn_s_barrier()
; #define PG8_SCHED __builtin_amdgcn_sched_barrier(0)
; template <class Epi>
; DI void gemm_phase(PG8_LAS unsigned char* lds, const Gemm g, const StaticOrder& S, const Epi& E) {
;     ...
;       PG8_BAR; PG8_WAIT_L(0); PG8_MMA(1, 0, At, B0); PG8_BAR; PG8_SCHED;
;       PG8_STAGE(PG8_SB(0, 1), b2 + hstepB, voffB);
;       PG8_WAIT_V(6); PG8_BAR; PG8_MMA(1, 1, At, B1); PG8_BAR;
;       PG8_LDB(B0, 1, 0); PG8_SCHED; PG8_LDA(At, 1, 0); PG8_STAGE(PG8_SA(0, 1), a2 + hstepA, voffA);
;       PG8_WAIT_L(8); PG8_BAR; PG8_WAIT_L(0); PG8_MMA(0, 0, At, B0); PG8_BAR; PG8_SCHED;
	s_waitcnt lgkmcnt(0)
	s_waitcnt lgkmcnt(0)
	v_mfma_f32_16x16x32_bf16 v[62:65], v[148:151], v[170:173], 0
	v_mfma_f32_16x16x32_bf16 v[58:61], v[162:165], v[170:173], 0
	v_mfma_f32_16x16x32_bf16 v[54:57], v[148:151], v[178:181], 0
	v_mfma_f32_16x16x32_bf16 v[46:49], v[162:165], v[178:181], 0
	v_mfma_f32_16x16x32_bf16 v[30:33], v[148:151], v[186:189], 0
	v_mfma_f32_16x16x32_bf16 v[26:29], v[162:165], v[186:189], 0
	v_mfma_f32_16x16x32_bf16 v[22:25], v[148:151], v[194:197], 0
	v_mfma_f32_16x16x32_bf16 v[14:17], v[162:165], v[194:197], 0
	v_mfma_f32_16x16x32_bf16 v[62:65], v[158:161], v[174:177], v[62:65]
	v_mfma_f32_16x16x32_bf16 v[58:61], v[166:169], v[174:177], v[58:61]
	v_mfma_f32_16x16x32_bf16 v[54:57], v[158:161], v[182:185], v[54:57]
	v_mfma_f32_16x16x32_bf16 v[46:49], v[166:169], v[182:185], v[46:49]
	v_mfma_f32_16x16x32_bf16 v[30:33], v[158:161], v[190:193], v[30:33]
	v_mfma_f32_16x16x32_bf16 v[26:29], v[166:169], v[190:193], v[26:29]
	v_mfma_f32_16x16x32_bf16 v[22:25], v[158:161], v[222:225], v[22:25]
	v_mfma_f32_16x16x32_bf16 v[14:17], v[166:169], v[222:225], v[14:17]
	s_barrier
	s_add_u32 s68, s50, 0x40000
	s_addc_u32 s69, s51, 0
	s_add_i32 s70, s70, s34
	v_lshl_add_u64 v[148:149], s[68:69], 0, v[0:1]
	s_mov_b32 m0, s70
	s_nop 0
	global_load_lds_dwordx4 v[148:149], off
	v_lshl_add_u64 v[148:149], s[68:69], 0, v[130:131]
	s_add_i32 m0, s70, 0x2000
	s_nop 0
	global_load_lds_dwordx4 v[148:149], off
	s_waitcnt vmcnt(6)
	s_barrier
	v_mfma_f32_16x16x32_bf16 v[50:53], v[226:229], v[170:173], 0
	v_mfma_f32_16x16x32_bf16 v[42:45], v[234:237], v[170:173], 0
	v_mfma_f32_16x16x32_bf16 v[38:41], v[226:229], v[178:181], 0
	v_mfma_f32_16x16x32_bf16 v[34:37], v[234:237], v[178:181], 0
	v_mfma_f32_16x16x32_bf16 v[18:21], v[226:229], v[186:189], 0
	v_mfma_f32_16x16x32_bf16 v[10:13], v[234:237], v[186:189], 0
	v_mfma_f32_16x16x32_bf16 v[6:9], v[226:229], v[194:197], 0
	v_mfma_f32_16x16x32_bf16 v[2:5], v[234:237], v[194:197], 0
	v_mfma_f32_16x16x32_bf16 v[50:53], v[230:233], v[174:177], v[50:53]
	v_mfma_f32_16x16x32_bf16 v[42:45], v[238:241], v[174:177], v[42:45]
	v_mfma_f32_16x16x32_bf16 v[38:41], v[230:233], v[182:185], v[38:41]
	v_mfma_f32_16x16x32_bf16 v[34:37], v[238:241], v[182:185], v[34:37]
	v_mfma_f32_16x16x32_bf16 v[18:21], v[230:233], v[190:193], v[18:21]
	v_mfma_f32_16x16x32_bf16 v[10:13], v[238:241], v[190:193], v[10:13]
	v_mfma_f32_16x16x32_bf16 v[6:9], v[230:233], v[222:225], v[6:9]
	v_mfma_f32_16x16x32_bf16 v[2:5], v[238:241], v[222:225], v[2:5]
	s_add_i32 s68, 0, 0x18000
	v_add_u32_e32 v157, s68, v153
	s_barrier
	ds_read_b128 v[148:151], v157
	ds_read_b128 v[158:161], v157 offset:1024
	ds_read_b128 v[162:165], v157 offset:2048
	ds_read_b128 v[166:169], v157 offset:3072
	s_add_u32 s52, s52, 0x40000
	s_addc_u32 s53, s53, 0
	s_mov_b32 m0, s55
	v_lshl_add_u64 v[226:227], s[52:53], 0, v[142:143]
	ds_read_b128 v[170:173], v156 offset:32768
	ds_read_b128 v[174:177], v156 offset:33792
	ds_read_b128 v[178:181], v156 offset:34816
	ds_read_b128 v[182:185], v156 offset:35840
	ds_read_b128 v[186:189], v156 offset:36864
	ds_read_b128 v[190:193], v156 offset:37888
	ds_read_b128 v[194:197], v156 offset:38912
	ds_read_b128 v[222:225], v156 offset:39936
	global_load_lds_dwordx4 v[226:227], off
	v_lshl_add_u64 v[226:227], s[52:53], 0, v[132:133]
	s_mov_b32 m0, s56
	s_nop 0
	global_load_lds_dwordx4 v[226:227], off
	s_waitcnt lgkmcnt(8)
	s_barrier
	s_waitcnt lgkmcnt(0)
	s_waitcnt lgkmcnt(0)
	v_mfma_f32_16x16x32_bf16 v[126:129], v[148:151], v[170:173], v[126:129]
	v_mfma_f32_16x16x32_bf16 v[122:125], v[162:165], v[170:173], v[122:125]
	v_mfma_f32_16x16x32_bf16 v[118:121], v[148:151], v[178:181], v[118:121]
	v_mfma_f32_16x16x32_bf16 v[110:113], v[162:165], v[178:181], v[110:113]
	v_mfma_f32_16x16x32_bf16 v[94:97], v[148:151], v[186:189], v[94:97]
	v_mfma_f32_16x16x32_bf16 v[90:93], v[162:165], v[186:189], v[90:93]
	v_mfma_f32_16x16x32_bf16 v[86:89], v[148:151], v[194:197], v[86:89]
	v_mfma_f32_16x16x32_bf16 v[78:81], v[162:165], v[194:197], v[78:81]
	v_mfma_f32_16x16x32_bf16 v[126:129], v[158:161], v[174:177], v[126:129]
	v_mfma_f32_16x16x32_bf16 v[122:125], v[166:169], v[174:177], v[122:125]
	v_mfma_f32_16x16x32_bf16 v[118:121], v[158:161], v[182:185], v[118:121]
	v_mfma_f32_16x16x32_bf16 v[110:113], v[166:169], v[182:185], v[110:113]
	v_mfma_f32_16x16x32_bf16 v[94:97], v[158:161], v[190:193], v[94:97]
	v_mfma_f32_16x16x32_bf16 v[90:93], v[166:169], v[190:193], v[90:93]
	v_mfma_f32_16x16x32_bf16 v[86:89], v[158:161], v[222:225], v[86:89]
	v_mfma_f32_16x16x32_bf16 v[78:81], v[166:169], v[222:225], v[78:81]
	s_barrier
; #define PG8_STAGE(bufoff, gbase, voff) do { _Pragma("unroll") for (int _i = 0; _i < 2; ++_i) \
;     __builtin_amdgcn_global_load_lds((const unsigned*)((const char*)(gbase) + (voff)[_i]), (PG8_LAS unsigned*)(lds + (bufoff) + ldsw + _i * 8192), 16, 0, 0); } while (0)
; #define PG8_LDA(dst, b, h) do { _Pragma("unroll") for (int m = 0; m < 4; ++m) _Pragma("unroll") for (int k = 0; k < 2; ++k) dst[m][k] = *(const PG8_LAS bf16x8*)(lds + PG8_SA(b, h) + aoff + m * 2048 + k * 1024); } while (0)
; #define PG8_LDB(dst, b, h) do { _Pragma("unroll") for (int n = 0; n < 2; ++n) _Pragma("unroll") for (int k = 0; k < 2; ++k) dst[n][k] = *(const PG8_LAS bf16x8*)(lds + PG8_SB(b, h) + boff + n * 2048 + k * 1024); } while (0)
; #define PG8_MMA(ai, bj, At, Bt) do { __builtin_amdgcn_s_setprio(1); _Pragma("unroll") for (int m = 0; m < 4; ++m) _Pragma("unroll") for (int n = 0; n < 2; ++n) _Pragma("unroll") for (int k = 0; k < 2; ++k) \
;     acc[ai][bj][m][n] = __builtin_amdgcn_mfma_f32_16x16x32_bf16(Bt[n][k], At[m][k], acc[ai][bj][m][n], 0, 0, 0); __builtin_amdgcn_s_setprio(0); } while (0)
; #define PG8_WAIT_V(n) asm volatile("s_waitcnt vmcnt(" #n ")" ::: "memory")
; #define PG8_WAIT_L(n) asm volatile("s_waitcnt lgkmcnt(" #n ")" ::: "memory")
; #define PG8_BAR __builtin_amdgcn_s_barrier()
; #define PG8_SCHED __builtin_amdgcn_sched_barrier(0)
; template <class Epi>
; DI void gemm_phase(PG8_LAS unsigned char* lds, const Gemm g, const StaticOrder& S, const Epi& E) {
;     ...
;       PG8_LDB(B1, 1, 1); PG8_STAGE(PG8_SB(1, 0), b3, voffB);
;       PG8_BAR; PG8_WAIT_L(0); PG8_MMA(0, 1, At, B1); PG8_BAR;
;       PG8_LDA(At, 1, 1); PG8_STAGE(PG8_SA(1, 0), a3, voffA);
;       PG8_BAR; PG8_WAIT_L(0); PG8_MMA(1, 0, At, B0); PG8_BAR; PG8_SCHED;
;       PG8_STAGE(PG8_SB(1, 1), b3 + hstepB, voffB);
;       PG8_WAIT_V(6); PG8_BAR; PG8_MMA(1, 1, At, B1); PG8_BAR;
	s_add_i32 s52, 0, 0x1c000
	s_add_i32 s53, s68, s34
	v_add_u32_e32 v157, s52, v153
	v_lshl_add_u64 v[198:199], v[198:199], 0, s[86:87]
	s_mov_b32 m0, s53
	ds_read_b128 v[226:229], v157
	ds_read_b128 v[230:233], v157 offset:1024
	ds_read_b128 v[234:237], v157 offset:2048
	ds_read_b128 v[238:241], v157 offset:3072
	global_load_lds_dwordx4 v[198:199], off
	v_lshl_add_u64 v[198:199], v[242:243], 0, s[86:87]
	s_add_i32 m0, s53, 0x2000
	s_nop 0
	global_load_lds_dwordx4 v[198:199], off
	s_barrier
	s_waitcnt lgkmcnt(0)
	s_waitcnt lgkmcnt(0)
	v_mfma_f32_16x16x32_bf16 v[114:117], v[226:229], v[170:173], v[114:117]
	v_mfma_f32_16x16x32_bf16 v[106:109], v[234:237], v[170:173], v[106:109]
	v_mfma_f32_16x16x32_bf16 v[102:105], v[226:229], v[178:181], v[102:105]
	v_mfma_f32_16x16x32_bf16 v[98:101], v[234:237], v[178:181], v[98:101]
	v_mfma_f32_16x16x32_bf16 v[82:85], v[226:229], v[186:189], v[82:85]
	v_mfma_f32_16x16x32_bf16 v[74:77], v[234:237], v[186:189], v[74:77]
	v_mfma_f32_16x16x32_bf16 v[70:73], v[226:229], v[194:197], v[70:73]
	v_mfma_f32_16x16x32_bf16 v[66:69], v[234:237], v[194:197], v[66:69]
	v_mfma_f32_16x16x32_bf16 v[114:117], v[230:233], v[174:177], v[114:117]
	v_mfma_f32_16x16x32_bf16 v[106:109], v[238:241], v[174:177], v[106:109]
	v_mfma_f32_16x16x32_bf16 v[102:105], v[230:233], v[182:185], v[102:105]
	v_mfma_f32_16x16x32_bf16 v[98:101], v[238:241], v[182:185], v[98:101]
	v_mfma_f32_16x16x32_bf16 v[82:85], v[230:233], v[190:193], v[82:85]
	v_mfma_f32_16x16x32_bf16 v[74:77], v[238:241], v[190:193], v[74:77]
	v_mfma_f32_16x16x32_bf16 v[70:73], v[230:233], v[222:225], v[70:73]
	v_mfma_f32_16x16x32_bf16 v[66:69], v[238:241], v[222:225], v[66:69]
	s_mov_b32 m0, s57
	v_lshl_add_u64 v[198:199], v[244:245], 0, s[86:87]
	s_barrier
	ds_read_b128 v[170:173], v156 offset:49152
	ds_read_b128 v[174:177], v156 offset:50176
	ds_read_b128 v[178:181], v156 offset:51200
	ds_read_b128 v[182:185], v156 offset:52224
	ds_read_b128 v[186:189], v156 offset:53248
	ds_read_b128 v[190:193], v156 offset:54272
	ds_read_b128 v[194:197], v156 offset:55296
	ds_read_b128 v[222:225], v156 offset:56320
	global_load_lds_dwordx4 v[198:199], off
	v_lshl_add_u64 v[198:199], v[246:247], 0, s[86:87]
	s_mov_b32 m0, s58
	s_nop 0
	global_load_lds_dwordx4 v[198:199], off
	s_barrier
	s_waitcnt lgkmcnt(0)
	s_waitcnt lgkmcnt(0)
	v_mfma_f32_16x16x32_bf16 v[62:65], v[148:151], v[170:173], v[62:65]
	v_mfma_f32_16x16x32_bf16 v[58:61], v[162:165], v[170:173], v[58:61]
	v_mfma_f32_16x16x32_bf16 v[54:57], v[148:151], v[178:181], v[54:57]
	v_mfma_f32_16x16x32_bf16 v[46:49], v[162:165], v[178:181], v[46:49]
	v_mfma_f32_16x16x32_bf16 v[30:33], v[148:151], v[186:189], v[30:33]
	v_mfma_f32_16x16x32_bf16 v[26:29], v[162:165], v[186:189], v[26:29]
	v_mfma_f32_16x16x32_bf16 v[22:25], v[148:151], v[194:197], v[22:25]
	v_mfma_f32_16x16x32_bf16 v[14:17], v[162:165], v[194:197], v[14:17]
	v_mfma_f32_16x16x32_bf16 v[62:65], v[158:161], v[174:177], v[62:65]
	v_mfma_f32_16x16x32_bf16 v[58:61], v[166:169], v[174:177], v[58:61]
	v_mfma_f32_16x16x32_bf16 v[54:57], v[158:161], v[182:185], v[54:57]
	v_mfma_f32_16x16x32_bf16 v[46:49], v[166:169], v[182:185], v[46:49]
	v_mfma_f32_16x16x32_bf16 v[30:33], v[158:161], v[190:193], v[30:33]
	v_mfma_f32_16x16x32_bf16 v[26:29], v[166:169], v[190:193], v[26:29]
	v_mfma_f32_16x16x32_bf16 v[22:25], v[158:161], v[222:225], v[22:25]
	v_mfma_f32_16x16x32_bf16 v[14:17], v[166:169], v[222:225], v[14:17]
	s_barrier
	s_add_u32 s50, s50, 0x40080
	s_addc_u32 s51, s51, 0
	s_add_i32 s52, s52, s34
	v_lshl_add_u64 v[148:149], s[50:51], 0, v[0:1]
	s_mov_b32 m0, s52
	s_nop 0
	global_load_lds_dwordx4 v[148:149], off
	v_lshl_add_u64 v[148:149], s[50:51], 0, v[130:131]
	s_add_i32 m0, s52, 0x2000
	s_nop 0
	global_load_lds_dwordx4 v[148:149], off
	s_waitcnt vmcnt(6)
	s_barrier
	v_mfma_f32_16x16x32_bf16 v[50:53], v[226:229], v[170:173], v[50:53]
	v_mfma_f32_16x16x32_bf16 v[42:45], v[234:237], v[170:173], v[42:45]
	v_mfma_f32_16x16x32_bf16 v[38:41], v[226:229], v[178:181], v[38:41]
	v_mfma_f32_16x16x32_bf16 v[34:37], v[234:237], v[178:181], v[34:37]
	v_mfma_f32_16x16x32_bf16 v[18:21], v[226:229], v[186:189], v[18:21]
	v_mfma_f32_16x16x32_bf16 v[10:13], v[234:237], v[186:189], v[10:13]
	v_mfma_f32_16x16x32_bf16 v[6:9], v[226:229], v[194:197], v[6:9]
	v_mfma_f32_16x16x32_bf16 v[2:5], v[234:237], v[194:197], v[2:5]
	v_mfma_f32_16x16x32_bf16 v[50:53], v[230:233], v[174:177], v[50:53]
	v_mfma_f32_16x16x32_bf16 v[42:45], v[238:241], v[174:177], v[42:45]
	v_mfma_f32_16x16x32_bf16 v[38:41], v[230:233], v[182:185], v[38:41]
	v_mfma_f32_16x16x32_bf16 v[34:37], v[238:241], v[182:185], v[34:37]
	v_mfma_f32_16x16x32_bf16 v[18:21], v[230:233], v[190:193], v[18:21]
	v_mfma_f32_16x16x32_bf16 v[10:13], v[238:241], v[190:193], v[10:13]
	v_mfma_f32_16x16x32_bf16 v[6:9], v[230:233], v[222:225], v[6:9]
	v_mfma_f32_16x16x32_bf16 v[2:5], v[238:241], v[222:225], v[2:5]
	s_add_i32 s67, s67, 2
	s_add_u32 s48, s48, 0x100
	s_addc_u32 s49, s49, 0
	s_add_u32 s65, s65, 0x100
	s_addc_u32 s66, s66, 0
	s_cmp_gt_u32 s67, 13
	s_barrier
	s_cbranch_scc1 .Lpeel_exit_3

; DI unsigned pk2(float lo, float hi) { f32x2 v = {lo, hi}; bf2_t r = __builtin_convertvector(v, bf2_t); return __builtin_bit_cast(unsigned, r); }
;   DI void operator()(const f32x4 (&acc)[2][2][4][2], const Unit& u, int wr, int wc, int fr, int fq, const PG8_LAS float* sR) const {
;     ...
;     const int col0 = u.pn * BM + wc * 32 + 8 * fq;
; #pragma unroll
;     for (int ai = 0; ai < 2; ++ai)
; #pragma unroll
;       for (int m = 0; m < 4; ++m) {
;         bf16_t* rowp = C + (size_t)(row0 + ai * HALF + m * 16) * ldc + col0;
;         const float rs = sR[ai * 128 + m * 16 + fr];
; #pragma unroll
;         for (int bj = 0; bj < 2; ++bj) {
;           const f32x4 v0 = acc[ai][bj][m][0] * rs, v1 = acc[ai][bj][m][1] * rs;
;           u32x4 w; w[0] = pk2(v0[0], v0[1]); w[1] = pk2(v0[2], v0[3]); w[2] = pk2(v1[0], v1[1]); w[3] = pk2(v1[2], v1[3]);
;           *(u32x4*)(rowp + bj * HALF) = w;
.Lpeel_exit_3:
	v_lshl_add_u32 v164, s61, 10, v154
	ds_read2_b32 v[160:161], v164 offset1:16
	v_readlane_b32 s4, v253, 16
	v_lshl_or_b32 v150, s60, 8, v155
	v_readlane_b32 s18, v253, 30
	v_readlane_b32 s19, v253, 31
	v_lshl_add_u32 v157, s62, 8, v152
	v_ashrrev_i32_e32 v151, 31, v150
	v_mov_b64_e32 v[148:149], s[18:19]
	v_mad_i64_i32 v[158:159], s[48:49], v157, s36, v[148:149]
	v_lshlrev_b64 v[150:151], 1, v[150:151]
	s_waitcnt lgkmcnt(0)
	v_pk_mul_f32 v[128:129], v[128:129], v[160:161] op_sel_hi:[1,0]
	v_pk_mul_f32 v[126:127], v[126:127], v[160:161] op_sel_hi:[1,0]
	v_pk_mul_f32 v[162:163], v[124:125], v[160:161] op_sel_hi:[1,0]
	v_pk_mul_f32 v[124:125], v[122:123], v[160:161] op_sel_hi:[1,0]
	v_lshl_add_u64 v[158:159], v[158:159], 0, v[150:151]
	v_cvt_pk_bf16_f32 v122, v126, v127
	v_cvt_pk_bf16_f32 v123, v128, v129
	v_cvt_pk_bf16_f32 v124, v124, v125
	v_cvt_pk_bf16_f32 v125, v162, v163
	global_store_dwordx4 v[158:159], v[122:125], off
	v_pk_mul_f32 v[116:117], v[116:117], v[160:161] op_sel_hi:[1,0]
	v_pk_mul_f32 v[114:115], v[114:115], v[160:161] op_sel_hi:[1,0]
	v_pk_mul_f32 v[122:123], v[108:109], v[160:161] op_sel_hi:[1,0]
	v_pk_mul_f32 v[108:109], v[106:107], v[160:161] op_sel_hi:[1,0]
	v_cvt_pk_bf16_f32 v106, v114, v115
	v_cvt_pk_bf16_f32 v107, v116, v117
	v_cvt_pk_bf16_f32 v108, v108, v109
	v_cvt_pk_bf16_f32 v109, v122, v123
	global_store_dwordx4 v[158:159], v[106:109], off offset:256
	v_mov_b32_e32 v116, v161
	v_pk_mul_f32 v[112:113], v[112:113], v[116:117] op_sel_hi:[1,0]
	v_or_b32_e32 v106, 16, v157
	v_mad_i64_i32 v[106:107], s[48:49], v106, s36, v[148:149]
	v_lshl_add_u64 v[114:115], v[106:107], 0, v[150:151]
	v_pk_mul_f32 v[108:109], v[120:121], v[116:117] op_sel_hi:[1,0]
	v_pk_mul_f32 v[106:107], v[118:119], v[116:117] op_sel_hi:[1,0]
	v_pk_mul_f32 v[110:111], v[110:111], v[116:117] op_sel_hi:[1,0]
	v_cvt_pk_bf16_f32 v106, v106, v107
	v_cvt_pk_bf16_f32 v107, v108, v109
	v_cvt_pk_bf16_f32 v108, v110, v111
	v_cvt_pk_bf16_f32 v109, v112, v113
	global_store_dwordx4 v[114:115], v[106:109], off
	v_pk_mul_f32 v[104:105], v[104:105], v[116:117] op_sel_hi:[1,0]
	v_pk_mul_f32 v[102:103], v[102:103], v[116:117] op_sel_hi:[1,0]
	v_pk_mul_f32 v[106:107], v[100:101], v[116:117] op_sel_hi:[1,0]
	v_pk_mul_f32 v[100:101], v[98:99], v[116:117] op_sel_hi:[1,0]
	v_cvt_pk_bf16_f32 v98, v102, v103
	v_cvt_pk_bf16_f32 v99, v104, v105
	v_cvt_pk_bf16_f32 v100, v100, v101
	v_cvt_pk_bf16_f32 v101, v106, v107
	global_store_dwordx4 v[114:115], v[98:101], off offset:256
	ds_read2_b32 v[100:101], v164 offset0:32 offset1:48
	s_and_b64 vcc, exec, s[40:41]
	v_or_b32_e32 v98, 32, v157
	v_mad_i64_i32 v[98:99], s[48:49], v98, s36, v[148:149]
	s_waitcnt lgkmcnt(0)
	v_pk_mul_f32 v[96:97], v[96:97], v[100:101] op_sel_hi:[1,0]
	v_pk_mul_f32 v[94:95], v[94:95], v[100:101] op_sel_hi:[1,0]
	v_pk_mul_f32 v[102:103], v[92:93], v[100:101] op_sel_hi:[1,0]
	v_pk_mul_f32 v[92:93], v[90:91], v[100:101] op_sel_hi:[1,0]
	v_lshl_add_u64 v[98:99], v[98:99], 0, v[150:151]
	v_cvt_pk_bf16_f32 v90, v94, v95
	v_cvt_pk_bf16_f32 v91, v96, v97
	v_cvt_pk_bf16_f32 v92, v92, v93
	v_cvt_pk_bf16_f32 v93, v102, v103
	global_store_dwordx4 v[98:99], v[90:93], off
	v_pk_mul_f32 v[84:85], v[84:85], v[100:101] op_sel_hi:[1,0]
	v_pk_mul_f32 v[82:83], v[82:83], v[100:101] op_sel_hi:[1,0]
	v_pk_mul_f32 v[90:91], v[76:77], v[100:101] op_sel_hi:[1,0]
	v_pk_mul_f32 v[76:77], v[74:75], v[100:101] op_sel_hi:[1,0]
	v_cvt_pk_bf16_f32 v74, v82, v83
	v_cvt_pk_bf16_f32 v75, v84, v85
	v_cvt_pk_bf16_f32 v76, v76, v77
	v_cvt_pk_bf16_f32 v77, v90, v91
	global_store_dwordx4 v[98:99], v[74:77], off offset:256
	v_mov_b32_e32 v84, v101
	v_pk_mul_f32 v[80:81], v[80:81], v[84:85] op_sel_hi:[1,0]
	v_or_b32_e32 v74, 48, v157
	v_mad_i64_i32 v[74:75], s[48:49], v74, s36, v[148:149]
	v_lshl_add_u64 v[82:83], v[74:75], 0, v[150:151]
	v_pk_mul_f32 v[76:77], v[88:89], v[84:85] op_sel_hi:[1,0]
	v_pk_mul_f32 v[74:75], v[86:87], v[84:85] op_sel_hi:[1,0]
	v_pk_mul_f32 v[78:79], v[78:79], v[84:85] op_sel_hi:[1,0]
	v_cvt_pk_bf16_f32 v74, v74, v75
	v_cvt_pk_bf16_f32 v75, v76, v77
	v_cvt_pk_bf16_f32 v76, v78, v79
	v_cvt_pk_bf16_f32 v77, v80, v81
	global_store_dwordx4 v[82:83], v[74:77], off
	v_pk_mul_f32 v[72:73], v[72:73], v[84:85] op_sel_hi:[1,0]
	v_pk_mul_f32 v[70:71], v[70:71], v[84:85] op_sel_hi:[1,0]
	v_pk_mul_f32 v[74:75], v[68:69], v[84:85] op_sel_hi:[1,0]
	v_pk_mul_f32 v[68:69], v[66:67], v[84:85] op_sel_hi:[1,0]
	v_cvt_pk_bf16_f32 v66, v70, v71
	v_cvt_pk_bf16_f32 v67, v72, v73
	v_cvt_pk_bf16_f32 v68, v68, v69
	v_cvt_pk_bf16_f32 v69, v74, v75
	global_store_dwordx4 v[82:83], v[66:69], off offset:256
	ds_read2_b32 v[68:69], v164 offset0:128 offset1:144
	s_mov_b32 s60, s30
	v_add_u32_e32 v66, 0x80, v157
	v_mad_i64_i32 v[66:67], s[48:49], v66, s36, v[148:149]
	s_waitcnt lgkmcnt(0)
; DI unsigned pk2(float lo, float hi) { f32x2 v = {lo, hi}; bf2_t r = __builtin_convertvector(v, bf2_t); return __builtin_bit_cast(unsigned, r); }
; #define PG8_WAIT_V(n) asm volatile("s_waitcnt vmcnt(" #n ")" ::: "memory")
; #define PG8_BAR __builtin_amdgcn_s_barrier()
;   DI void operator()(const f32x4 (&acc)[2][2][4][2], const Unit& u, int wr, int wc, int fr, int fq, const PG8_LAS float* sR) const {
;     ...
;     for (int ai = 0; ai < 2; ++ai)
; #pragma unroll
;       for (int m = 0; m < 4; ++m) {
;         bf16_t* rowp = C + (size_t)(row0 + ai * HALF + m * 16) * ldc + col0;
;         const float rs = sR[ai * 128 + m * 16 + fr];
; #pragma unroll
;         for (int bj = 0; bj < 2; ++bj) {
;           const f32x4 v0 = acc[ai][bj][m][0] * rs, v1 = acc[ai][bj][m][1] * rs;
;           u32x4 w; w[0] = pk2(v0[0], v0[1]); w[1] = pk2(v0[2], v0[3]); w[2] = pk2(v1[0], v1[1]); w[3] = pk2(v1[2], v1[3]);
;           *(u32x4*)(rowp + bj * HALF) = w;
; template <class Epi>
; DI void gemm_phase(PG8_LAS unsigned char* lds, const Gemm g, const StaticOrder& S, const Epi& E) {
;     ...
;     if (!has_next) break;
; #pragma unroll
;     for (int a = 0; a < 2; ++a)
; #pragma unroll
;       for (int b = 0; b < 2; ++b)
; #pragma unroll
;         for (int m = 0; m < 4; ++m)
; #pragma unroll
;           for (int n = 0; n < 2; ++n) acc[a][b][m][n] = (f32x4){0.f, 0.f, 0.f, 0.f};
;     cur = nxt; cA = nA; cB = nB; ++ui;
;   }
;   PG8_WAIT_V(0);
;   if (wr == 0) PG8_BAR;
;   PG8_BAR;
	v_pk_mul_f32 v[64:65], v[64:65], v[68:69] op_sel_hi:[1,0]
	v_pk_mul_f32 v[62:63], v[62:63], v[68:69] op_sel_hi:[1,0]
	v_pk_mul_f32 v[70:71], v[60:61], v[68:69] op_sel_hi:[1,0]
	v_pk_mul_f32 v[60:61], v[58:59], v[68:69] op_sel_hi:[1,0]
	v_lshl_add_u64 v[66:67], v[66:67], 0, v[150:151]
	v_cvt_pk_bf16_f32 v58, v62, v63
	v_cvt_pk_bf16_f32 v59, v64, v65
	v_cvt_pk_bf16_f32 v60, v60, v61
	v_cvt_pk_bf16_f32 v61, v70, v71
	global_store_dwordx4 v[66:67], v[58:61], off
	v_pk_mul_f32 v[52:53], v[52:53], v[68:69] op_sel_hi:[1,0]
	v_pk_mul_f32 v[50:51], v[50:51], v[68:69] op_sel_hi:[1,0]
	v_pk_mul_f32 v[58:59], v[44:45], v[68:69] op_sel_hi:[1,0]
	v_pk_mul_f32 v[44:45], v[42:43], v[68:69] op_sel_hi:[1,0]
	v_cvt_pk_bf16_f32 v42, v50, v51
	v_cvt_pk_bf16_f32 v43, v52, v53
	v_cvt_pk_bf16_f32 v44, v44, v45
	v_cvt_pk_bf16_f32 v45, v58, v59
	global_store_dwordx4 v[66:67], v[42:45], off offset:256
	v_mov_b32_e32 v52, v69
	v_pk_mul_f32 v[48:49], v[48:49], v[52:53] op_sel_hi:[1,0]
	v_add_u32_e32 v42, 0x90, v157
	v_mad_i64_i32 v[42:43], s[48:49], v42, s36, v[148:149]
	v_lshl_add_u64 v[50:51], v[42:43], 0, v[150:151]
	v_pk_mul_f32 v[44:45], v[56:57], v[52:53] op_sel_hi:[1,0]
	v_pk_mul_f32 v[42:43], v[54:55], v[52:53] op_sel_hi:[1,0]
	v_pk_mul_f32 v[46:47], v[46:47], v[52:53] op_sel_hi:[1,0]
	v_cvt_pk_bf16_f32 v42, v42, v43
	v_cvt_pk_bf16_f32 v43, v44, v45
	v_cvt_pk_bf16_f32 v44, v46, v47
	v_cvt_pk_bf16_f32 v45, v48, v49
	global_store_dwordx4 v[50:51], v[42:45], off
	v_pk_mul_f32 v[40:41], v[40:41], v[52:53] op_sel_hi:[1,0]
	v_pk_mul_f32 v[38:39], v[38:39], v[52:53] op_sel_hi:[1,0]
	v_pk_mul_f32 v[42:43], v[36:37], v[52:53] op_sel_hi:[1,0]
	v_pk_mul_f32 v[36:37], v[34:35], v[52:53] op_sel_hi:[1,0]
	v_cvt_pk_bf16_f32 v34, v38, v39
	v_cvt_pk_bf16_f32 v35, v40, v41
	v_cvt_pk_bf16_f32 v36, v36, v37
	v_cvt_pk_bf16_f32 v37, v42, v43
	global_store_dwordx4 v[50:51], v[34:37], off offset:256
	ds_read2_b32 v[36:37], v164 offset0:160 offset1:176
	s_mov_b32 s62, s42
	v_add_u32_e32 v34, 0xa0, v157
	v_mad_i64_i32 v[34:35], s[48:49], v34, s36, v[148:149]
	s_waitcnt lgkmcnt(0)
	v_pk_mul_f32 v[32:33], v[32:33], v[36:37] op_sel_hi:[1,0]
	v_pk_mul_f32 v[30:31], v[30:31], v[36:37] op_sel_hi:[1,0]
	v_pk_mul_f32 v[38:39], v[28:29], v[36:37] op_sel_hi:[1,0]
	v_pk_mul_f32 v[28:29], v[26:27], v[36:37] op_sel_hi:[1,0]
	v_lshl_add_u64 v[34:35], v[34:35], 0, v[150:151]
	v_cvt_pk_bf16_f32 v26, v30, v31
	v_cvt_pk_bf16_f32 v27, v32, v33
	v_cvt_pk_bf16_f32 v28, v28, v29
	v_cvt_pk_bf16_f32 v29, v38, v39
	global_store_dwordx4 v[34:35], v[26:29], off
	v_pk_mul_f32 v[20:21], v[20:21], v[36:37] op_sel_hi:[1,0]
	v_pk_mul_f32 v[18:19], v[18:19], v[36:37] op_sel_hi:[1,0]
	v_pk_mul_f32 v[26:27], v[12:13], v[36:37] op_sel_hi:[1,0]
	v_pk_mul_f32 v[12:13], v[10:11], v[36:37] op_sel_hi:[1,0]
	v_cvt_pk_bf16_f32 v10, v18, v19
	v_cvt_pk_bf16_f32 v11, v20, v21
	v_cvt_pk_bf16_f32 v12, v12, v13
	v_cvt_pk_bf16_f32 v13, v26, v27
	global_store_dwordx4 v[34:35], v[10:13], off offset:256
	v_mov_b32_e32 v20, v37
	v_pk_mul_f32 v[16:17], v[16:17], v[20:21] op_sel_hi:[1,0]
	v_add_u32_e32 v10, 0xb0, v157
	v_mad_i64_i32 v[10:11], s[48:49], v10, s36, v[148:149]
	v_lshl_add_u64 v[18:19], v[10:11], 0, v[150:151]
	v_pk_mul_f32 v[12:13], v[24:25], v[20:21] op_sel_hi:[1,0]
	v_pk_mul_f32 v[10:11], v[22:23], v[20:21] op_sel_hi:[1,0]
	v_pk_mul_f32 v[14:15], v[14:15], v[20:21] op_sel_hi:[1,0]
	v_cvt_pk_bf16_f32 v10, v10, v11
	v_cvt_pk_bf16_f32 v11, v12, v13
	v_cvt_pk_bf16_f32 v12, v14, v15
	v_cvt_pk_bf16_f32 v13, v16, v17
	global_store_dwordx4 v[18:19], v[10:13], off
	v_pk_mul_f32 v[8:9], v[8:9], v[20:21] op_sel_hi:[1,0]
	v_pk_mul_f32 v[6:7], v[6:7], v[20:21] op_sel_hi:[1,0]
	v_pk_mul_f32 v[10:11], v[4:5], v[20:21] op_sel_hi:[1,0]
	v_pk_mul_f32 v[4:5], v[2:3], v[20:21] op_sel_hi:[1,0]
	v_cvt_pk_bf16_f32 v2, v6, v7
	v_cvt_pk_bf16_f32 v3, v8, v9
	v_cvt_pk_bf16_f32 v4, v4, v5
	v_cvt_pk_bf16_f32 v5, v10, v11
	s_mov_b64 s[50:51], s[46:47]
	s_mov_b64 s[48:49], s[44:45]
	s_mov_b32 s61, s59
	v_readlane_b32 s5, v253, 17
	v_readlane_b32 s6, v253, 18
	v_readlane_b32 s7, v253, 19
	v_readlane_b32 s8, v253, 20
	v_readlane_b32 s9, v253, 21
	v_readlane_b32 s10, v253, 22
	v_readlane_b32 s11, v253, 23
	v_readlane_b32 s12, v253, 24
	v_readlane_b32 s13, v253, 25
	v_readlane_b32 s14, v253, 26
	v_readlane_b32 s15, v253, 27
	v_readlane_b32 s16, v253, 28
	v_readlane_b32 s17, v253, 29
	global_store_dwordx4 v[18:19], v[2:5], off offset:256
	s_cbranch_vccz .LBB0_1194
	s_waitcnt vmcnt(0)
	s_cmpk_gt_u32 s28, 0xff
	s_cbranch_scc1 .LBB0_1201
	s_barrier
